# v12 + next-unit SA(1,1) tile-1 stage hoisted before the epilogue; post-epilogue first iteration copy without P1 stage and without phase-4 vmcnt wait (no wait on epilogue stores), GEMM kinds 0,2,3
# speedup vs baseline: 1.0012x; 1.0012x over previous
.LBB0_210:
	s_or_b64 exec, exec, s[4:5]
	s_and_b64 vcc, exec, s[44:45]
	s_cbranch_vccnz .LBB0_229
	s_add_i32 s60, s60, 1
	s_mov_b64 s[36:37], s[18:19]
	s_mul_i32 s18, s60, s26
	s_add_i32 s38, s18, s2
	s_cmpk_gt_i32 s38, 0x1ff
	s_cselect_b64 s[44:45], -1, 0
	s_lshl_b32 s18, s38, 3
	s_and_b32 s18, s18, 56
	s_bfe_u32 s19, s38, 0x30003
	s_mov_b32 s27, s61
	s_or_b32 s61, s18, s19
	s_mov_b32 s3, s42
	s_ashr_i32 s42, s38, 6
	s_lshl_b32 s18, s61, 19
	s_mov_b64 s[4:5], s[20:21]
	s_add_u32 s20, s14, s18
	s_addc_u32 s21, s15, 0
	s_ashr_i32 s43, s42, 31
	s_lshl_b64 s[18:19], s[42:43], 19
	s_add_u32 s18, s16, s18
	s_addc_u32 s19, s17, s19
	s_cmpk_lt_i32 s38, 0x200
	s_cselect_b32 s38, s21, s5
	s_cselect_b32 s43, s20, s4
	s_cselect_b32 s62, s19, s37
	s_cselect_b32 s63, s18, s36
	s_add_u32 s64, s36, 0x100
	s_addc_u32 s65, s37, 0
	s_mov_b32 s66, -2
	s_waitcnt lgkmcnt(0)
	s_add_u32 s36, s4, 0x100
	s_addc_u32 s37, s5, 0
	s_add_i32 s67, 0, 0x10000
	v_add_u32_e32 v1, s67, v191
	ds_read_b128 v[34:37], v1
	ds_read_b128 v[38:41], v1 offset:1024
	ds_read_b128 v[42:45], v1 offset:2048
	ds_read_b128 v[46:49], v1 offset:3072
	s_cmp_eq_u32 s66, 12
	s_cselect_b32 s49, s38, s37
	s_cselect_b32 s48, s43, s36
	s_cselect_b32 s47, s62, s65
	s_cselect_b32 s46, s63, s64
	v_lshl_add_u64 v[186:187], s[4:5], 0, v[168:169]
	s_add_i32 m0, s53, 0xc000
	ds_read_b128 v[50:53], v206
	ds_read_b128 v[58:61], v206 offset:1024
	ds_read_b128 v[62:65], v206 offset:2048
	ds_read_b128 v[66:69], v206 offset:3072
	ds_read_b128 v[170:173], v206 offset:4096
	ds_read_b128 v[174:177], v206 offset:5120
	ds_read_b128 v[178:181], v206 offset:6144
	ds_read_b128 v[182:185], v206 offset:7168
	v_lshl_add_u64 v[186:187], s[4:5], 0, v[166:167]
	s_add_i32 m0, s53, 0xe000
	s_nop 0
	s_waitcnt lgkmcnt(8)
	s_barrier
	s_waitcnt lgkmcnt(0)
	s_setprio 1
	s_waitcnt lgkmcnt(0)
	v_mfma_f32_16x16x32_bf16 v[158:161], v[34:37], v[50:53], 0
	v_mfma_f32_16x16x32_bf16 v[154:157], v[42:45], v[50:53], 0
	v_mfma_f32_16x16x32_bf16 v[142:145], v[34:37], v[62:65], 0
	v_mfma_f32_16x16x32_bf16 v[138:141], v[42:45], v[62:65], 0
	v_mfma_f32_16x16x32_bf16 v[126:129], v[34:37], v[170:173], 0
	v_mfma_f32_16x16x32_bf16 v[122:125], v[42:45], v[170:173], 0
	v_mfma_f32_16x16x32_bf16 v[110:113], v[34:37], v[178:181], 0
	v_mfma_f32_16x16x32_bf16 v[106:109], v[42:45], v[178:181], 0
	v_mfma_f32_16x16x32_bf16 v[158:161], v[38:41], v[58:61], v[158:161]
	v_mfma_f32_16x16x32_bf16 v[154:157], v[46:49], v[58:61], v[154:157]
	v_mfma_f32_16x16x32_bf16 v[142:145], v[38:41], v[66:69], v[142:145]
	v_mfma_f32_16x16x32_bf16 v[138:141], v[46:49], v[66:69], v[138:141]
	v_mfma_f32_16x16x32_bf16 v[126:129], v[38:41], v[174:177], v[126:129]
	v_mfma_f32_16x16x32_bf16 v[122:125], v[46:49], v[174:177], v[122:125]
	v_mfma_f32_16x16x32_bf16 v[110:113], v[38:41], v[182:185], v[110:113]
	v_mfma_f32_16x16x32_bf16 v[106:109], v[46:49], v[182:185], v[106:109]
	s_setprio 0
	s_barrier
	s_add_i32 s68, 0, 0x14000
	s_add_i32 s4, s67, s52
	v_add_u32_e32 v1, s68, v191
	v_lshl_add_u64 v[214:215], s[46:47], 0, v[164:165]
	s_mov_b32 m0, s4
	ds_read_b128 v[186:189], v1
	ds_read_b128 v[208:211], v1 offset:1024
	ds_read_b128 v[222:225], v1 offset:2048
	ds_read_b128 v[226:229], v1 offset:3072
	global_load_lds_dwordx4 v[214:215], off
	v_lshl_add_u64 v[238:239], s[46:47], 0, v[162:163]
	s_add_i32 m0, s4, 0x2000
	s_nop 0
	global_load_lds_dwordx4 v[238:239], off
	s_barrier
	s_waitcnt lgkmcnt(0)
	s_setprio 1
	s_waitcnt lgkmcnt(0)
	v_mfma_f32_16x16x32_bf16 v[150:153], v[186:189], v[50:53], 0
	v_mfma_f32_16x16x32_bf16 v[50:53], v[222:225], v[50:53], 0
	v_mfma_f32_16x16x32_bf16 v[150:153], v[208:211], v[58:61], v[150:153]
	v_mfma_f32_16x16x32_bf16 v[50:53], v[226:229], v[58:61], v[50:53]
	v_mfma_f32_16x16x32_bf16 v[58:61], v[186:189], v[62:65], 0
	v_mfma_f32_16x16x32_bf16 v[62:65], v[222:225], v[62:65], 0
	v_mfma_f32_16x16x32_bf16 v[114:117], v[222:225], v[170:173], 0
	v_mfma_f32_16x16x32_bf16 v[102:105], v[186:189], v[178:181], 0
	v_mfma_f32_16x16x32_bf16 v[98:101], v[222:225], v[178:181], 0
	v_mfma_f32_16x16x32_bf16 v[58:61], v[208:211], v[66:69], v[58:61]
	v_mfma_f32_16x16x32_bf16 v[62:65], v[226:229], v[66:69], v[62:65]
	v_mfma_f32_16x16x32_bf16 v[66:69], v[186:189], v[170:173], 0
	v_mfma_f32_16x16x32_bf16 v[114:117], v[226:229], v[174:177], v[114:117]
	v_mfma_f32_16x16x32_bf16 v[102:105], v[208:211], v[182:185], v[102:105]
	v_mfma_f32_16x16x32_bf16 v[98:101], v[226:229], v[182:185], v[98:101]
	v_mfma_f32_16x16x32_bf16 v[66:69], v[208:211], v[174:177], v[66:69]
	s_setprio 0
	s_mov_b32 m0, s53
	v_lshl_add_u64 v[240:241], s[48:49], 0, v[164:165]
	s_barrier
	ds_read_b128 v[118:121], v206 offset:16384
	ds_read_b128 v[130:133], v206 offset:17408
	ds_read_b128 v[134:137], v206 offset:18432
	ds_read_b128 v[146:149], v206 offset:19456
	ds_read_b128 v[170:173], v206 offset:20480
	ds_read_b128 v[174:177], v206 offset:21504
	ds_read_b128 v[178:181], v206 offset:22528
	ds_read_b128 v[182:185], v206 offset:23552
	global_load_lds_dwordx4 v[240:241], off
	v_lshl_add_u64 v[242:243], s[48:49], 0, v[162:163]
	s_mov_b32 m0, s54
	s_nop 0
	global_load_lds_dwordx4 v[242:243], off
	s_barrier
	s_waitcnt lgkmcnt(0)
	s_setprio 1
	s_waitcnt lgkmcnt(0)
	v_mfma_f32_16x16x32_bf16 v[94:97], v[34:37], v[118:121], 0
	v_mfma_f32_16x16x32_bf16 v[90:93], v[42:45], v[118:121], 0
	v_mfma_f32_16x16x32_bf16 v[78:81], v[34:37], v[134:137], 0
	v_mfma_f32_16x16x32_bf16 v[74:77], v[42:45], v[134:137], 0
	v_mfma_f32_16x16x32_bf16 v[30:33], v[34:37], v[170:173], 0
	v_mfma_f32_16x16x32_bf16 v[26:29], v[42:45], v[170:173], 0
	v_mfma_f32_16x16x32_bf16 v[14:17], v[34:37], v[178:181], 0
	v_mfma_f32_16x16x32_bf16 v[10:13], v[42:45], v[178:181], 0
	v_mfma_f32_16x16x32_bf16 v[94:97], v[38:41], v[130:133], v[94:97]
	v_mfma_f32_16x16x32_bf16 v[90:93], v[46:49], v[130:133], v[90:93]
	v_mfma_f32_16x16x32_bf16 v[78:81], v[38:41], v[146:149], v[78:81]
	v_mfma_f32_16x16x32_bf16 v[74:77], v[46:49], v[146:149], v[74:77]
	v_mfma_f32_16x16x32_bf16 v[30:33], v[38:41], v[174:177], v[30:33]
	v_mfma_f32_16x16x32_bf16 v[26:29], v[46:49], v[174:177], v[26:29]
	v_mfma_f32_16x16x32_bf16 v[14:17], v[38:41], v[182:185], v[14:17]
	v_mfma_f32_16x16x32_bf16 v[10:13], v[46:49], v[182:185], v[10:13]
	s_setprio 0
	s_barrier
	s_add_u32 s4, s46, 0x40000
	s_addc_u32 s5, s47, 0
	s_add_i32 s67, s68, s52
	v_lshl_add_u64 v[34:35], s[4:5], 0, v[164:165]
	s_mov_b32 m0, s67
	s_nop 0
	global_load_lds_dwordx4 v[34:35], off
	v_lshl_add_u64 v[34:35], s[4:5], 0, v[162:163]
	s_add_i32 m0, s67, 0x2000
	s_nop 0
	global_load_lds_dwordx4 v[34:35], off
	s_barrier
	s_setprio 1
	v_mfma_f32_16x16x32_bf16 v[22:25], v[186:189], v[170:173], 0
	v_mfma_f32_16x16x32_bf16 v[18:21], v[222:225], v[170:173], 0
	v_mfma_f32_16x16x32_bf16 v[6:9], v[186:189], v[178:181], 0
	v_mfma_f32_16x16x32_bf16 v[2:5], v[222:225], v[178:181], 0
	v_mfma_f32_16x16x32_bf16 v[34:37], v[186:189], v[118:121], 0
	v_mfma_f32_16x16x32_bf16 v[38:41], v[222:225], v[118:121], 0
	v_mfma_f32_16x16x32_bf16 v[42:45], v[186:189], v[134:137], 0
	v_mfma_f32_16x16x32_bf16 v[46:49], v[222:225], v[134:137], 0
	v_mfma_f32_16x16x32_bf16 v[22:25], v[208:211], v[174:177], v[22:25]
	v_mfma_f32_16x16x32_bf16 v[18:21], v[226:229], v[174:177], v[18:21]
	v_mfma_f32_16x16x32_bf16 v[6:9], v[208:211], v[182:185], v[6:9]
	v_mfma_f32_16x16x32_bf16 v[2:5], v[226:229], v[182:185], v[2:5]
	v_mfma_f32_16x16x32_bf16 v[34:37], v[208:211], v[130:133], v[34:37]
	v_mfma_f32_16x16x32_bf16 v[38:41], v[226:229], v[130:133], v[38:41]
	v_mfma_f32_16x16x32_bf16 v[42:45], v[208:211], v[146:149], v[42:45]
	v_mfma_f32_16x16x32_bf16 v[46:49], v[226:229], v[146:149], v[46:49]
	s_setprio 0
	s_add_i32 s67, 0, 0x18000
	v_add_u32_e32 v1, s67, v191
	s_barrier
	ds_read_b128 v[54:57], v1
	ds_read_b128 v[70:73], v1 offset:1024
	ds_read_b128 v[82:85], v1 offset:2048
	ds_read_b128 v[86:89], v1 offset:3072
	s_add_u32 s4, s48, 0x40000
	s_addc_u32 s5, s49, 0
	s_mov_b32 m0, s55
	v_lshl_add_u64 v[134:135], s[4:5], 0, v[164:165]
	ds_read_b128 v[118:121], v206 offset:32768
	ds_read_b128 v[130:133], v206 offset:33792
	ds_read_b128 v[170:173], v206 offset:34816
	ds_read_b128 v[174:177], v206 offset:35840
	ds_read_b128 v[178:181], v206 offset:36864
	ds_read_b128 v[182:185], v206 offset:37888
	ds_read_b128 v[186:189], v206 offset:38912
	ds_read_b128 v[208:211], v206 offset:39936
	global_load_lds_dwordx4 v[134:135], off
	v_lshl_add_u64 v[134:135], s[4:5], 0, v[162:163]
	s_mov_b32 m0, s56
	s_nop 0
	global_load_lds_dwordx4 v[134:135], off
	s_waitcnt lgkmcnt(8)
	s_barrier
	s_waitcnt lgkmcnt(0)
	s_setprio 1
	s_waitcnt lgkmcnt(0)
	v_mfma_f32_16x16x32_bf16 v[134:137], v[54:57], v[118:121], v[158:161]
	v_mfma_f32_16x16x32_bf16 v[158:161], v[70:73], v[130:133], v[134:137]
	v_mfma_f32_16x16x32_bf16 v[134:137], v[82:85], v[118:121], v[154:157]
	v_mfma_f32_16x16x32_bf16 v[154:157], v[86:89], v[130:133], v[134:137]
	v_mfma_f32_16x16x32_bf16 v[134:137], v[54:57], v[170:173], v[142:145]
	v_mfma_f32_16x16x32_bf16 v[142:145], v[70:73], v[174:177], v[134:137]
	v_mfma_f32_16x16x32_bf16 v[134:137], v[82:85], v[170:173], v[138:141]
	v_mfma_f32_16x16x32_bf16 v[126:129], v[54:57], v[178:181], v[126:129]
	v_mfma_f32_16x16x32_bf16 v[122:125], v[82:85], v[178:181], v[122:125]
	v_mfma_f32_16x16x32_bf16 v[110:113], v[54:57], v[186:189], v[110:113]
	v_mfma_f32_16x16x32_bf16 v[106:109], v[82:85], v[186:189], v[106:109]
	v_mfma_f32_16x16x32_bf16 v[138:141], v[86:89], v[174:177], v[134:137]
	v_mfma_f32_16x16x32_bf16 v[126:129], v[70:73], v[182:185], v[126:129]
	v_mfma_f32_16x16x32_bf16 v[122:125], v[86:89], v[182:185], v[122:125]
	v_mfma_f32_16x16x32_bf16 v[110:113], v[70:73], v[208:211], v[110:113]
	v_mfma_f32_16x16x32_bf16 v[106:109], v[86:89], v[208:211], v[106:109]
	s_setprio 0
	s_barrier
	s_add_i32 s48, 0, 0x1c000
	s_add_i32 s4, s67, s52
	v_add_u32_e32 v1, s48, v191
	v_lshl_add_u64 v[134:135], v[214:215], 0, s[22:23]
	s_mov_b32 m0, s4
	ds_read_b128 v[222:225], v1
	ds_read_b128 v[226:229], v1 offset:1024
	ds_read_b128 v[230:233], v1 offset:2048
	ds_read_b128 v[234:237], v1 offset:3072
	global_load_lds_dwordx4 v[134:135], off
	v_lshl_add_u64 v[134:135], v[238:239], 0, s[22:23]
	s_add_i32 m0, s4, 0x2000
	s_nop 0
	global_load_lds_dwordx4 v[134:135], off
	s_barrier
	s_waitcnt lgkmcnt(0)
	s_setprio 1
	s_waitcnt lgkmcnt(0)
	v_mfma_f32_16x16x32_bf16 v[50:53], v[230:233], v[118:121], v[50:53]
	v_mfma_f32_16x16x32_bf16 v[134:137], v[222:225], v[118:121], v[150:153]
	v_mfma_f32_16x16x32_bf16 v[146:149], v[234:237], v[130:133], v[50:53]
	v_mfma_f32_16x16x32_bf16 v[50:53], v[222:225], v[170:173], v[58:61]
	v_mfma_f32_16x16x32_bf16 v[150:153], v[226:229], v[130:133], v[134:137]
	v_mfma_f32_16x16x32_bf16 v[134:137], v[226:229], v[174:177], v[50:53]
	v_mfma_f32_16x16x32_bf16 v[50:53], v[230:233], v[170:173], v[62:65]
	v_mfma_f32_16x16x32_bf16 v[130:133], v[234:237], v[174:177], v[50:53]
	v_mfma_f32_16x16x32_bf16 v[50:53], v[222:225], v[178:181], v[66:69]
	v_mfma_f32_16x16x32_bf16 v[118:121], v[226:229], v[182:185], v[50:53]
	v_mfma_f32_16x16x32_bf16 v[50:53], v[230:233], v[178:181], v[114:117]
	v_mfma_f32_16x16x32_bf16 v[114:117], v[234:237], v[182:185], v[50:53]
	v_mfma_f32_16x16x32_bf16 v[50:53], v[222:225], v[186:189], v[102:105]
	v_mfma_f32_16x16x32_bf16 v[102:105], v[226:229], v[208:211], v[50:53]
	v_mfma_f32_16x16x32_bf16 v[50:53], v[230:233], v[186:189], v[98:101]
	v_mfma_f32_16x16x32_bf16 v[98:101], v[234:237], v[208:211], v[50:53]
	s_setprio 0
	s_mov_b32 m0, s58
	v_lshl_add_u64 v[186:187], v[240:241], 0, s[22:23]
	s_barrier
	s_nop 2
	ds_read_b128 v[50:53], v206 offset:49152
	ds_read_b128 v[58:61], v206 offset:50176
	ds_read_b128 v[62:65], v206 offset:51200
	ds_read_b128 v[66:69], v206 offset:52224
	ds_read_b128 v[170:173], v206 offset:53248
	ds_read_b128 v[174:177], v206 offset:54272
	ds_read_b128 v[178:181], v206 offset:55296
	ds_read_b128 v[182:185], v206 offset:56320
	global_load_lds_dwordx4 v[186:187], off
	v_lshl_add_u64 v[186:187], v[242:243], 0, s[22:23]
	s_mov_b32 m0, s59
	s_nop 0
	global_load_lds_dwordx4 v[186:187], off
	s_barrier
	s_waitcnt lgkmcnt(0)
	s_setprio 1
	s_waitcnt lgkmcnt(0)
	v_mfma_f32_16x16x32_bf16 v[94:97], v[54:57], v[50:53], v[94:97]
	v_mfma_f32_16x16x32_bf16 v[90:93], v[82:85], v[50:53], v[90:93]
	v_mfma_f32_16x16x32_bf16 v[78:81], v[54:57], v[62:65], v[78:81]
	v_mfma_f32_16x16x32_bf16 v[74:77], v[82:85], v[62:65], v[74:77]
	v_mfma_f32_16x16x32_bf16 v[30:33], v[54:57], v[170:173], v[30:33]
	v_mfma_f32_16x16x32_bf16 v[26:29], v[82:85], v[170:173], v[26:29]
	v_mfma_f32_16x16x32_bf16 v[14:17], v[54:57], v[178:181], v[14:17]
	v_mfma_f32_16x16x32_bf16 v[10:13], v[82:85], v[178:181], v[10:13]
	v_mfma_f32_16x16x32_bf16 v[94:97], v[70:73], v[58:61], v[94:97]
	v_mfma_f32_16x16x32_bf16 v[90:93], v[86:89], v[58:61], v[90:93]
	v_mfma_f32_16x16x32_bf16 v[78:81], v[70:73], v[66:69], v[78:81]
	v_mfma_f32_16x16x32_bf16 v[74:77], v[86:89], v[66:69], v[74:77]
	v_mfma_f32_16x16x32_bf16 v[30:33], v[70:73], v[174:177], v[30:33]
	v_mfma_f32_16x16x32_bf16 v[26:29], v[86:89], v[174:177], v[26:29]
	v_mfma_f32_16x16x32_bf16 v[14:17], v[70:73], v[182:185], v[14:17]
	v_mfma_f32_16x16x32_bf16 v[10:13], v[86:89], v[182:185], v[10:13]
	s_setprio 0
	s_barrier
	s_add_u32 s4, s46, 0x40080
	s_addc_u32 s5, s47, 0
	s_add_i32 s46, s48, s52
	v_lshl_add_u64 v[54:55], s[4:5], 0, v[164:165]
	s_mov_b32 m0, s46
	s_nop 0
	global_load_lds_dwordx4 v[54:55], off
	v_lshl_add_u64 v[54:55], s[4:5], 0, v[162:163]
	s_add_i32 m0, s46, 0x2000
	s_nop 0
	global_load_lds_dwordx4 v[54:55], off
	s_waitcnt vmcnt(6)
	s_barrier
	s_setprio 1
	v_mfma_f32_16x16x32_bf16 v[34:37], v[222:225], v[50:53], v[34:37]
	v_mfma_f32_16x16x32_bf16 v[86:89], v[226:229], v[58:61], v[34:37]
	v_mfma_f32_16x16x32_bf16 v[34:37], v[230:233], v[50:53], v[38:41]
	v_mfma_f32_16x16x32_bf16 v[82:85], v[234:237], v[58:61], v[34:37]
	v_mfma_f32_16x16x32_bf16 v[34:37], v[222:225], v[62:65], v[42:45]
	v_mfma_f32_16x16x32_bf16 v[70:73], v[226:229], v[66:69], v[34:37]
	v_mfma_f32_16x16x32_bf16 v[34:37], v[230:233], v[62:65], v[46:49]
	v_mfma_f32_16x16x32_bf16 v[22:25], v[222:225], v[170:173], v[22:25]
	v_mfma_f32_16x16x32_bf16 v[18:21], v[230:233], v[170:173], v[18:21]
	v_mfma_f32_16x16x32_bf16 v[6:9], v[222:225], v[178:181], v[6:9]
	v_mfma_f32_16x16x32_bf16 v[2:5], v[230:233], v[178:181], v[2:5]
	v_mfma_f32_16x16x32_bf16 v[54:57], v[234:237], v[66:69], v[34:37]
	v_mfma_f32_16x16x32_bf16 v[22:25], v[226:229], v[174:177], v[22:25]
	v_mfma_f32_16x16x32_bf16 v[18:21], v[234:237], v[174:177], v[18:21]
	v_mfma_f32_16x16x32_bf16 v[6:9], v[226:229], v[182:185], v[6:9]
	v_mfma_f32_16x16x32_bf16 v[2:5], v[234:237], v[182:185], v[2:5]
	s_setprio 0
	s_add_i32 s66, s66, 2
	s_add_u32 s64, s64, 0x100
	s_addc_u32 s65, s65, 0
	s_cmp_gt_u32 s66, 13
	s_mov_b64 s[4:5], s[36:37]
	s_barrier
	s_branch .LBB0_212

.LBB0_212:
	s_add_u32 s36, s4, 0x100
	s_addc_u32 s37, s5, 0
	s_add_i32 s67, 0, 0x10000
	v_add_u32_e32 v1, s67, v191
	ds_read_b128 v[34:37], v1
	ds_read_b128 v[38:41], v1 offset:1024
	ds_read_b128 v[42:45], v1 offset:2048
	ds_read_b128 v[46:49], v1 offset:3072
	s_cmp_eq_u32 s66, 12
	s_cselect_b32 s49, s38, s37
	s_cselect_b32 s48, s43, s36
	s_cselect_b32 s47, s62, s65
	s_cselect_b32 s46, s63, s64
	v_lshl_add_u64 v[186:187], s[4:5], 0, v[168:169]
	s_add_i32 m0, s53, 0xc000
	ds_read_b128 v[50:53], v206
	ds_read_b128 v[58:61], v206 offset:1024
	ds_read_b128 v[62:65], v206 offset:2048
	ds_read_b128 v[66:69], v206 offset:3072
	ds_read_b128 v[170:173], v206 offset:4096
	ds_read_b128 v[174:177], v206 offset:5120
	ds_read_b128 v[178:181], v206 offset:6144
	ds_read_b128 v[182:185], v206 offset:7168
	global_load_lds_dwordx4 v[186:187], off
	v_lshl_add_u64 v[186:187], s[4:5], 0, v[166:167]
	s_add_i32 m0, s53, 0xe000
	s_nop 0
	global_load_lds_dwordx4 v[186:187], off
	s_waitcnt lgkmcnt(8)
	s_barrier
	s_waitcnt lgkmcnt(0)
	s_setprio 1
	s_waitcnt lgkmcnt(0)
	v_mfma_f32_16x16x32_bf16 v[158:161], v[34:37], v[50:53], v[158:161]
	v_mfma_f32_16x16x32_bf16 v[154:157], v[42:45], v[50:53], v[154:157]
	v_mfma_f32_16x16x32_bf16 v[142:145], v[34:37], v[62:65], v[142:145]
	v_mfma_f32_16x16x32_bf16 v[138:141], v[42:45], v[62:65], v[138:141]
	v_mfma_f32_16x16x32_bf16 v[126:129], v[34:37], v[170:173], v[126:129]
	v_mfma_f32_16x16x32_bf16 v[122:125], v[42:45], v[170:173], v[122:125]
	v_mfma_f32_16x16x32_bf16 v[110:113], v[34:37], v[178:181], v[110:113]
	v_mfma_f32_16x16x32_bf16 v[106:109], v[42:45], v[178:181], v[106:109]
	v_mfma_f32_16x16x32_bf16 v[158:161], v[38:41], v[58:61], v[158:161]
	v_mfma_f32_16x16x32_bf16 v[154:157], v[46:49], v[58:61], v[154:157]
	v_mfma_f32_16x16x32_bf16 v[142:145], v[38:41], v[66:69], v[142:145]
	v_mfma_f32_16x16x32_bf16 v[138:141], v[46:49], v[66:69], v[138:141]
	v_mfma_f32_16x16x32_bf16 v[126:129], v[38:41], v[174:177], v[126:129]
	v_mfma_f32_16x16x32_bf16 v[122:125], v[46:49], v[174:177], v[122:125]
	v_mfma_f32_16x16x32_bf16 v[110:113], v[38:41], v[182:185], v[110:113]
	v_mfma_f32_16x16x32_bf16 v[106:109], v[46:49], v[182:185], v[106:109]
	s_setprio 0
	s_barrier
	s_add_i32 s68, 0, 0x14000
	s_add_i32 s4, s67, s52
	v_add_u32_e32 v1, s68, v191
	v_lshl_add_u64 v[214:215], s[46:47], 0, v[164:165]
	s_mov_b32 m0, s4
	ds_read_b128 v[186:189], v1
	ds_read_b128 v[208:211], v1 offset:1024
	ds_read_b128 v[222:225], v1 offset:2048
	ds_read_b128 v[226:229], v1 offset:3072
	global_load_lds_dwordx4 v[214:215], off
	v_lshl_add_u64 v[238:239], s[46:47], 0, v[162:163]
	s_add_i32 m0, s4, 0x2000
	s_nop 0
	global_load_lds_dwordx4 v[238:239], off
	s_barrier
	s_waitcnt lgkmcnt(0)
	s_setprio 1
	s_waitcnt lgkmcnt(0)
	v_mfma_f32_16x16x32_bf16 v[150:153], v[186:189], v[50:53], v[150:153]
	v_mfma_f32_16x16x32_bf16 v[50:53], v[222:225], v[50:53], v[146:149]
	v_mfma_f32_16x16x32_bf16 v[150:153], v[208:211], v[58:61], v[150:153]
	v_mfma_f32_16x16x32_bf16 v[50:53], v[226:229], v[58:61], v[50:53]
	v_mfma_f32_16x16x32_bf16 v[58:61], v[186:189], v[62:65], v[134:137]
	v_mfma_f32_16x16x32_bf16 v[62:65], v[222:225], v[62:65], v[130:133]
	v_mfma_f32_16x16x32_bf16 v[114:117], v[222:225], v[170:173], v[114:117]
	v_mfma_f32_16x16x32_bf16 v[102:105], v[186:189], v[178:181], v[102:105]
	v_mfma_f32_16x16x32_bf16 v[98:101], v[222:225], v[178:181], v[98:101]
	v_mfma_f32_16x16x32_bf16 v[58:61], v[208:211], v[66:69], v[58:61]
	v_mfma_f32_16x16x32_bf16 v[62:65], v[226:229], v[66:69], v[62:65]
	v_mfma_f32_16x16x32_bf16 v[66:69], v[186:189], v[170:173], v[118:121]
	v_mfma_f32_16x16x32_bf16 v[114:117], v[226:229], v[174:177], v[114:117]
	v_mfma_f32_16x16x32_bf16 v[102:105], v[208:211], v[182:185], v[102:105]
	v_mfma_f32_16x16x32_bf16 v[98:101], v[226:229], v[182:185], v[98:101]
	v_mfma_f32_16x16x32_bf16 v[66:69], v[208:211], v[174:177], v[66:69]
	s_setprio 0
	s_mov_b32 m0, s53
	v_lshl_add_u64 v[240:241], s[48:49], 0, v[164:165]
	s_barrier
	ds_read_b128 v[118:121], v206 offset:16384
	ds_read_b128 v[130:133], v206 offset:17408
	ds_read_b128 v[134:137], v206 offset:18432
	ds_read_b128 v[146:149], v206 offset:19456
	ds_read_b128 v[170:173], v206 offset:20480
	ds_read_b128 v[174:177], v206 offset:21504
	ds_read_b128 v[178:181], v206 offset:22528
	ds_read_b128 v[182:185], v206 offset:23552
	global_load_lds_dwordx4 v[240:241], off
	v_lshl_add_u64 v[242:243], s[48:49], 0, v[162:163]
	s_mov_b32 m0, s54
	s_nop 0
	global_load_lds_dwordx4 v[242:243], off
	s_barrier
	s_waitcnt lgkmcnt(0)
	s_setprio 1
	s_waitcnt lgkmcnt(0)
	v_mfma_f32_16x16x32_bf16 v[94:97], v[34:37], v[118:121], v[94:97]
	v_mfma_f32_16x16x32_bf16 v[90:93], v[42:45], v[118:121], v[90:93]
	v_mfma_f32_16x16x32_bf16 v[78:81], v[34:37], v[134:137], v[78:81]
	v_mfma_f32_16x16x32_bf16 v[74:77], v[42:45], v[134:137], v[74:77]
	v_mfma_f32_16x16x32_bf16 v[30:33], v[34:37], v[170:173], v[30:33]
	v_mfma_f32_16x16x32_bf16 v[26:29], v[42:45], v[170:173], v[26:29]
	v_mfma_f32_16x16x32_bf16 v[14:17], v[34:37], v[178:181], v[14:17]
	v_mfma_f32_16x16x32_bf16 v[10:13], v[42:45], v[178:181], v[10:13]
	v_mfma_f32_16x16x32_bf16 v[94:97], v[38:41], v[130:133], v[94:97]
	v_mfma_f32_16x16x32_bf16 v[90:93], v[46:49], v[130:133], v[90:93]
	v_mfma_f32_16x16x32_bf16 v[78:81], v[38:41], v[146:149], v[78:81]
	v_mfma_f32_16x16x32_bf16 v[74:77], v[46:49], v[146:149], v[74:77]
	v_mfma_f32_16x16x32_bf16 v[30:33], v[38:41], v[174:177], v[30:33]
	v_mfma_f32_16x16x32_bf16 v[26:29], v[46:49], v[174:177], v[26:29]
	v_mfma_f32_16x16x32_bf16 v[14:17], v[38:41], v[182:185], v[14:17]
	v_mfma_f32_16x16x32_bf16 v[10:13], v[46:49], v[182:185], v[10:13]
	s_setprio 0
	s_barrier
	s_add_u32 s4, s46, 0x40000
	s_addc_u32 s5, s47, 0
	s_add_i32 s67, s68, s52
	v_lshl_add_u64 v[34:35], s[4:5], 0, v[164:165]
	s_mov_b32 m0, s67
	s_nop 0
	global_load_lds_dwordx4 v[34:35], off
	v_lshl_add_u64 v[34:35], s[4:5], 0, v[162:163]
	s_add_i32 m0, s67, 0x2000
	s_nop 0
	global_load_lds_dwordx4 v[34:35], off
	s_waitcnt vmcnt(6)
	s_barrier
	s_setprio 1
	v_mfma_f32_16x16x32_bf16 v[22:25], v[186:189], v[170:173], v[22:25]
	v_mfma_f32_16x16x32_bf16 v[18:21], v[222:225], v[170:173], v[18:21]
	v_mfma_f32_16x16x32_bf16 v[6:9], v[186:189], v[178:181], v[6:9]
	v_mfma_f32_16x16x32_bf16 v[2:5], v[222:225], v[178:181], v[2:5]
	v_mfma_f32_16x16x32_bf16 v[34:37], v[186:189], v[118:121], v[86:89]
	v_mfma_f32_16x16x32_bf16 v[38:41], v[222:225], v[118:121], v[82:85]
	v_mfma_f32_16x16x32_bf16 v[42:45], v[186:189], v[134:137], v[70:73]
	v_mfma_f32_16x16x32_bf16 v[46:49], v[222:225], v[134:137], v[54:57]
	v_mfma_f32_16x16x32_bf16 v[22:25], v[208:211], v[174:177], v[22:25]
	v_mfma_f32_16x16x32_bf16 v[18:21], v[226:229], v[174:177], v[18:21]
	v_mfma_f32_16x16x32_bf16 v[6:9], v[208:211], v[182:185], v[6:9]
	v_mfma_f32_16x16x32_bf16 v[2:5], v[226:229], v[182:185], v[2:5]
	v_mfma_f32_16x16x32_bf16 v[34:37], v[208:211], v[130:133], v[34:37]
	v_mfma_f32_16x16x32_bf16 v[38:41], v[226:229], v[130:133], v[38:41]
	v_mfma_f32_16x16x32_bf16 v[42:45], v[208:211], v[146:149], v[42:45]
	v_mfma_f32_16x16x32_bf16 v[46:49], v[226:229], v[146:149], v[46:49]
	s_setprio 0
	s_add_i32 s67, 0, 0x18000
	v_add_u32_e32 v1, s67, v191
	s_barrier
	ds_read_b128 v[54:57], v1
	ds_read_b128 v[70:73], v1 offset:1024
	ds_read_b128 v[82:85], v1 offset:2048
	ds_read_b128 v[86:89], v1 offset:3072
	s_add_u32 s4, s48, 0x40000
	s_addc_u32 s5, s49, 0
	s_mov_b32 m0, s55
	v_lshl_add_u64 v[134:135], s[4:5], 0, v[164:165]
	ds_read_b128 v[118:121], v206 offset:32768
	ds_read_b128 v[130:133], v206 offset:33792
	ds_read_b128 v[170:173], v206 offset:34816
	ds_read_b128 v[174:177], v206 offset:35840
	ds_read_b128 v[178:181], v206 offset:36864
	ds_read_b128 v[182:185], v206 offset:37888
	ds_read_b128 v[186:189], v206 offset:38912
	ds_read_b128 v[208:211], v206 offset:39936
	global_load_lds_dwordx4 v[134:135], off
	v_lshl_add_u64 v[134:135], s[4:5], 0, v[162:163]
	s_mov_b32 m0, s56
	s_nop 0
	global_load_lds_dwordx4 v[134:135], off
	s_waitcnt lgkmcnt(8)
	s_barrier
	s_waitcnt lgkmcnt(0)
	s_setprio 1
	s_waitcnt lgkmcnt(0)
	v_mfma_f32_16x16x32_bf16 v[134:137], v[54:57], v[118:121], v[158:161]
	v_mfma_f32_16x16x32_bf16 v[158:161], v[70:73], v[130:133], v[134:137]
	v_mfma_f32_16x16x32_bf16 v[134:137], v[82:85], v[118:121], v[154:157]
	v_mfma_f32_16x16x32_bf16 v[154:157], v[86:89], v[130:133], v[134:137]
	v_mfma_f32_16x16x32_bf16 v[134:137], v[54:57], v[170:173], v[142:145]
	v_mfma_f32_16x16x32_bf16 v[142:145], v[70:73], v[174:177], v[134:137]
	v_mfma_f32_16x16x32_bf16 v[134:137], v[82:85], v[170:173], v[138:141]
	v_mfma_f32_16x16x32_bf16 v[126:129], v[54:57], v[178:181], v[126:129]
	v_mfma_f32_16x16x32_bf16 v[122:125], v[82:85], v[178:181], v[122:125]
	v_mfma_f32_16x16x32_bf16 v[110:113], v[54:57], v[186:189], v[110:113]
	v_mfma_f32_16x16x32_bf16 v[106:109], v[82:85], v[186:189], v[106:109]
	v_mfma_f32_16x16x32_bf16 v[138:141], v[86:89], v[174:177], v[134:137]
	v_mfma_f32_16x16x32_bf16 v[126:129], v[70:73], v[182:185], v[126:129]
	v_mfma_f32_16x16x32_bf16 v[122:125], v[86:89], v[182:185], v[122:125]
	v_mfma_f32_16x16x32_bf16 v[110:113], v[70:73], v[208:211], v[110:113]
	v_mfma_f32_16x16x32_bf16 v[106:109], v[86:89], v[208:211], v[106:109]
	s_setprio 0
	s_barrier
	s_add_i32 s48, 0, 0x1c000
	s_add_i32 s4, s67, s52
	v_add_u32_e32 v1, s48, v191
	v_lshl_add_u64 v[134:135], v[214:215], 0, s[22:23]
	s_mov_b32 m0, s4
	ds_read_b128 v[222:225], v1
	ds_read_b128 v[226:229], v1 offset:1024
	ds_read_b128 v[230:233], v1 offset:2048
	ds_read_b128 v[234:237], v1 offset:3072
	global_load_lds_dwordx4 v[134:135], off
	v_lshl_add_u64 v[134:135], v[238:239], 0, s[22:23]
	s_add_i32 m0, s4, 0x2000
	s_nop 0
	global_load_lds_dwordx4 v[134:135], off
	s_barrier
	s_waitcnt lgkmcnt(0)
	s_setprio 1
	s_waitcnt lgkmcnt(0)
	v_mfma_f32_16x16x32_bf16 v[50:53], v[230:233], v[118:121], v[50:53]
	v_mfma_f32_16x16x32_bf16 v[134:137], v[222:225], v[118:121], v[150:153]
	v_mfma_f32_16x16x32_bf16 v[146:149], v[234:237], v[130:133], v[50:53]
	v_mfma_f32_16x16x32_bf16 v[50:53], v[222:225], v[170:173], v[58:61]
	v_mfma_f32_16x16x32_bf16 v[150:153], v[226:229], v[130:133], v[134:137]
	v_mfma_f32_16x16x32_bf16 v[134:137], v[226:229], v[174:177], v[50:53]
	v_mfma_f32_16x16x32_bf16 v[50:53], v[230:233], v[170:173], v[62:65]
	v_mfma_f32_16x16x32_bf16 v[130:133], v[234:237], v[174:177], v[50:53]
	v_mfma_f32_16x16x32_bf16 v[50:53], v[222:225], v[178:181], v[66:69]
	v_mfma_f32_16x16x32_bf16 v[118:121], v[226:229], v[182:185], v[50:53]
	v_mfma_f32_16x16x32_bf16 v[50:53], v[230:233], v[178:181], v[114:117]
	v_mfma_f32_16x16x32_bf16 v[114:117], v[234:237], v[182:185], v[50:53]
	v_mfma_f32_16x16x32_bf16 v[50:53], v[222:225], v[186:189], v[102:105]
	v_mfma_f32_16x16x32_bf16 v[102:105], v[226:229], v[208:211], v[50:53]
	v_mfma_f32_16x16x32_bf16 v[50:53], v[230:233], v[186:189], v[98:101]
	v_mfma_f32_16x16x32_bf16 v[98:101], v[234:237], v[208:211], v[50:53]
	s_setprio 0
	s_mov_b32 m0, s58
	v_lshl_add_u64 v[186:187], v[240:241], 0, s[22:23]
	s_barrier
	s_nop 2
	ds_read_b128 v[50:53], v206 offset:49152
	ds_read_b128 v[58:61], v206 offset:50176
	ds_read_b128 v[62:65], v206 offset:51200
	ds_read_b128 v[66:69], v206 offset:52224
	ds_read_b128 v[170:173], v206 offset:53248
	ds_read_b128 v[174:177], v206 offset:54272
	ds_read_b128 v[178:181], v206 offset:55296
	ds_read_b128 v[182:185], v206 offset:56320
	global_load_lds_dwordx4 v[186:187], off
	v_lshl_add_u64 v[186:187], v[242:243], 0, s[22:23]
	s_mov_b32 m0, s59
	s_nop 0
	global_load_lds_dwordx4 v[186:187], off
	s_barrier
	s_waitcnt lgkmcnt(0)
	s_setprio 1
	s_waitcnt lgkmcnt(0)
	v_mfma_f32_16x16x32_bf16 v[94:97], v[54:57], v[50:53], v[94:97]
	v_mfma_f32_16x16x32_bf16 v[90:93], v[82:85], v[50:53], v[90:93]
	v_mfma_f32_16x16x32_bf16 v[78:81], v[54:57], v[62:65], v[78:81]
	v_mfma_f32_16x16x32_bf16 v[74:77], v[82:85], v[62:65], v[74:77]
	v_mfma_f32_16x16x32_bf16 v[30:33], v[54:57], v[170:173], v[30:33]
	v_mfma_f32_16x16x32_bf16 v[26:29], v[82:85], v[170:173], v[26:29]
	v_mfma_f32_16x16x32_bf16 v[14:17], v[54:57], v[178:181], v[14:17]
	v_mfma_f32_16x16x32_bf16 v[10:13], v[82:85], v[178:181], v[10:13]
	v_mfma_f32_16x16x32_bf16 v[94:97], v[70:73], v[58:61], v[94:97]
	v_mfma_f32_16x16x32_bf16 v[90:93], v[86:89], v[58:61], v[90:93]
	v_mfma_f32_16x16x32_bf16 v[78:81], v[70:73], v[66:69], v[78:81]
	v_mfma_f32_16x16x32_bf16 v[74:77], v[86:89], v[66:69], v[74:77]
	v_mfma_f32_16x16x32_bf16 v[30:33], v[70:73], v[174:177], v[30:33]
	v_mfma_f32_16x16x32_bf16 v[26:29], v[86:89], v[174:177], v[26:29]
	v_mfma_f32_16x16x32_bf16 v[14:17], v[70:73], v[182:185], v[14:17]
	v_mfma_f32_16x16x32_bf16 v[10:13], v[86:89], v[182:185], v[10:13]
	s_setprio 0
	s_barrier
	s_add_u32 s4, s46, 0x40080
	s_addc_u32 s5, s47, 0
	s_add_i32 s46, s48, s52
	v_lshl_add_u64 v[54:55], s[4:5], 0, v[164:165]
	s_mov_b32 m0, s46
	s_nop 0
	global_load_lds_dwordx4 v[54:55], off
	v_lshl_add_u64 v[54:55], s[4:5], 0, v[162:163]
	s_add_i32 m0, s46, 0x2000
	s_nop 0
	global_load_lds_dwordx4 v[54:55], off
	s_waitcnt vmcnt(6)
	s_barrier
	s_setprio 1
	v_mfma_f32_16x16x32_bf16 v[34:37], v[222:225], v[50:53], v[34:37]
	v_mfma_f32_16x16x32_bf16 v[86:89], v[226:229], v[58:61], v[34:37]
	v_mfma_f32_16x16x32_bf16 v[34:37], v[230:233], v[50:53], v[38:41]
	v_mfma_f32_16x16x32_bf16 v[82:85], v[234:237], v[58:61], v[34:37]
	v_mfma_f32_16x16x32_bf16 v[34:37], v[222:225], v[62:65], v[42:45]
	v_mfma_f32_16x16x32_bf16 v[70:73], v[226:229], v[66:69], v[34:37]
	v_mfma_f32_16x16x32_bf16 v[34:37], v[230:233], v[62:65], v[46:49]
	v_mfma_f32_16x16x32_bf16 v[22:25], v[222:225], v[170:173], v[22:25]
	v_mfma_f32_16x16x32_bf16 v[18:21], v[230:233], v[170:173], v[18:21]
	v_mfma_f32_16x16x32_bf16 v[6:9], v[222:225], v[178:181], v[6:9]
	v_mfma_f32_16x16x32_bf16 v[2:5], v[230:233], v[178:181], v[2:5]
	v_mfma_f32_16x16x32_bf16 v[54:57], v[234:237], v[66:69], v[34:37]
	v_mfma_f32_16x16x32_bf16 v[22:25], v[226:229], v[174:177], v[22:25]
	v_mfma_f32_16x16x32_bf16 v[18:21], v[234:237], v[174:177], v[18:21]
	v_mfma_f32_16x16x32_bf16 v[6:9], v[226:229], v[182:185], v[6:9]
	v_mfma_f32_16x16x32_bf16 v[2:5], v[234:237], v[182:185], v[2:5]
	s_setprio 0
	s_add_i32 s66, s66, 2
	s_add_u32 s64, s64, 0x100
	s_addc_u32 s65, s65, 0
	s_cmp_gt_u32 s66, 13
	s_mov_b64 s[4:5], s[36:37]
	s_barrier
	s_cbranch_scc0 .LBB0_212
	v_lshl_add_u64 v[250:251], s[20:21], 0, v[168:169]
	s_add_i32 m0, s53, 0xc000
	s_nop 0
	global_load_lds_dwordx4 v[250:251], off
	v_lshl_add_u64 v[250:251], s[20:21], 0, v[166:167]
	s_add_i32 m0, s53, 0xe000
	s_nop 0
	global_load_lds_dwordx4 v[250:251], off
	v_lshl_or_b32 v208, s3, 8, v192
	v_mov_b32_e32 v1, v190
	v_ashrrev_i32_e32 v209, 31, v208
	v_lshlrev_b64 v[34:35], 2, v[208:209]
	v_lshl_add_u64 v[36:37], s[8:9], 0, v[34:35]
	flat_load_dwordx4 v[62:65], v[36:37]
	flat_load_dwordx4 v[50:53], v[36:37] offset:16
	v_lshl_add_u64 v[34:35], s[10:11], 0, v[34:35]
	flat_load_dwordx4 v[66:69], v[34:35]
	flat_load_dwordx4 v[42:45], v[34:35] offset:16
	flat_load_dwordx4 v[58:61], v[36:37] offset:512
	flat_load_dwordx4 v[38:41], v[36:37] offset:528
	flat_load_dwordx4 v[46:49], v[34:35] offset:512
	s_nop 0
	flat_load_dwordx4 v[34:37], v[34:35] offset:528
	s_lshl_b32 s37, s27, 8
	v_lshl_add_u32 v170, v1, 3, 0
	v_add_u32_e32 v170, 0x20040, v170
	s_waitcnt vmcnt(0)
	ds_read_b64 v[188:189], v170
	s_mov_b32 s4, 0xbf3a00e3
	s_cmp_gt_i32 s3, 3
	v_mov_b64_e32 v[176:177], s[4:5]
	s_cselect_b64 s[4:5], -1, 0
	s_and_b64 s[46:47], s[40:41], s[4:5]
	s_mov_b32 s4, 0x3f07dc22
	s_mov_b32 s38, 0x3f35f0e3
	s_mov_b32 s48, 0xbe11a98e
	s_mov_b32 s62, 0x3e027906
	s_lshl_b32 s3, s3, 2
	s_and_b32 s36, s3, 12
	s_mov_b32 s3, 0x1020000
	v_add_u32_e32 v170, s37, v1
	v_lshlrev_b32_e32 v1, 10, v170
	s_waitcnt lgkmcnt(0)
	v_xor_b32_e32 v65, 0x80000000, v65
	v_xor_b32_e32 v64, 0x80000000, v64
	v_pk_fma_f32 v[158:159], v[62:63], v[188:189], v[158:159] op_sel_hi:[1,0,1] neg_lo:[1,0,0] neg_hi:[1,0,0]
	v_xor_b32_e32 v53, 0x80000000, v53
	v_xor_b32_e32 v52, 0x80000000, v52
	v_pk_fma_f32 v[154:155], v[50:51], v[188:189], v[154:155] op_sel_hi:[1,0,1] neg_lo:[1,0,0] neg_hi:[1,0,0]
	v_pk_fma_f32 v[160:161], v[64:65], v[188:189], v[160:161] op_sel_hi:[1,0,1]
	v_pk_fma_f32 v[158:159], v[188:189], v[158:159], v[66:67] op_sel:[1,0,0]
	v_pk_fma_f32 v[172:173], v[52:53], v[188:189], v[156:157] op_sel_hi:[1,0,1]
	v_pk_fma_f32 v[156:157], v[188:189], v[154:155], v[42:43] op_sel:[1,0,0]
	v_pk_fma_f32 v[154:155], v[188:189], v[160:161], v[68:69] op_sel:[1,0,0]
	v_fma_f32 v175, |v159|, s1, 1.0
	v_fma_f32 v171, |v158|, s1, 1.0
	v_pk_fma_f32 v[160:161], v[188:189], v[172:173], v[44:45] op_sel:[1,0,0]
	v_fma_f32 v172, |v156|, s1, 1.0
	v_rcp_f32_e32 v175, v175
	v_fma_f32 v187, |v155|, s1, 1.0
	v_mul_f32_e32 v174, v158, v158
	v_rcp_f32_e32 v182, v171
	v_rcp_f32_e32 v183, v172
	v_rcp_f32_e32 v215, v187
	v_mul_f32_e32 v173, v156, v156
	v_fma_f32 v179, |v157|, s1, 1.0
	v_mul_f32_e32 v180, v157, v157
	v_mul_f32_e32 v171, 0xbf38aa3b, v174
	v_mul_f32_e32 v186, v154, v154
	v_fma_f32 v181, |v154|, s1, 1.0
	v_mul_f32_e32 v172, 0xbf38aa3b, v173
	v_rcp_f32_e32 v185, v179
	v_mul_f32_e32 v173, 0xbf38aa3b, v180
	v_fma_f32 v179, |v160|, s1, 1.0
	v_mul_f32_e32 v209, v160, v160
	v_exp_f32_e32 v180, v171
	v_mul_f32_e32 v171, 0xbf38aa3b, v186
	v_fma_f32 v211, |v161|, s1, 1.0
	v_rcp_f32_e32 v184, v181
	v_exp_f32_e32 v181, v172
	v_rcp_f32_e32 v210, v179
	v_mul_f32_e32 v179, 0xbf38aa3b, v209
	v_exp_f32_e32 v172, v171
	v_fmamk_f32 v171, v175, 0x3f07dc22, v218
	v_rcp_f32_e32 v211, v211
	v_exp_f32_e32 v214, v179
	v_pk_fma_f32 v[186:187], v[182:183], s[4:5], v[176:177] op_sel_hi:[1,0,0]
	v_fmaak_f32 v171, v175, v171, 0x3f35f0e3
	v_fmamk_f32 v179, v215, 0x3f07dc22, v218
	v_pk_fma_f32 v[186:187], v[182:183], v[186:187], s[38:39] op_sel_hi:[1,1,0]
	v_fmaak_f32 v171, v175, v171, 0xbe11a98e
	v_fmaak_f32 v179, v215, v179, 0x3f35f0e3
	v_pk_fma_f32 v[186:187], v[182:183], v[186:187], s[48:49] op_sel_hi:[1,1,0]
	v_fmaak_f32 v171, v175, v171, 0x3e027906
	v_fmaak_f32 v179, v215, v179, 0xbe11a98e
	v_mul_f32_e32 v212, v161, v161
	v_pk_fma_f32 v[224:225], v[182:183], v[186:187], s[62:63] op_sel_hi:[1,1,0]
	v_mul_f32_e32 v186, v175, v171
	v_fmaak_f32 v171, v215, v179, 0x3e027906
	v_pk_fma_f32 v[222:223], v[184:185], s[4:5], v[176:177] op_sel_hi:[1,0,0]
	v_pk_mul_f32 v[224:225], v[182:183], v[224:225]
	v_mul_f32_e32 v182, v215, v171
	v_mul_f32_e32 v171, 0xbf38aa3b, v212
	v_pk_fma_f32 v[176:177], v[210:211], s[4:5], v[176:177] op_sel_hi:[1,0,0]
	v_exp_f32_e32 v215, v171
	v_pk_fma_f32 v[176:177], v[210:211], v[176:177], s[38:39] op_sel_hi:[1,1,0]
	v_cmp_gt_f32_e32 vcc, 0, v161
	v_pk_fma_f32 v[176:177], v[210:211], v[176:177], s[48:49] op_sel_hi:[1,1,0]
	v_pk_fma_f32 v[150:151], v[58:59], v[188:189], v[150:151] op_sel_hi:[1,0,1] neg_lo:[1,0,0] neg_hi:[1,0,0]
	v_pk_fma_f32 v[176:177], v[210:211], v[176:177], s[62:63] op_sel_hi:[1,1,0]
	v_pk_fma_f32 v[150:151], v[188:189], v[150:151], v[46:47] op_sel:[1,0,0]
	v_pk_mul_f32 v[176:177], v[210:211], v[176:177]
	v_fma_f32 v175, |v150|, s1, 1.0
	v_pk_mul_f32 v[176:177], v[214:215], v[176:177]
	v_rcp_f32_e32 v175, v175
	v_pk_mul_f32 v[210:211], v[160:161], v[176:177]
	v_pk_fma_f32 v[176:177], v[160:161], v[176:177], v[160:161] neg_lo:[1,0,0] neg_hi:[1,0,0]
	v_mul_f32_e32 v178, v159, v159
	v_cndmask_b32_e32 v177, v177, v211, vcc
	v_cmp_gt_f32_e32 vcc, 0, v160
	v_xor_b32_e32 v61, 0x80000000, v61
	v_xor_b32_e32 v60, 0x80000000, v60
	v_cndmask_b32_e32 v176, v176, v210, vcc
	v_mul_f32_e32 v160, v176, v176
	v_pk_fma_f32 v[160:161], v[176:177], v[176:177], v[160:161] op_sel_hi:[1,1,0]
	v_mul_f32_e32 v174, 0xbf38aa3b, v178
	v_lshrrev_b32_e32 v160, 10, v208
	v_mul_f32_e32 v207, v155, v155
	v_mul_lo_u32 v160, v160, s3
	s_movk_i32 s4, 0x3ff
	v_pk_fma_f32 v[152:153], v[60:61], v[188:189], v[152:153] op_sel_hi:[1,0,1]
	v_exp_f32_e32 v178, v174
	v_mul_f32_e32 v174, 0xbf38aa3b, v207
	v_and_or_b32 v207, v208, s4, v160
	v_add_u32_e32 v171, 0x80, v208
	v_pk_fma_f32 v[208:209], v[188:189], v[152:153], v[48:49] op_sel:[1,0,0]
	v_fmamk_f32 v152, v175, 0x3f07dc22, v218
	v_fmaak_f32 v152, v175, v152, 0x3f35f0e3
	v_mul_f32_e32 v153, v150, v150
	v_mul_f32_e32 v153, 0xbf38aa3b, v153
	v_fmaak_f32 v152, v175, v152, 0xbe11a98e
	v_exp_f32_e32 v153, v153
	v_fmaak_f32 v152, v175, v152, 0x3e027906
	v_mul_f32_e32 v152, v175, v152
	v_fma_f32 v175, |v151|, s1, 1.0
	v_rcp_f32_e32 v175, v175
	v_mul_f32_e32 v152, v153, v152
	v_mul_f32_e32 v153, v150, v152
	v_fma_f32 v152, -v150, v152, v150
	v_cmp_gt_f32_e32 vcc, 0, v150
	v_pk_fma_f32 v[146:147], v[38:39], v[188:189], v[146:147] op_sel_hi:[1,0,1] neg_lo:[1,0,0] neg_hi:[1,0,0]
	v_xor_b32_e32 v41, 0x80000000, v41
	v_cndmask_b32_e32 v150, v152, v153, vcc
	v_fmamk_f32 v152, v175, 0x3f07dc22, v218
	v_fmaak_f32 v152, v175, v152, 0x3f35f0e3
	v_mul_f32_e32 v153, v151, v151
	v_fmaak_f32 v152, v175, v152, 0xbe11a98e
	v_mul_f32_e32 v153, 0xbf38aa3b, v153
	v_fmaak_f32 v152, v175, v152, 0x3e027906
	v_exp_f32_e32 v153, v153
	v_mul_f32_e32 v152, v175, v152
	v_fma_f32 v175, |v208|, s1, 1.0
	v_rcp_f32_e32 v175, v175
	v_mul_f32_e32 v152, v153, v152
	v_mul_f32_e32 v153, v151, v152
	v_fma_f32 v152, -v151, v152, v151
	v_cmp_gt_f32_e32 vcc, 0, v151
	v_fmamk_f32 v151, v175, 0x3f07dc22, v218
	v_fmaak_f32 v151, v175, v151, 0x3f35f0e3
	v_cndmask_b32_e32 v152, v152, v153, vcc
	v_mul_f32_e32 v153, v208, v208
	v_mul_f32_e32 v153, 0xbf38aa3b, v153
	v_fmaak_f32 v151, v175, v151, 0xbe11a98e
	v_exp_f32_e32 v153, v153
	v_fmaak_f32 v151, v175, v151, 0x3e027906
	v_mul_f32_e32 v151, v175, v151
	v_fma_f32 v175, |v209|, s1, 1.0
	v_rcp_f32_e32 v175, v175
	v_mul_f32_e32 v151, v153, v151
	v_mul_f32_e32 v153, v208, v151
	v_fma_f32 v151, -v208, v151, v208
	v_cmp_gt_f32_e32 vcc, 0, v208
	v_pk_fma_f32 v[146:147], v[188:189], v[146:147], v[34:35] op_sel:[1,0,0]
	v_xor_b32_e32 v40, 0x80000000, v40
	v_cndmask_b32_e32 v208, v151, v153, vcc
	v_fmamk_f32 v151, v175, 0x3f07dc22, v218
	v_fmaak_f32 v151, v175, v151, 0x3f35f0e3
	v_fmaak_f32 v151, v175, v151, 0xbe11a98e
	v_fmaak_f32 v151, v175, v151, 0x3e027906
	v_mul_f32_e32 v151, v175, v151
	v_fma_f32 v175, |v146|, s1, 1.0
	v_rcp_f32_e32 v175, v175
	v_mul_f32_e32 v183, v146, v146
	v_mul_f32_e32 v153, v209, v209
	v_mul_f32_e32 v183, 0xbf38aa3b, v183
	v_fmamk_f32 v179, v175, 0x3f07dc22, v218
	v_mul_f32_e32 v153, 0xbf38aa3b, v153
	v_fmaak_f32 v179, v175, v179, 0x3f35f0e3
	v_exp_f32_e32 v183, v183
	v_exp_f32_e32 v153, v153
	v_fmaak_f32 v179, v175, v179, 0xbe11a98e
	v_fmaak_f32 v179, v175, v179, 0x3e027906
	v_mul_f32_e32 v175, v175, v179
	v_mul_f32_e32 v175, v183, v175
	v_fma_f32 v183, |v147|, s1, 1.0
	v_mul_f32_e32 v151, v153, v151
	v_rcp_f32_e32 v183, v183
	v_mul_f32_e32 v153, v209, v151
	v_fma_f32 v151, -v209, v151, v209
	v_cmp_gt_f32_e32 vcc, 0, v209
	v_mul_f32_e32 v179, v146, v175
	v_fma_f32 v175, -v146, v175, v146
	v_cndmask_b32_e32 v210, v151, v153, vcc
	v_cmp_gt_f32_e32 vcc, 0, v146
	v_pk_fma_f32 v[148:149], v[40:41], v[188:189], v[148:149] op_sel_hi:[1,0,1]
	v_fmamk_f32 v146, v183, 0x3f07dc22, v218
	v_cndmask_b32_e32 v214, v175, v179, vcc
	v_mul_f32_e32 v175, v147, v147
	v_mul_f32_e32 v175, 0xbf38aa3b, v175
	v_pk_fma_f32 v[148:149], v[188:189], v[148:149], v[36:37] op_sel:[1,0,0]
	v_fmaak_f32 v146, v183, v146, 0x3f35f0e3
	v_exp_f32_e32 v175, v175
	v_fmaak_f32 v146, v183, v146, 0xbe11a98e
	v_fma_f32 v179, |v148|, s1, 1.0
	v_fmaak_f32 v146, v183, v146, 0x3e027906
	v_rcp_f32_e32 v179, v179
	v_pk_fma_f32 v[222:223], v[184:185], v[222:223], s[38:39] op_sel_hi:[1,1,0]
	v_mul_f32_e32 v146, v183, v146
	v_pk_fma_f32 v[222:223], v[184:185], v[222:223], s[48:49] op_sel_hi:[1,1,0]
	v_mul_f32_e32 v146, v175, v146
	v_pk_fma_f32 v[222:223], v[184:185], v[222:223], s[62:63] op_sel_hi:[1,1,0]
	v_mul_f32_e32 v175, v147, v146
	v_fma_f32 v146, -v147, v146, v147
	v_cmp_gt_f32_e32 vcc, 0, v147
	v_mul_f32_e32 v147, v148, v148
	v_pk_mul_f32 v[184:185], v[184:185], v[222:223]
	v_cndmask_b32_e32 v222, v146, v175, vcc
	v_fmamk_f32 v146, v179, 0x3f07dc22, v218
	v_mul_f32_e32 v147, 0xbf38aa3b, v147
	v_fmaak_f32 v146, v179, v146, 0x3f35f0e3
	v_exp_f32_e32 v147, v147
	v_fmaak_f32 v146, v179, v146, 0xbe11a98e
	v_fmaak_f32 v146, v179, v146, 0x3e027906
	v_fma_f32 v175, |v149|, s1, 1.0
	v_mul_f32_e32 v146, v179, v146
	v_rcp_f32_e32 v175, v175
	v_mul_f32_e32 v146, v147, v146
	v_mul_f32_e32 v147, v148, v146
	v_fma_f32 v146, -v148, v146, v148
	v_cmp_gt_f32_e32 vcc, 0, v148
	v_exp_f32_e32 v173, v173
	v_exp_f32_e32 v174, v174
	v_cndmask_b32_e32 v226, v146, v147, vcc
	v_mul_f32_e32 v147, v149, v149
	v_fmamk_f32 v146, v175, 0x3f07dc22, v218
	v_mul_f32_e32 v147, 0xbf38aa3b, v147
	v_fmaak_f32 v146, v175, v146, 0x3f35f0e3
	v_exp_f32_e32 v147, v147
	v_fmaak_f32 v146, v175, v146, 0xbe11a98e
	v_fmaak_f32 v146, v175, v146, 0x3e027906
	v_mul_f32_e32 v146, v175, v146
	v_mul_f32_e32 v146, v147, v146
	v_mul_f32_e32 v147, v149, v146
	v_fma_f32 v146, -v149, v146, v149
	v_cmp_gt_f32_e32 vcc, 0, v149
	v_mov_b32_e32 v179, v181
	v_mov_b32_e32 v187, v225
	v_cndmask_b32_e32 v228, v146, v147, vcc
	v_lshrrev_b32_e32 v146, 10, v171
	v_mul_lo_u32 v146, v146, s3
	v_and_or_b32 v188, v171, s4, v146
	v_pk_mul_f32 v[146:147], v[180:181], v[224:225]
	v_pk_mul_f32 v[148:149], v[178:179], v[186:187]
	v_mov_b32_e32 v178, v158
	v_mov_b32_e32 v179, v156
	v_pk_mov_b32 v[186:187], v[158:159], v[156:157] op_sel:[1,0]
	v_pk_mul_f32 v[180:181], v[178:179], v[146:147]
	v_pk_mul_f32 v[224:225], v[186:187], v[148:149]
	v_pk_fma_f32 v[146:147], v[178:179], v[146:147], v[178:179] neg_lo:[1,0,0] neg_hi:[1,0,0]
	v_pk_fma_f32 v[148:149], v[186:187], v[148:149], v[186:187] neg_lo:[1,0,0] neg_hi:[1,0,0]
	v_cmp_gt_f32_e32 vcc, 0, v156
	v_cmp_gt_f32_e64 s[4:5], 0, v158
	v_mov_b32_e32 v175, v173
	v_cndmask_b32_e32 v179, v147, v181, vcc
	v_cndmask_b32_e32 v181, v149, v225, vcc
	v_cmp_gt_f32_e32 vcc, 0, v159
	v_mov_b32_e32 v183, v185
	v_cndmask_b32_e64 v178, v146, v180, s[4:5]
	v_cndmask_b32_e32 v180, v148, v224, vcc
	v_pk_mul_f32 v[148:149], v[172:173], v[184:185]
	v_pk_mul_f32 v[158:159], v[174:175], v[182:183]
	v_mov_b32_e32 v156, v154
	v_mov_b32_e32 v174, v155
	v_mov_b32_e32 v175, v157
	v_pk_mul_f32 v[172:173], v[156:157], v[148:149]
	v_pk_mul_f32 v[182:183], v[174:175], v[158:159]
	v_pk_fma_f32 v[148:149], v[156:157], v[148:149], v[156:157] neg_lo:[1,0,0] neg_hi:[1,0,0]
	v_pk_fma_f32 v[158:159], v[174:175], v[158:159], v[174:175] neg_lo:[1,0,0] neg_hi:[1,0,0]
	v_cmp_gt_f32_e32 vcc, 0, v157
	v_cmp_gt_f32_e64 s[4:5], 0, v154
	v_add_lshl_u32 v160, v1, v207, 1
	v_cndmask_b32_e32 v157, v149, v173, vcc
	v_cndmask_b32_e64 v156, v148, v172, s[4:5]
	v_cndmask_b32_e32 v159, v159, v183, vcc
	v_cmp_gt_f32_e32 vcc, 0, v155
	v_pk_mul_f32 v[174:175], v[156:157], v[156:157]
	v_mul_f32_e32 v151, v150, v150
	v_cndmask_b32_e32 v158, v158, v182, vcc
	v_mul_f32_e32 v153, v152, v152
	v_mul_f32_e32 v209, v208, v208
	v_mul_f32_e32 v211, v210, v210
	v_mul_f32_e32 v215, v214, v214
	v_mul_f32_e32 v223, v222, v222
	v_mul_f32_e32 v227, v226, v226
	v_mul_f32_e32 v229, v228, v228
	v_add_lshl_u32 v171, v1, v188, 1
	v_cvt_pk_bf16_f32 v146, v178, v180
	v_cvt_pk_bf16_f32 v147, v156, v158
	v_pk_mul_f32 v[154:155], v[178:179], v[178:179]
	v_pk_mul_f32 v[172:173], v[180:181], v[180:181]
	v_pk_mul_f32 v[182:183], v[158:159], v[158:159]
	v_pk_mov_b32 v[154:155], v[178:179], v[154:155] op_sel:[1,0]
	v_pk_mov_b32 v[172:173], v[156:157], v[172:173] op_sel:[1,0]
	v_cvt_pk_bf16_f32 v148, v179, v157
	v_mov_b32_e32 v1, v161
	v_pk_add_f32 v[154:155], v[154:155], v[172:173]
	v_mov_b32_e32 v172, v176
	v_mov_b32_e32 v173, v174
	v_pk_mov_b32 v[174:175], v[176:177], v[182:183] op_sel:[1,0]
	v_cvt_pk_bf16_f32 v149, v176, v177
	buffer_store_dwordx4 v[146:149], v160, s[28:31], 0 offen sc1
	v_pk_add_f32 v[172:173], v[172:173], v[174:175]
	v_pk_mul_f32 v[174:175], v[178:179], v[180:181]
	v_pk_add_f32 v[154:155], v[154:155], v[172:173]
	v_pk_add_f32 v[172:173], v[178:179], v[180:181]
	s_nop 0
	v_mov_b32_e32 v173, v175
	v_pk_add_f32 v[174:175], v[156:157], v[158:159]
	v_pk_mul_f32 v[156:157], v[156:157], v[158:159]
	s_nop 0
	v_mov_b32_e32 v175, v157
	v_pk_add_f32 v[156:157], v[172:173], v[174:175]
	s_nop 0
	v_pk_add_f32 v[156:157], v[156:157], v[0:1]
	s_nop 0
	v_pk_add_f32 v[154:155], v[154:155], v[156:157]
	v_cvt_pk_bf16_f32 v146, v150, v152
	v_pk_add_f32 v[148:149], v[150:151], v[152:153]
	v_pk_add_f32 v[150:151], v[208:209], v[210:211]
	v_cvt_pk_bf16_f32 v147, v208, v210
	s_nop 0
	v_pk_add_f32 v[148:149], v[148:149], v[150:151]
	s_nop 0
	v_pk_add_f32 v[150:151], v[148:149], v[154:155]
	v_pk_add_f32 v[152:153], v[214:215], v[222:223]
	v_pk_add_f32 v[154:155], v[226:227], v[228:229]
	v_cvt_pk_bf16_f32 v148, v214, v222
	v_cvt_pk_bf16_f32 v149, v226, v228
	buffer_store_dwordx4 v[146:149], v171, s[28:31], 0 offen sc1
	v_pk_add_f32 v[152:153], v[152:153], v[154:155]
	s_nop 0
	v_pk_add_f32 v[150:151], v[152:153], v[150:151]
	v_and_b32_e32 v146, 64, v216
	v_xor_b32_e32 v1, 16, v216
	v_add_u32_e32 v148, 64, v146
	v_cmp_lt_i32_e32 vcc, v1, v148
	s_nop 1
	v_cndmask_b32_e32 v1, v216, v1, vcc
	v_lshlrev_b32_e32 v174, 2, v1
	ds_bpermute_b32 v146, v174, v150
	ds_bpermute_b32 v147, v174, v151
	v_xor_b32_e32 v1, 32, v216
	v_cmp_lt_i32_e32 vcc, v1, v148
	s_waitcnt lgkmcnt(0)
	v_pk_add_f32 v[146:147], v[150:151], v[146:147]
	v_cndmask_b32_e32 v1, v216, v1, vcc
	v_lshlrev_b32_e32 v175, 2, v1
	ds_bpermute_b32 v148, v175, v146
	ds_bpermute_b32 v149, v175, v147
	s_and_saveexec_b64 s[4:5], s[46:47]
	s_cbranch_execz .LBB0_215
	v_ashrrev_i32_e32 v171, 31, v170
	v_lshlrev_b64 v[150:151], 7, v[170:171]
	v_lshl_add_u64 v[150:151], s[12:13], 0, v[150:151]
	s_lshl_b32 s38, s36, 3
	v_lshl_add_u64 v[150:151], v[150:151], 0, s[38:39]
	s_lshl_b32 s38, s57, 3
	v_lshl_add_u64 v[150:151], v[150:151], 0, s[38:39]
	s_waitcnt lgkmcnt(0)
	v_pk_add_f32 v[146:147], v[146:147], v[148:149]
	flat_store_dwordx2 v[150:151], v[146:147]

.LBB0_394:
	s_or_b64 exec, exec, s[4:5]
	v_add_lshl_u32 v2, v46, v138, 1
	v_cvt_pk_bf16_f32 v8, v8, v9
	v_cvt_pk_bf16_f32 v9, v10, v11
	buffer_store_dwordx4 v[6:9], v2, s[28:31], 0 offen sc1
	s_and_b64 vcc, exec, s[52:53]
	s_cbranch_vccnz .LBB0_813
	s_add_i32 s66, s66, 1
	s_mov_b64 s[36:37], s[20:21]
	s_mul_i32 s20, s66, s26
	s_add_i32 s42, s20, s2
	s_cmpk_gt_i32 s42, 0x3ff
	s_cselect_b64 s[52:53], -1, 0
	s_lshl_b32 s20, s42, 3
	s_and_b32 s20, s20, 56
	s_bfe_u32 s21, s42, 0x30003
	s_mov_b32 s3, s67
	s_or_b32 s67, s20, s21
	s_mov_b32 s27, s50
	s_ashr_i32 s50, s42, 6
	s_lshl_b32 s20, s67, 19
	s_mov_b64 s[4:5], s[48:49]
	s_add_u32 s48, s18, s20
	s_addc_u32 s49, s19, 0
	s_ashr_i32 s51, s50, 31
	s_lshl_b64 s[20:21], s[50:51], 19
	s_add_u32 s20, s16, s20
	s_addc_u32 s21, s17, s21
	s_cmpk_lt_i32 s42, 0x400
	s_cselect_b32 s46, s49, s5
	s_cselect_b32 s47, s48, s4
	s_cselect_b32 s51, s21, s37
	s_cselect_b32 s54, s20, s36
	s_add_u32 s55, s36, 0x100
	s_addc_u32 s56, s37, 0
	s_mov_b32 s57, -2
	s_add_u32 s36, s4, 0x100
	s_addc_u32 s37, s5, 0
	s_add_i32 s68, 0, 0x10000
	v_add_u32_e32 v30, s68, v204
	ds_read_b128 v[14:17], v30
	ds_read_b128 v[22:25], v30 offset:1024
	ds_read_b128 v[26:29], v30 offset:2048
	ds_read_b128 v[30:33], v30 offset:3072
	s_cmp_eq_u32 s57, 12
	s_cselect_b32 s45, s46, s37
	s_cselect_b32 s44, s47, s36
	s_cselect_b32 s43, s51, s56
	s_cselect_b32 s42, s54, s55
	v_lshl_add_u64 v[178:179], s[4:5], 0, v[188:189]
	s_add_i32 m0, s60, 0xc000
	ds_read_b128 v[38:41], v209
	ds_read_b128 v[42:45], v209 offset:1024
	ds_read_b128 v[46:49], v209 offset:2048
	ds_read_b128 v[54:57], v209 offset:3072
	ds_read_b128 v[58:61], v209 offset:4096
	ds_read_b128 v[62:65], v209 offset:5120
	ds_read_b128 v[66:69], v209 offset:6144
	ds_read_b128 v[70:73], v209 offset:7168
	v_lshl_add_u64 v[178:179], s[4:5], 0, v[186:187]
	s_add_i32 m0, s60, 0xe000
	s_nop 0
	s_waitcnt lgkmcnt(8)
	s_barrier
	s_waitcnt lgkmcnt(0)
	s_setprio 1
	s_waitcnt lgkmcnt(0)
	v_mfma_f32_16x16x32_bf16 v[174:177], v[14:17], v[38:41], 0
	v_mfma_f32_16x16x32_bf16 v[170:173], v[26:29], v[38:41], 0
	v_mfma_f32_16x16x32_bf16 v[158:161], v[14:17], v[46:49], 0
	v_mfma_f32_16x16x32_bf16 v[154:157], v[26:29], v[46:49], 0
	v_mfma_f32_16x16x32_bf16 v[142:145], v[14:17], v[58:61], 0
	v_mfma_f32_16x16x32_bf16 v[138:141], v[26:29], v[58:61], 0
	v_mfma_f32_16x16x32_bf16 v[126:129], v[14:17], v[66:69], 0
	v_mfma_f32_16x16x32_bf16 v[122:125], v[26:29], v[66:69], 0
	v_mfma_f32_16x16x32_bf16 v[174:177], v[22:25], v[42:45], v[174:177]
	v_mfma_f32_16x16x32_bf16 v[170:173], v[30:33], v[42:45], v[170:173]
	v_mfma_f32_16x16x32_bf16 v[158:161], v[22:25], v[54:57], v[158:161]
	v_mfma_f32_16x16x32_bf16 v[154:157], v[30:33], v[54:57], v[154:157]
	v_mfma_f32_16x16x32_bf16 v[142:145], v[22:25], v[62:65], v[142:145]
	v_mfma_f32_16x16x32_bf16 v[138:141], v[30:33], v[62:65], v[138:141]
	v_mfma_f32_16x16x32_bf16 v[126:129], v[22:25], v[70:73], v[126:129]
	v_mfma_f32_16x16x32_bf16 v[122:125], v[30:33], v[70:73], v[122:125]
	s_setprio 0
	s_barrier
	s_add_i32 s69, 0, 0x14000
	v_add_u32_e32 v210, s69, v204
	s_add_i32 s4, s68, s59
	ds_read_b128 v[178:181], v210
	ds_read_b128 v[190:193], v210 offset:1024
	ds_read_b128 v[200:203], v210 offset:2048
	ds_read_b128 v[222:225], v210 offset:3072
	v_lshl_add_u64 v[210:211], s[42:43], 0, v[184:185]
	s_mov_b32 m0, s4
	v_lshl_add_u64 v[214:215], s[42:43], 0, v[182:183]
	global_load_lds_dwordx4 v[210:211], off
	s_add_i32 m0, s4, 0x2000
	s_nop 0
	global_load_lds_dwordx4 v[214:215], off
	s_barrier
	s_waitcnt lgkmcnt(0)
	s_setprio 1
	s_waitcnt lgkmcnt(0)
	v_mfma_f32_16x16x32_bf16 v[166:169], v[178:181], v[38:41], 0
	v_mfma_f32_16x16x32_bf16 v[38:41], v[200:203], v[38:41], 0
	v_mfma_f32_16x16x32_bf16 v[166:169], v[190:193], v[42:45], v[166:169]
	v_mfma_f32_16x16x32_bf16 v[38:41], v[222:225], v[42:45], v[38:41]
	v_mfma_f32_16x16x32_bf16 v[42:45], v[178:181], v[46:49], 0
	v_mfma_f32_16x16x32_bf16 v[46:49], v[200:203], v[46:49], 0
	v_mfma_f32_16x16x32_bf16 v[42:45], v[190:193], v[54:57], v[42:45]
	v_mfma_f32_16x16x32_bf16 v[46:49], v[222:225], v[54:57], v[46:49]
	v_mfma_f32_16x16x32_bf16 v[54:57], v[178:181], v[58:61], 0
	v_mfma_f32_16x16x32_bf16 v[58:61], v[200:203], v[58:61], 0
	v_mfma_f32_16x16x32_bf16 v[54:57], v[190:193], v[62:65], v[54:57]
	v_mfma_f32_16x16x32_bf16 v[58:61], v[222:225], v[62:65], v[58:61]
	v_mfma_f32_16x16x32_bf16 v[62:65], v[178:181], v[66:69], 0
	v_mfma_f32_16x16x32_bf16 v[66:69], v[200:203], v[66:69], 0
	v_mfma_f32_16x16x32_bf16 v[62:65], v[190:193], v[70:73], v[62:65]
	v_mfma_f32_16x16x32_bf16 v[66:69], v[222:225], v[70:73], v[66:69]
	s_setprio 0
	s_mov_b32 m0, s60
	v_lshl_add_u64 v[242:243], s[44:45], 0, v[184:185]
	s_barrier
	ds_read_b128 v[70:73], v209 offset:16384
	ds_read_b128 v[114:117], v209 offset:17408
	ds_read_b128 v[118:121], v209 offset:18432
	ds_read_b128 v[130:133], v209 offset:19456
	ds_read_b128 v[134:137], v209 offset:20480
	ds_read_b128 v[146:149], v209 offset:21504
	ds_read_b128 v[150:153], v209 offset:22528
	ds_read_b128 v[162:165], v209 offset:23552
	global_load_lds_dwordx4 v[242:243], off
	v_lshl_add_u64 v[244:245], s[44:45], 0, v[182:183]
	s_mov_b32 m0, s61
	s_nop 0
	global_load_lds_dwordx4 v[244:245], off
	s_barrier
	s_waitcnt lgkmcnt(0)
	s_setprio 1
	s_waitcnt lgkmcnt(0)
	v_mfma_f32_16x16x32_bf16 v[110:113], v[14:17], v[70:73], 0
	v_mfma_f32_16x16x32_bf16 v[106:109], v[26:29], v[70:73], 0
	v_mfma_f32_16x16x32_bf16 v[94:97], v[14:17], v[118:121], 0
	v_mfma_f32_16x16x32_bf16 v[90:93], v[26:29], v[118:121], 0
	v_mfma_f32_16x16x32_bf16 v[78:81], v[14:17], v[134:137], 0
	v_mfma_f32_16x16x32_bf16 v[74:77], v[26:29], v[134:137], 0
	v_mfma_f32_16x16x32_bf16 v[10:13], v[26:29], v[150:153], 0
	v_mfma_f32_16x16x32_bf16 v[110:113], v[22:25], v[114:117], v[110:113]
	v_mfma_f32_16x16x32_bf16 v[106:109], v[30:33], v[114:117], v[106:109]
	v_mfma_f32_16x16x32_bf16 v[94:97], v[22:25], v[130:133], v[94:97]
	v_mfma_f32_16x16x32_bf16 v[90:93], v[30:33], v[130:133], v[90:93]
	v_mfma_f32_16x16x32_bf16 v[78:81], v[22:25], v[146:149], v[78:81]
	v_mfma_f32_16x16x32_bf16 v[74:77], v[30:33], v[146:149], v[74:77]
	v_mfma_f32_16x16x32_bf16 v[14:17], v[14:17], v[150:153], 0
	v_mfma_f32_16x16x32_bf16 v[10:13], v[30:33], v[162:165], v[10:13]
	v_mfma_f32_16x16x32_bf16 v[14:17], v[22:25], v[162:165], v[14:17]
	s_setprio 0
	s_barrier
	s_add_u32 s4, s42, 0x40000
	s_addc_u32 s5, s43, 0
	s_add_i32 s68, s69, s59
	v_lshl_add_u64 v[18:19], s[4:5], 0, v[184:185]
	s_mov_b32 m0, s68
	s_nop 0
	global_load_lds_dwordx4 v[18:19], off
	v_lshl_add_u64 v[18:19], s[4:5], 0, v[182:183]
	s_add_i32 m0, s68, 0x2000
	s_nop 0
	global_load_lds_dwordx4 v[18:19], off
	s_barrier
	s_setprio 1
	v_mfma_f32_16x16x32_bf16 v[18:21], v[178:181], v[70:73], 0
	v_mfma_f32_16x16x32_bf16 v[22:25], v[190:193], v[114:117], v[18:21]
	v_mfma_f32_16x16x32_bf16 v[18:21], v[200:203], v[70:73], 0
	v_mfma_f32_16x16x32_bf16 v[26:29], v[222:225], v[114:117], v[18:21]
	v_mfma_f32_16x16x32_bf16 v[18:21], v[178:181], v[118:121], 0
	v_mfma_f32_16x16x32_bf16 v[30:33], v[190:193], v[130:133], v[18:21]
	v_mfma_f32_16x16x32_bf16 v[18:21], v[200:203], v[118:121], 0
	v_mfma_f32_16x16x32_bf16 v[70:73], v[222:225], v[130:133], v[18:21]
	v_mfma_f32_16x16x32_bf16 v[18:21], v[178:181], v[134:137], 0
	v_mfma_f32_16x16x32_bf16 v[50:53], v[190:193], v[146:149], v[18:21]
	v_mfma_f32_16x16x32_bf16 v[18:21], v[200:203], v[134:137], 0
	v_mfma_f32_16x16x32_bf16 v[6:9], v[178:181], v[150:153], 0
	v_mfma_f32_16x16x32_bf16 v[2:5], v[200:203], v[150:153], 0
	v_mfma_f32_16x16x32_bf16 v[34:37], v[222:225], v[146:149], v[18:21]
	v_mfma_f32_16x16x32_bf16 v[6:9], v[190:193], v[162:165], v[6:9]
	v_mfma_f32_16x16x32_bf16 v[2:5], v[222:225], v[162:165], v[2:5]
	s_setprio 0
	s_add_i32 s68, 0, 0x18000
	v_add_u32_e32 v98, s68, v204
	s_barrier
	ds_read_b128 v[18:21], v98
	ds_read_b128 v[82:85], v98 offset:1024
	ds_read_b128 v[86:89], v98 offset:2048
	ds_read_b128 v[98:101], v98 offset:3072
	s_add_u32 s4, s44, 0x40000
	s_addc_u32 s5, s45, 0
	s_mov_b32 m0, s62
	v_lshl_add_u64 v[134:135], s[4:5], 0, v[184:185]
	ds_read_b128 v[102:105], v209 offset:32768
	ds_read_b128 v[114:117], v209 offset:33792
	ds_read_b128 v[118:121], v209 offset:34816
	ds_read_b128 v[130:133], v209 offset:35840
	ds_read_b128 v[178:181], v209 offset:36864
	ds_read_b128 v[190:193], v209 offset:37888
	ds_read_b128 v[200:203], v209 offset:38912
	ds_read_b128 v[222:225], v209 offset:39936
	global_load_lds_dwordx4 v[134:135], off
	v_lshl_add_u64 v[134:135], s[4:5], 0, v[182:183]
	s_mov_b32 m0, s63
	s_nop 0
	global_load_lds_dwordx4 v[134:135], off
	s_waitcnt lgkmcnt(8)
	s_barrier
	s_waitcnt lgkmcnt(0)
	s_setprio 1
	s_waitcnt lgkmcnt(0)
	v_mfma_f32_16x16x32_bf16 v[134:137], v[18:21], v[102:105], v[174:177]
	v_mfma_f32_16x16x32_bf16 v[174:177], v[82:85], v[114:117], v[134:137]
	v_mfma_f32_16x16x32_bf16 v[134:137], v[86:89], v[102:105], v[170:173]
	v_mfma_f32_16x16x32_bf16 v[170:173], v[98:101], v[114:117], v[134:137]
	v_mfma_f32_16x16x32_bf16 v[134:137], v[18:21], v[118:121], v[158:161]
	v_mfma_f32_16x16x32_bf16 v[158:161], v[82:85], v[130:133], v[134:137]
	v_mfma_f32_16x16x32_bf16 v[134:137], v[86:89], v[118:121], v[154:157]
	v_mfma_f32_16x16x32_bf16 v[154:157], v[98:101], v[130:133], v[134:137]
	v_mfma_f32_16x16x32_bf16 v[134:137], v[18:21], v[178:181], v[142:145]
	v_mfma_f32_16x16x32_bf16 v[142:145], v[82:85], v[190:193], v[134:137]
	v_mfma_f32_16x16x32_bf16 v[134:137], v[86:89], v[178:181], v[138:141]
	v_mfma_f32_16x16x32_bf16 v[126:129], v[18:21], v[200:203], v[126:129]
	v_mfma_f32_16x16x32_bf16 v[122:125], v[86:89], v[200:203], v[122:125]
	v_mfma_f32_16x16x32_bf16 v[138:141], v[98:101], v[190:193], v[134:137]
	v_mfma_f32_16x16x32_bf16 v[126:129], v[82:85], v[222:225], v[126:129]
	v_mfma_f32_16x16x32_bf16 v[122:125], v[98:101], v[222:225], v[122:125]
	s_setprio 0
	s_barrier
	s_add_i32 s44, 0, 0x1c000
	v_add_u32_e32 v134, s44, v204
	s_add_i32 s4, s68, s59
	ds_read_b128 v[226:229], v134
	ds_read_b128 v[230:233], v134 offset:1024
	ds_read_b128 v[234:237], v134 offset:2048
	ds_read_b128 v[238:241], v134 offset:3072
	v_lshl_add_u64 v[134:135], v[210:211], 0, s[22:23]
	s_mov_b32 m0, s4
	s_nop 0
	global_load_lds_dwordx4 v[134:135], off
	v_lshl_add_u64 v[134:135], v[214:215], 0, s[22:23]
	s_add_i32 m0, s4, 0x2000
	s_nop 0
	global_load_lds_dwordx4 v[134:135], off
	s_barrier
	s_waitcnt lgkmcnt(0)
	s_setprio 1
	s_waitcnt lgkmcnt(0)
	v_mfma_f32_16x16x32_bf16 v[38:41], v[234:237], v[102:105], v[38:41]
	v_mfma_f32_16x16x32_bf16 v[162:165], v[238:241], v[114:117], v[38:41]
	v_mfma_f32_16x16x32_bf16 v[38:41], v[226:229], v[118:121], v[42:45]
	v_mfma_f32_16x16x32_bf16 v[150:153], v[230:233], v[130:133], v[38:41]
	v_mfma_f32_16x16x32_bf16 v[38:41], v[234:237], v[118:121], v[46:49]
	v_mfma_f32_16x16x32_bf16 v[134:137], v[226:229], v[102:105], v[166:169]
	v_mfma_f32_16x16x32_bf16 v[146:149], v[238:241], v[130:133], v[38:41]
	v_mfma_f32_16x16x32_bf16 v[38:41], v[226:229], v[178:181], v[54:57]
	v_mfma_f32_16x16x32_bf16 v[166:169], v[230:233], v[114:117], v[134:137]
	v_mfma_f32_16x16x32_bf16 v[134:137], v[230:233], v[190:193], v[38:41]
	v_mfma_f32_16x16x32_bf16 v[38:41], v[234:237], v[178:181], v[58:61]
	v_mfma_f32_16x16x32_bf16 v[130:133], v[238:241], v[190:193], v[38:41]
	v_mfma_f32_16x16x32_bf16 v[38:41], v[226:229], v[200:203], v[62:65]
	v_mfma_f32_16x16x32_bf16 v[118:121], v[230:233], v[222:225], v[38:41]
	v_mfma_f32_16x16x32_bf16 v[38:41], v[234:237], v[200:203], v[66:69]
	v_mfma_f32_16x16x32_bf16 v[114:117], v[238:241], v[222:225], v[38:41]
	s_setprio 0
	s_mov_b32 m0, s64
	v_lshl_add_u64 v[102:103], v[242:243], 0, s[22:23]
	s_barrier
	s_nop 2
	ds_read_b128 v[38:41], v209 offset:49152
	ds_read_b128 v[42:45], v209 offset:50176
	ds_read_b128 v[46:49], v209 offset:51200
	ds_read_b128 v[54:57], v209 offset:52224
	ds_read_b128 v[58:61], v209 offset:53248
	ds_read_b128 v[62:65], v209 offset:54272
	ds_read_b128 v[66:69], v209 offset:55296
	ds_read_b128 v[178:181], v209 offset:56320
	global_load_lds_dwordx4 v[102:103], off
	v_lshl_add_u64 v[102:103], v[244:245], 0, s[22:23]
	s_mov_b32 m0, s65
	s_nop 0
	global_load_lds_dwordx4 v[102:103], off
	s_barrier
	s_waitcnt lgkmcnt(0)
	s_setprio 1
	s_waitcnt lgkmcnt(0)
	v_mfma_f32_16x16x32_bf16 v[102:105], v[18:21], v[38:41], v[110:113]
	v_mfma_f32_16x16x32_bf16 v[110:113], v[82:85], v[42:45], v[102:105]
	v_mfma_f32_16x16x32_bf16 v[102:105], v[86:89], v[38:41], v[106:109]
	v_mfma_f32_16x16x32_bf16 v[94:97], v[18:21], v[46:49], v[94:97]
	v_mfma_f32_16x16x32_bf16 v[90:93], v[86:89], v[46:49], v[90:93]
	v_mfma_f32_16x16x32_bf16 v[78:81], v[18:21], v[58:61], v[78:81]
	v_mfma_f32_16x16x32_bf16 v[74:77], v[86:89], v[58:61], v[74:77]
	v_mfma_f32_16x16x32_bf16 v[14:17], v[18:21], v[66:69], v[14:17]
	v_mfma_f32_16x16x32_bf16 v[10:13], v[86:89], v[66:69], v[10:13]
	v_mfma_f32_16x16x32_bf16 v[106:109], v[98:101], v[42:45], v[102:105]
	v_mfma_f32_16x16x32_bf16 v[94:97], v[82:85], v[54:57], v[94:97]
	v_mfma_f32_16x16x32_bf16 v[90:93], v[98:101], v[54:57], v[90:93]
	v_mfma_f32_16x16x32_bf16 v[78:81], v[82:85], v[62:65], v[78:81]
	v_mfma_f32_16x16x32_bf16 v[74:77], v[98:101], v[62:65], v[74:77]
	v_mfma_f32_16x16x32_bf16 v[18:21], v[82:85], v[178:181], v[14:17]
	v_mfma_f32_16x16x32_bf16 v[10:13], v[98:101], v[178:181], v[10:13]
	s_setprio 0
	s_barrier
	s_add_u32 s4, s42, 0x40080
	s_addc_u32 s5, s43, 0
	s_add_i32 s42, s44, s59
	v_lshl_add_u64 v[14:15], s[4:5], 0, v[184:185]
	s_mov_b32 m0, s42
	s_nop 0
	global_load_lds_dwordx4 v[14:15], off
	v_lshl_add_u64 v[14:15], s[4:5], 0, v[182:183]
	s_add_i32 m0, s42, 0x2000
	s_nop 0
	global_load_lds_dwordx4 v[14:15], off
	s_waitcnt vmcnt(6)
	s_barrier
	s_setprio 1
	v_mfma_f32_16x16x32_bf16 v[14:17], v[226:229], v[38:41], v[22:25]
	v_mfma_f32_16x16x32_bf16 v[102:105], v[230:233], v[42:45], v[14:17]
	v_mfma_f32_16x16x32_bf16 v[14:17], v[234:237], v[38:41], v[26:29]
	v_mfma_f32_16x16x32_bf16 v[98:101], v[238:241], v[42:45], v[14:17]
	v_mfma_f32_16x16x32_bf16 v[14:17], v[226:229], v[46:49], v[30:33]
	v_mfma_f32_16x16x32_bf16 v[86:89], v[230:233], v[54:57], v[14:17]
	v_mfma_f32_16x16x32_bf16 v[14:17], v[234:237], v[46:49], v[70:73]
	v_mfma_f32_16x16x32_bf16 v[82:85], v[238:241], v[54:57], v[14:17]
	v_mfma_f32_16x16x32_bf16 v[14:17], v[226:229], v[58:61], v[50:53]
	v_mfma_f32_16x16x32_bf16 v[50:53], v[230:233], v[62:65], v[14:17]
	v_mfma_f32_16x16x32_bf16 v[14:17], v[234:237], v[58:61], v[34:37]
	v_mfma_f32_16x16x32_bf16 v[6:9], v[226:229], v[66:69], v[6:9]
	v_mfma_f32_16x16x32_bf16 v[2:5], v[234:237], v[66:69], v[2:5]
	v_mfma_f32_16x16x32_bf16 v[34:37], v[238:241], v[62:65], v[14:17]
	v_mfma_f32_16x16x32_bf16 v[6:9], v[230:233], v[178:181], v[6:9]
	v_mfma_f32_16x16x32_bf16 v[2:5], v[238:241], v[178:181], v[2:5]
	s_setprio 0
	s_add_i32 s57, s57, 2
	s_add_u32 s55, s55, 0x100
	s_addc_u32 s56, s56, 0
	s_cmp_gt_u32 s57, 13
	s_mov_b64 s[4:5], s[36:37]
	s_barrier
	s_branch .LBB0_396

.LBB0_396:
	s_add_u32 s36, s4, 0x100
	s_addc_u32 s37, s5, 0
	s_add_i32 s68, 0, 0x10000
	v_add_u32_e32 v30, s68, v204
	ds_read_b128 v[14:17], v30
	ds_read_b128 v[22:25], v30 offset:1024
	ds_read_b128 v[26:29], v30 offset:2048
	ds_read_b128 v[30:33], v30 offset:3072
	s_cmp_eq_u32 s57, 12
	s_cselect_b32 s45, s46, s37
	s_cselect_b32 s44, s47, s36
	s_cselect_b32 s43, s51, s56
	s_cselect_b32 s42, s54, s55
	v_lshl_add_u64 v[178:179], s[4:5], 0, v[188:189]
	s_add_i32 m0, s60, 0xc000
	ds_read_b128 v[38:41], v209
	ds_read_b128 v[42:45], v209 offset:1024
	ds_read_b128 v[46:49], v209 offset:2048
	ds_read_b128 v[54:57], v209 offset:3072
	ds_read_b128 v[58:61], v209 offset:4096
	ds_read_b128 v[62:65], v209 offset:5120
	ds_read_b128 v[66:69], v209 offset:6144
	ds_read_b128 v[70:73], v209 offset:7168
	global_load_lds_dwordx4 v[178:179], off
	v_lshl_add_u64 v[178:179], s[4:5], 0, v[186:187]
	s_add_i32 m0, s60, 0xe000
	s_nop 0
	global_load_lds_dwordx4 v[178:179], off
	s_waitcnt lgkmcnt(8)
	s_barrier
	s_waitcnt lgkmcnt(0)
	s_setprio 1
	s_waitcnt lgkmcnt(0)
	v_mfma_f32_16x16x32_bf16 v[174:177], v[14:17], v[38:41], v[174:177]
	v_mfma_f32_16x16x32_bf16 v[170:173], v[26:29], v[38:41], v[170:173]
	v_mfma_f32_16x16x32_bf16 v[158:161], v[14:17], v[46:49], v[158:161]
	v_mfma_f32_16x16x32_bf16 v[154:157], v[26:29], v[46:49], v[154:157]
	v_mfma_f32_16x16x32_bf16 v[142:145], v[14:17], v[58:61], v[142:145]
	v_mfma_f32_16x16x32_bf16 v[138:141], v[26:29], v[58:61], v[138:141]
	v_mfma_f32_16x16x32_bf16 v[126:129], v[14:17], v[66:69], v[126:129]
	v_mfma_f32_16x16x32_bf16 v[122:125], v[26:29], v[66:69], v[122:125]
	v_mfma_f32_16x16x32_bf16 v[174:177], v[22:25], v[42:45], v[174:177]
	v_mfma_f32_16x16x32_bf16 v[170:173], v[30:33], v[42:45], v[170:173]
	v_mfma_f32_16x16x32_bf16 v[158:161], v[22:25], v[54:57], v[158:161]
	v_mfma_f32_16x16x32_bf16 v[154:157], v[30:33], v[54:57], v[154:157]
	v_mfma_f32_16x16x32_bf16 v[142:145], v[22:25], v[62:65], v[142:145]
	v_mfma_f32_16x16x32_bf16 v[138:141], v[30:33], v[62:65], v[138:141]
	v_mfma_f32_16x16x32_bf16 v[126:129], v[22:25], v[70:73], v[126:129]
	v_mfma_f32_16x16x32_bf16 v[122:125], v[30:33], v[70:73], v[122:125]
	s_setprio 0
	s_barrier
	s_add_i32 s69, 0, 0x14000
	v_add_u32_e32 v210, s69, v204
	s_add_i32 s4, s68, s59
	ds_read_b128 v[178:181], v210
	ds_read_b128 v[190:193], v210 offset:1024
	ds_read_b128 v[200:203], v210 offset:2048
	ds_read_b128 v[222:225], v210 offset:3072
	v_lshl_add_u64 v[210:211], s[42:43], 0, v[184:185]
	s_mov_b32 m0, s4
	v_lshl_add_u64 v[214:215], s[42:43], 0, v[182:183]
	global_load_lds_dwordx4 v[210:211], off
	s_add_i32 m0, s4, 0x2000
	s_nop 0
	global_load_lds_dwordx4 v[214:215], off
	s_barrier
	s_waitcnt lgkmcnt(0)
	s_setprio 1
	s_waitcnt lgkmcnt(0)
	v_mfma_f32_16x16x32_bf16 v[166:169], v[178:181], v[38:41], v[166:169]
	v_mfma_f32_16x16x32_bf16 v[38:41], v[200:203], v[38:41], v[162:165]
	v_mfma_f32_16x16x32_bf16 v[166:169], v[190:193], v[42:45], v[166:169]
	v_mfma_f32_16x16x32_bf16 v[38:41], v[222:225], v[42:45], v[38:41]
	v_mfma_f32_16x16x32_bf16 v[42:45], v[178:181], v[46:49], v[150:153]
	v_mfma_f32_16x16x32_bf16 v[46:49], v[200:203], v[46:49], v[146:149]
	v_mfma_f32_16x16x32_bf16 v[42:45], v[190:193], v[54:57], v[42:45]
	v_mfma_f32_16x16x32_bf16 v[46:49], v[222:225], v[54:57], v[46:49]
	v_mfma_f32_16x16x32_bf16 v[54:57], v[178:181], v[58:61], v[134:137]
	v_mfma_f32_16x16x32_bf16 v[58:61], v[200:203], v[58:61], v[130:133]
	v_mfma_f32_16x16x32_bf16 v[54:57], v[190:193], v[62:65], v[54:57]
	v_mfma_f32_16x16x32_bf16 v[58:61], v[222:225], v[62:65], v[58:61]
	v_mfma_f32_16x16x32_bf16 v[62:65], v[178:181], v[66:69], v[118:121]
	v_mfma_f32_16x16x32_bf16 v[66:69], v[200:203], v[66:69], v[114:117]
	v_mfma_f32_16x16x32_bf16 v[62:65], v[190:193], v[70:73], v[62:65]
	v_mfma_f32_16x16x32_bf16 v[66:69], v[222:225], v[70:73], v[66:69]
	s_setprio 0
	s_mov_b32 m0, s60
	v_lshl_add_u64 v[242:243], s[44:45], 0, v[184:185]
	s_barrier
	ds_read_b128 v[70:73], v209 offset:16384
	ds_read_b128 v[114:117], v209 offset:17408
	ds_read_b128 v[118:121], v209 offset:18432
	ds_read_b128 v[130:133], v209 offset:19456
	ds_read_b128 v[134:137], v209 offset:20480
	ds_read_b128 v[146:149], v209 offset:21504
	ds_read_b128 v[150:153], v209 offset:22528
	ds_read_b128 v[162:165], v209 offset:23552
	global_load_lds_dwordx4 v[242:243], off
	v_lshl_add_u64 v[244:245], s[44:45], 0, v[182:183]
	s_mov_b32 m0, s61
	s_nop 0
	global_load_lds_dwordx4 v[244:245], off
	s_barrier
	s_waitcnt lgkmcnt(0)
	s_setprio 1
	s_waitcnt lgkmcnt(0)
	v_mfma_f32_16x16x32_bf16 v[110:113], v[14:17], v[70:73], v[110:113]
	v_mfma_f32_16x16x32_bf16 v[106:109], v[26:29], v[70:73], v[106:109]
	v_mfma_f32_16x16x32_bf16 v[94:97], v[14:17], v[118:121], v[94:97]
	v_mfma_f32_16x16x32_bf16 v[90:93], v[26:29], v[118:121], v[90:93]
	v_mfma_f32_16x16x32_bf16 v[78:81], v[14:17], v[134:137], v[78:81]
	v_mfma_f32_16x16x32_bf16 v[74:77], v[26:29], v[134:137], v[74:77]
	v_mfma_f32_16x16x32_bf16 v[10:13], v[26:29], v[150:153], v[10:13]
	v_mfma_f32_16x16x32_bf16 v[110:113], v[22:25], v[114:117], v[110:113]
	v_mfma_f32_16x16x32_bf16 v[106:109], v[30:33], v[114:117], v[106:109]
	v_mfma_f32_16x16x32_bf16 v[94:97], v[22:25], v[130:133], v[94:97]
	v_mfma_f32_16x16x32_bf16 v[90:93], v[30:33], v[130:133], v[90:93]
	v_mfma_f32_16x16x32_bf16 v[78:81], v[22:25], v[146:149], v[78:81]
	v_mfma_f32_16x16x32_bf16 v[74:77], v[30:33], v[146:149], v[74:77]
	v_mfma_f32_16x16x32_bf16 v[14:17], v[14:17], v[150:153], v[18:21]
	v_mfma_f32_16x16x32_bf16 v[10:13], v[30:33], v[162:165], v[10:13]
	v_mfma_f32_16x16x32_bf16 v[14:17], v[22:25], v[162:165], v[14:17]
	s_setprio 0
	s_barrier
	s_add_u32 s4, s42, 0x40000
	s_addc_u32 s5, s43, 0
	s_add_i32 s68, s69, s59
	v_lshl_add_u64 v[18:19], s[4:5], 0, v[184:185]
	s_mov_b32 m0, s68
	s_nop 0
	global_load_lds_dwordx4 v[18:19], off
	v_lshl_add_u64 v[18:19], s[4:5], 0, v[182:183]
	s_add_i32 m0, s68, 0x2000
	s_nop 0
	global_load_lds_dwordx4 v[18:19], off
	s_waitcnt vmcnt(6)
	s_barrier
	s_setprio 1
	v_mfma_f32_16x16x32_bf16 v[18:21], v[178:181], v[70:73], v[102:105]
	v_mfma_f32_16x16x32_bf16 v[22:25], v[190:193], v[114:117], v[18:21]
	v_mfma_f32_16x16x32_bf16 v[18:21], v[200:203], v[70:73], v[98:101]
	v_mfma_f32_16x16x32_bf16 v[26:29], v[222:225], v[114:117], v[18:21]
	v_mfma_f32_16x16x32_bf16 v[18:21], v[178:181], v[118:121], v[86:89]
	v_mfma_f32_16x16x32_bf16 v[30:33], v[190:193], v[130:133], v[18:21]
	v_mfma_f32_16x16x32_bf16 v[18:21], v[200:203], v[118:121], v[82:85]
	v_mfma_f32_16x16x32_bf16 v[70:73], v[222:225], v[130:133], v[18:21]
	v_mfma_f32_16x16x32_bf16 v[18:21], v[178:181], v[134:137], v[50:53]
	v_mfma_f32_16x16x32_bf16 v[50:53], v[190:193], v[146:149], v[18:21]
	v_mfma_f32_16x16x32_bf16 v[18:21], v[200:203], v[134:137], v[34:37]
	v_mfma_f32_16x16x32_bf16 v[6:9], v[178:181], v[150:153], v[6:9]
	v_mfma_f32_16x16x32_bf16 v[2:5], v[200:203], v[150:153], v[2:5]
	v_mfma_f32_16x16x32_bf16 v[34:37], v[222:225], v[146:149], v[18:21]
	v_mfma_f32_16x16x32_bf16 v[6:9], v[190:193], v[162:165], v[6:9]
	v_mfma_f32_16x16x32_bf16 v[2:5], v[222:225], v[162:165], v[2:5]
	s_setprio 0
	s_add_i32 s68, 0, 0x18000
	v_add_u32_e32 v98, s68, v204
	s_barrier
	ds_read_b128 v[18:21], v98
	ds_read_b128 v[82:85], v98 offset:1024
	ds_read_b128 v[86:89], v98 offset:2048
	ds_read_b128 v[98:101], v98 offset:3072
	s_add_u32 s4, s44, 0x40000
	s_addc_u32 s5, s45, 0
	s_mov_b32 m0, s62
	v_lshl_add_u64 v[134:135], s[4:5], 0, v[184:185]
	ds_read_b128 v[102:105], v209 offset:32768
	ds_read_b128 v[114:117], v209 offset:33792
	ds_read_b128 v[118:121], v209 offset:34816
	ds_read_b128 v[130:133], v209 offset:35840
	ds_read_b128 v[178:181], v209 offset:36864
	ds_read_b128 v[190:193], v209 offset:37888
	ds_read_b128 v[200:203], v209 offset:38912
	ds_read_b128 v[222:225], v209 offset:39936
	global_load_lds_dwordx4 v[134:135], off
	v_lshl_add_u64 v[134:135], s[4:5], 0, v[182:183]
	s_mov_b32 m0, s63
	s_nop 0
	global_load_lds_dwordx4 v[134:135], off
	s_waitcnt lgkmcnt(8)
	s_barrier
	s_waitcnt lgkmcnt(0)
	s_setprio 1
	s_waitcnt lgkmcnt(0)
	v_mfma_f32_16x16x32_bf16 v[134:137], v[18:21], v[102:105], v[174:177]
	v_mfma_f32_16x16x32_bf16 v[174:177], v[82:85], v[114:117], v[134:137]
	v_mfma_f32_16x16x32_bf16 v[134:137], v[86:89], v[102:105], v[170:173]
	v_mfma_f32_16x16x32_bf16 v[170:173], v[98:101], v[114:117], v[134:137]
	v_mfma_f32_16x16x32_bf16 v[134:137], v[18:21], v[118:121], v[158:161]
	v_mfma_f32_16x16x32_bf16 v[158:161], v[82:85], v[130:133], v[134:137]
	v_mfma_f32_16x16x32_bf16 v[134:137], v[86:89], v[118:121], v[154:157]
	v_mfma_f32_16x16x32_bf16 v[154:157], v[98:101], v[130:133], v[134:137]
	v_mfma_f32_16x16x32_bf16 v[134:137], v[18:21], v[178:181], v[142:145]
	v_mfma_f32_16x16x32_bf16 v[142:145], v[82:85], v[190:193], v[134:137]
	v_mfma_f32_16x16x32_bf16 v[134:137], v[86:89], v[178:181], v[138:141]
	v_mfma_f32_16x16x32_bf16 v[126:129], v[18:21], v[200:203], v[126:129]
	v_mfma_f32_16x16x32_bf16 v[122:125], v[86:89], v[200:203], v[122:125]
	v_mfma_f32_16x16x32_bf16 v[138:141], v[98:101], v[190:193], v[134:137]
	v_mfma_f32_16x16x32_bf16 v[126:129], v[82:85], v[222:225], v[126:129]
	v_mfma_f32_16x16x32_bf16 v[122:125], v[98:101], v[222:225], v[122:125]
	s_setprio 0
	s_barrier
	s_add_i32 s44, 0, 0x1c000
	v_add_u32_e32 v134, s44, v204
	s_add_i32 s4, s68, s59
	ds_read_b128 v[226:229], v134
	ds_read_b128 v[230:233], v134 offset:1024
	ds_read_b128 v[234:237], v134 offset:2048
	ds_read_b128 v[238:241], v134 offset:3072
	v_lshl_add_u64 v[134:135], v[210:211], 0, s[22:23]
	s_mov_b32 m0, s4
	s_nop 0
	global_load_lds_dwordx4 v[134:135], off
	v_lshl_add_u64 v[134:135], v[214:215], 0, s[22:23]
	s_add_i32 m0, s4, 0x2000
	s_nop 0
	global_load_lds_dwordx4 v[134:135], off
	s_barrier
	s_waitcnt lgkmcnt(0)
	s_setprio 1
	s_waitcnt lgkmcnt(0)
	v_mfma_f32_16x16x32_bf16 v[38:41], v[234:237], v[102:105], v[38:41]
	v_mfma_f32_16x16x32_bf16 v[162:165], v[238:241], v[114:117], v[38:41]
	v_mfma_f32_16x16x32_bf16 v[38:41], v[226:229], v[118:121], v[42:45]
	v_mfma_f32_16x16x32_bf16 v[150:153], v[230:233], v[130:133], v[38:41]
	v_mfma_f32_16x16x32_bf16 v[38:41], v[234:237], v[118:121], v[46:49]
	v_mfma_f32_16x16x32_bf16 v[134:137], v[226:229], v[102:105], v[166:169]
	v_mfma_f32_16x16x32_bf16 v[146:149], v[238:241], v[130:133], v[38:41]
	v_mfma_f32_16x16x32_bf16 v[38:41], v[226:229], v[178:181], v[54:57]
	v_mfma_f32_16x16x32_bf16 v[166:169], v[230:233], v[114:117], v[134:137]
	v_mfma_f32_16x16x32_bf16 v[134:137], v[230:233], v[190:193], v[38:41]
	v_mfma_f32_16x16x32_bf16 v[38:41], v[234:237], v[178:181], v[58:61]
	v_mfma_f32_16x16x32_bf16 v[130:133], v[238:241], v[190:193], v[38:41]
	v_mfma_f32_16x16x32_bf16 v[38:41], v[226:229], v[200:203], v[62:65]
	v_mfma_f32_16x16x32_bf16 v[118:121], v[230:233], v[222:225], v[38:41]
	v_mfma_f32_16x16x32_bf16 v[38:41], v[234:237], v[200:203], v[66:69]
	v_mfma_f32_16x16x32_bf16 v[114:117], v[238:241], v[222:225], v[38:41]
	s_setprio 0
	s_mov_b32 m0, s64
	v_lshl_add_u64 v[102:103], v[242:243], 0, s[22:23]
	s_barrier
	s_nop 2
	ds_read_b128 v[38:41], v209 offset:49152
	ds_read_b128 v[42:45], v209 offset:50176
	ds_read_b128 v[46:49], v209 offset:51200
	ds_read_b128 v[54:57], v209 offset:52224
	ds_read_b128 v[58:61], v209 offset:53248
	ds_read_b128 v[62:65], v209 offset:54272
	ds_read_b128 v[66:69], v209 offset:55296
	ds_read_b128 v[178:181], v209 offset:56320
	global_load_lds_dwordx4 v[102:103], off
	v_lshl_add_u64 v[102:103], v[244:245], 0, s[22:23]
	s_mov_b32 m0, s65
	s_nop 0
	global_load_lds_dwordx4 v[102:103], off
	s_barrier
	s_waitcnt lgkmcnt(0)
	s_setprio 1
	s_waitcnt lgkmcnt(0)
	v_mfma_f32_16x16x32_bf16 v[102:105], v[18:21], v[38:41], v[110:113]
	v_mfma_f32_16x16x32_bf16 v[110:113], v[82:85], v[42:45], v[102:105]
	v_mfma_f32_16x16x32_bf16 v[102:105], v[86:89], v[38:41], v[106:109]
	v_mfma_f32_16x16x32_bf16 v[94:97], v[18:21], v[46:49], v[94:97]
	v_mfma_f32_16x16x32_bf16 v[90:93], v[86:89], v[46:49], v[90:93]
	v_mfma_f32_16x16x32_bf16 v[78:81], v[18:21], v[58:61], v[78:81]
	v_mfma_f32_16x16x32_bf16 v[74:77], v[86:89], v[58:61], v[74:77]
	v_mfma_f32_16x16x32_bf16 v[14:17], v[18:21], v[66:69], v[14:17]
	v_mfma_f32_16x16x32_bf16 v[10:13], v[86:89], v[66:69], v[10:13]
	v_mfma_f32_16x16x32_bf16 v[106:109], v[98:101], v[42:45], v[102:105]
	v_mfma_f32_16x16x32_bf16 v[94:97], v[82:85], v[54:57], v[94:97]
	v_mfma_f32_16x16x32_bf16 v[90:93], v[98:101], v[54:57], v[90:93]
	v_mfma_f32_16x16x32_bf16 v[78:81], v[82:85], v[62:65], v[78:81]
	v_mfma_f32_16x16x32_bf16 v[74:77], v[98:101], v[62:65], v[74:77]
	v_mfma_f32_16x16x32_bf16 v[18:21], v[82:85], v[178:181], v[14:17]
	v_mfma_f32_16x16x32_bf16 v[10:13], v[98:101], v[178:181], v[10:13]
	s_setprio 0
	s_barrier
	s_add_u32 s4, s42, 0x40080
	s_addc_u32 s5, s43, 0
	s_add_i32 s42, s44, s59
	v_lshl_add_u64 v[14:15], s[4:5], 0, v[184:185]
	s_mov_b32 m0, s42
	s_nop 0
	global_load_lds_dwordx4 v[14:15], off
	v_lshl_add_u64 v[14:15], s[4:5], 0, v[182:183]
	s_add_i32 m0, s42, 0x2000
	s_nop 0
	global_load_lds_dwordx4 v[14:15], off
	s_waitcnt vmcnt(6)
	s_barrier
	s_setprio 1
	v_mfma_f32_16x16x32_bf16 v[14:17], v[226:229], v[38:41], v[22:25]
	v_mfma_f32_16x16x32_bf16 v[102:105], v[230:233], v[42:45], v[14:17]
	v_mfma_f32_16x16x32_bf16 v[14:17], v[234:237], v[38:41], v[26:29]
	v_mfma_f32_16x16x32_bf16 v[98:101], v[238:241], v[42:45], v[14:17]
	v_mfma_f32_16x16x32_bf16 v[14:17], v[226:229], v[46:49], v[30:33]
	v_mfma_f32_16x16x32_bf16 v[86:89], v[230:233], v[54:57], v[14:17]
	v_mfma_f32_16x16x32_bf16 v[14:17], v[234:237], v[46:49], v[70:73]
	v_mfma_f32_16x16x32_bf16 v[82:85], v[238:241], v[54:57], v[14:17]
	v_mfma_f32_16x16x32_bf16 v[14:17], v[226:229], v[58:61], v[50:53]
	v_mfma_f32_16x16x32_bf16 v[50:53], v[230:233], v[62:65], v[14:17]
	v_mfma_f32_16x16x32_bf16 v[14:17], v[234:237], v[58:61], v[34:37]
	v_mfma_f32_16x16x32_bf16 v[6:9], v[226:229], v[66:69], v[6:9]
	v_mfma_f32_16x16x32_bf16 v[2:5], v[234:237], v[66:69], v[2:5]
	v_mfma_f32_16x16x32_bf16 v[34:37], v[238:241], v[62:65], v[14:17]
	v_mfma_f32_16x16x32_bf16 v[6:9], v[230:233], v[178:181], v[6:9]
	v_mfma_f32_16x16x32_bf16 v[2:5], v[238:241], v[178:181], v[2:5]
	s_setprio 0
	s_add_i32 s57, s57, 2
	s_add_u32 s55, s55, 0x100
	s_addc_u32 s56, s56, 0
	s_cmp_gt_u32 s57, 13
	s_mov_b64 s[4:5], s[36:37]
	s_barrier
	s_cbranch_scc0 .LBB0_396
	v_lshl_add_u64 v[250:251], s[48:49], 0, v[188:189]
	s_add_i32 m0, s60, 0xc000
	s_nop 0
	global_load_lds_dwordx4 v[250:251], off
	v_lshl_add_u64 v[250:251], s[48:49], 0, v[186:187]
	s_add_i32 m0, s60, 0xe000
	s_nop 0
	global_load_lds_dwordx4 v[250:251], off
	v_lshl_or_b32 v202, s27, 8, v208
	s_and_b32 s4, s27, -4
	v_ashrrev_i32_e32 v203, 31, v202
	v_lshlrev_b64 v[14:15], 2, v[202:203]
	v_lshl_add_u64 v[16:17], s[10:11], 0, v[14:15]
	v_lshl_add_u64 v[22:23], s[12:13], 0, v[14:15]
	flat_load_dwordx4 v[70:73], v[16:17]
	flat_load_dwordx4 v[66:69], v[22:23]
	s_cmp_eq_u32 s4, 4
	s_cselect_b64 s[36:37], -1, 0
	s_cmp_lg_u32 s4, 4
	v_mov_b32_e32 v46, 0
	v_and_b32_e32 v210, 0x3ff, v202
	v_mov_b32_e32 v62, 0
	v_mov_b32_e32 v63, 0
	v_mov_b32_e32 v64, 0
	v_mov_b32_e32 v65, 0
	s_cbranch_scc1 .LBB0_399
	v_lshlrev_b32_e32 v14, 2, v210
	v_mov_b32_e32 v15, v0
	v_lshl_add_u64 v[14:15], s[14:15], 0, v[14:15]
	flat_load_dwordx4 v[62:65], v[14:15]

.LBB0_1099:
	s_add_u32 s62, s36, 0x100
	s_addc_u32 s63, s37, 0
	s_add_i32 s84, 0, 0x10000
	v_add_u32_e32 v70, s84, v170
	ds_read_b128 v[58:61], v70
	ds_read_b128 v[62:65], v70 offset:1024
	ds_read_b128 v[66:69], v70 offset:2048
	ds_read_b128 v[70:73], v70 offset:3072
	s_cmp_eq_u32 s83, 12
	s_cselect_b32 s67, s59, s63
	s_cselect_b32 s66, s78, s62
	s_cselect_b32 s65, s79, s82
	s_cselect_b32 s64, s80, s81
	v_lshl_add_u64 v[192:193], s[36:37], 0, v[168:169]
	s_add_i32 m0, s69, 0xc000
	ds_read_b128 v[78:81], v175
	ds_read_b128 v[86:89], v175 offset:1024
	ds_read_b128 v[90:93], v175 offset:2048
	ds_read_b128 v[94:97], v175 offset:3072
	ds_read_b128 v[176:179], v175 offset:4096
	ds_read_b128 v[180:183], v175 offset:5120
	ds_read_b128 v[184:187], v175 offset:6144
	ds_read_b128 v[188:191], v175 offset:7168
	global_load_lds_dwordx4 v[192:193], off
	v_lshl_add_u64 v[192:193], s[36:37], 0, v[166:167]
	s_add_i32 m0, s69, 0xe000
	s_nop 0
	global_load_lds_dwordx4 v[192:193], off
	s_waitcnt lgkmcnt(8)
	s_barrier
	s_waitcnt lgkmcnt(0)
	s_setprio 1
	s_waitcnt lgkmcnt(0)
	v_mfma_f32_16x16x32_bf16 v[158:161], v[58:61], v[78:81], v[158:161]
	v_mfma_f32_16x16x32_bf16 v[150:153], v[66:69], v[78:81], v[150:153]
	v_mfma_f32_16x16x32_bf16 v[142:145], v[58:61], v[90:93], v[142:145]
	v_mfma_f32_16x16x32_bf16 v[134:137], v[66:69], v[90:93], v[134:137]
	v_mfma_f32_16x16x32_bf16 v[126:129], v[58:61], v[176:179], v[126:129]
	v_mfma_f32_16x16x32_bf16 v[118:121], v[66:69], v[176:179], v[118:121]
	v_mfma_f32_16x16x32_bf16 v[110:113], v[58:61], v[184:187], v[110:113]
	v_mfma_f32_16x16x32_bf16 v[102:105], v[66:69], v[184:187], v[102:105]
	v_mfma_f32_16x16x32_bf16 v[158:161], v[62:65], v[86:89], v[158:161]
	v_mfma_f32_16x16x32_bf16 v[150:153], v[70:73], v[86:89], v[150:153]
	v_mfma_f32_16x16x32_bf16 v[142:145], v[62:65], v[94:97], v[142:145]
	v_mfma_f32_16x16x32_bf16 v[134:137], v[70:73], v[94:97], v[134:137]
	v_mfma_f32_16x16x32_bf16 v[126:129], v[62:65], v[180:183], v[126:129]
	v_mfma_f32_16x16x32_bf16 v[118:121], v[70:73], v[180:183], v[118:121]
	v_mfma_f32_16x16x32_bf16 v[110:113], v[62:65], v[188:191], v[110:113]
	v_mfma_f32_16x16x32_bf16 v[102:105], v[70:73], v[188:191], v[102:105]
	s_setprio 0
	s_barrier
	s_add_i32 s85, 0, 0x14000
	v_add_u32_e32 v192, s85, v170
	s_add_i32 s36, s84, s68
	ds_read_b128 v[200:203], v192
	ds_read_b128 v[204:207], v192 offset:1024
	ds_read_b128 v[208:211], v192 offset:2048
	ds_read_b128 v[222:225], v192 offset:3072
	v_lshl_add_u64 v[192:193], s[64:65], 0, v[164:165]
	s_mov_b32 m0, s36
	v_lshl_add_u64 v[214:215], s[64:65], 0, v[162:163]
	global_load_lds_dwordx4 v[192:193], off
	s_add_i32 m0, s36, 0x2000
	s_nop 0
	global_load_lds_dwordx4 v[214:215], off
	s_barrier
	s_waitcnt lgkmcnt(0)
	s_setprio 1
	s_waitcnt lgkmcnt(0)
	v_mfma_f32_16x16x32_bf16 v[154:157], v[200:203], v[78:81], v[154:157]
	v_mfma_f32_16x16x32_bf16 v[78:81], v[208:211], v[78:81], v[146:149]
	v_mfma_f32_16x16x32_bf16 v[154:157], v[204:207], v[86:89], v[154:157]
	v_mfma_f32_16x16x32_bf16 v[78:81], v[222:225], v[86:89], v[78:81]
	v_mfma_f32_16x16x32_bf16 v[86:89], v[200:203], v[90:93], v[138:141]
	v_mfma_f32_16x16x32_bf16 v[90:93], v[208:211], v[90:93], v[130:133]
	v_mfma_f32_16x16x32_bf16 v[114:117], v[208:211], v[176:179], v[114:117]
	v_mfma_f32_16x16x32_bf16 v[106:109], v[200:203], v[184:187], v[106:109]
	v_mfma_f32_16x16x32_bf16 v[98:101], v[208:211], v[184:187], v[98:101]
	v_mfma_f32_16x16x32_bf16 v[86:89], v[204:207], v[94:97], v[86:89]
	v_mfma_f32_16x16x32_bf16 v[90:93], v[222:225], v[94:97], v[90:93]
	v_mfma_f32_16x16x32_bf16 v[94:97], v[200:203], v[176:179], v[122:125]
	v_mfma_f32_16x16x32_bf16 v[114:117], v[222:225], v[180:183], v[114:117]
	v_mfma_f32_16x16x32_bf16 v[106:109], v[204:207], v[188:191], v[106:109]
	v_mfma_f32_16x16x32_bf16 v[98:101], v[222:225], v[188:191], v[98:101]
	v_mfma_f32_16x16x32_bf16 v[94:97], v[204:207], v[180:183], v[94:97]
	s_setprio 0
	s_mov_b32 m0, s69
	v_lshl_add_u64 v[234:235], s[66:67], 0, v[164:165]
	s_barrier
	ds_read_b128 v[122:125], v175 offset:16384
	ds_read_b128 v[130:133], v175 offset:17408
	ds_read_b128 v[138:141], v175 offset:18432
	ds_read_b128 v[146:149], v175 offset:19456
	ds_read_b128 v[176:179], v175 offset:20480
	ds_read_b128 v[180:183], v175 offset:21504
	ds_read_b128 v[184:187], v175 offset:22528
	ds_read_b128 v[188:191], v175 offset:23552
	global_load_lds_dwordx4 v[234:235], off
	v_lshl_add_u64 v[236:237], s[66:67], 0, v[162:163]
	s_mov_b32 m0, s70
	s_nop 0
	global_load_lds_dwordx4 v[236:237], off
	s_barrier
	s_waitcnt lgkmcnt(0)
	s_setprio 1
	s_waitcnt lgkmcnt(0)
	v_mfma_f32_16x16x32_bf16 v[82:85], v[58:61], v[122:125], v[82:85]
	v_mfma_f32_16x16x32_bf16 v[54:57], v[66:69], v[122:125], v[54:57]
	v_mfma_f32_16x16x32_bf16 v[46:49], v[58:61], v[138:141], v[46:49]
	v_mfma_f32_16x16x32_bf16 v[38:41], v[66:69], v[138:141], v[38:41]
	v_mfma_f32_16x16x32_bf16 v[30:33], v[58:61], v[176:179], v[30:33]
	v_mfma_f32_16x16x32_bf16 v[22:25], v[66:69], v[176:179], v[22:25]
	v_mfma_f32_16x16x32_bf16 v[14:17], v[58:61], v[184:187], v[14:17]
	v_mfma_f32_16x16x32_bf16 v[6:9], v[66:69], v[184:187], v[6:9]
	v_mfma_f32_16x16x32_bf16 v[82:85], v[62:65], v[130:133], v[82:85]
	v_mfma_f32_16x16x32_bf16 v[54:57], v[70:73], v[130:133], v[54:57]
	v_mfma_f32_16x16x32_bf16 v[46:49], v[62:65], v[146:149], v[46:49]
	v_mfma_f32_16x16x32_bf16 v[38:41], v[70:73], v[146:149], v[38:41]
	v_mfma_f32_16x16x32_bf16 v[30:33], v[62:65], v[180:183], v[30:33]
	v_mfma_f32_16x16x32_bf16 v[22:25], v[70:73], v[180:183], v[22:25]
	v_mfma_f32_16x16x32_bf16 v[14:17], v[62:65], v[188:191], v[14:17]
	v_mfma_f32_16x16x32_bf16 v[6:9], v[70:73], v[188:191], v[6:9]
	s_setprio 0
	s_barrier
	s_add_u32 s36, s64, 0x40000
	s_addc_u32 s37, s65, 0
	s_add_i32 s84, s85, s68
	v_lshl_add_u64 v[58:59], s[36:37], 0, v[164:165]
	s_mov_b32 m0, s84
	s_nop 0
	global_load_lds_dwordx4 v[58:59], off
	v_lshl_add_u64 v[58:59], s[36:37], 0, v[162:163]
	s_add_i32 m0, s84, 0x2000
	s_nop 0
	global_load_lds_dwordx4 v[58:59], off
	s_waitcnt vmcnt(6)
	s_barrier
	s_setprio 1
	v_mfma_f32_16x16x32_bf16 v[50:53], v[208:211], v[122:125], v[50:53]
	v_mfma_f32_16x16x32_bf16 v[42:45], v[200:203], v[138:141], v[42:45]
	v_mfma_f32_16x16x32_bf16 v[34:37], v[208:211], v[138:141], v[34:37]
	v_mfma_f32_16x16x32_bf16 v[26:29], v[200:203], v[176:179], v[26:29]
	v_mfma_f32_16x16x32_bf16 v[18:21], v[208:211], v[176:179], v[18:21]
	v_mfma_f32_16x16x32_bf16 v[10:13], v[200:203], v[184:187], v[10:13]
	v_mfma_f32_16x16x32_bf16 v[2:5], v[208:211], v[184:187], v[2:5]
	v_mfma_f32_16x16x32_bf16 v[58:61], v[200:203], v[122:125], v[74:77]
	v_mfma_f32_16x16x32_bf16 v[50:53], v[222:225], v[130:133], v[50:53]
	v_mfma_f32_16x16x32_bf16 v[42:45], v[204:207], v[146:149], v[42:45]
	v_mfma_f32_16x16x32_bf16 v[34:37], v[222:225], v[146:149], v[34:37]
	v_mfma_f32_16x16x32_bf16 v[26:29], v[204:207], v[180:183], v[26:29]
	v_mfma_f32_16x16x32_bf16 v[18:21], v[222:225], v[180:183], v[18:21]
	v_mfma_f32_16x16x32_bf16 v[10:13], v[204:207], v[188:191], v[10:13]
	v_mfma_f32_16x16x32_bf16 v[2:5], v[222:225], v[188:191], v[2:5]
	v_mfma_f32_16x16x32_bf16 v[58:61], v[204:207], v[130:133], v[58:61]
	s_setprio 0
	s_add_i32 s84, 0, 0x18000
	v_add_u32_e32 v74, s84, v170
	s_barrier
	ds_read_b128 v[62:65], v74
	ds_read_b128 v[66:69], v74 offset:1024
	ds_read_b128 v[70:73], v74 offset:2048
	ds_read_b128 v[74:77], v74 offset:3072
	s_add_u32 s36, s66, 0x40000
	s_addc_u32 s37, s67, 0
	s_mov_b32 m0, s71
	v_lshl_add_u64 v[138:139], s[36:37], 0, v[164:165]
	ds_read_b128 v[122:125], v175 offset:32768
	ds_read_b128 v[130:133], v175 offset:33792
	ds_read_b128 v[176:179], v175 offset:34816
	ds_read_b128 v[180:183], v175 offset:35840
	ds_read_b128 v[184:187], v175 offset:36864
	ds_read_b128 v[188:191], v175 offset:37888
	ds_read_b128 v[200:203], v175 offset:38912
	ds_read_b128 v[204:207], v175 offset:39936
	global_load_lds_dwordx4 v[138:139], off
	v_lshl_add_u64 v[138:139], s[36:37], 0, v[162:163]
	s_mov_b32 m0, s72
	s_nop 0
	global_load_lds_dwordx4 v[138:139], off
	s_waitcnt lgkmcnt(8)
	s_barrier
	s_waitcnt lgkmcnt(0)
	s_setprio 1
	s_waitcnt lgkmcnt(0)
	v_mfma_f32_16x16x32_bf16 v[138:141], v[62:65], v[122:125], v[158:161]
	v_mfma_f32_16x16x32_bf16 v[158:161], v[66:69], v[130:133], v[138:141]
	v_mfma_f32_16x16x32_bf16 v[138:141], v[70:73], v[122:125], v[150:153]
	v_mfma_f32_16x16x32_bf16 v[150:153], v[74:77], v[130:133], v[138:141]
	v_mfma_f32_16x16x32_bf16 v[138:141], v[62:65], v[176:179], v[142:145]
	v_mfma_f32_16x16x32_bf16 v[134:137], v[70:73], v[176:179], v[134:137]
	v_mfma_f32_16x16x32_bf16 v[126:129], v[62:65], v[184:187], v[126:129]
	v_mfma_f32_16x16x32_bf16 v[118:121], v[70:73], v[184:187], v[118:121]
	v_mfma_f32_16x16x32_bf16 v[110:113], v[62:65], v[200:203], v[110:113]
	v_mfma_f32_16x16x32_bf16 v[102:105], v[70:73], v[200:203], v[102:105]
	v_mfma_f32_16x16x32_bf16 v[142:145], v[66:69], v[180:183], v[138:141]
	v_mfma_f32_16x16x32_bf16 v[134:137], v[74:77], v[180:183], v[134:137]
	v_mfma_f32_16x16x32_bf16 v[126:129], v[66:69], v[188:191], v[126:129]
	v_mfma_f32_16x16x32_bf16 v[118:121], v[74:77], v[188:191], v[118:121]
	v_mfma_f32_16x16x32_bf16 v[110:113], v[66:69], v[204:207], v[110:113]
	v_mfma_f32_16x16x32_bf16 v[102:105], v[74:77], v[204:207], v[102:105]
	s_setprio 0
	s_barrier
	s_add_i32 s66, 0, 0x1c000
	v_add_u32_e32 v138, s66, v170
	s_add_i32 s36, s84, s68
	ds_read_b128 v[208:211], v138
	ds_read_b128 v[222:225], v138 offset:1024
	ds_read_b128 v[226:229], v138 offset:2048
	ds_read_b128 v[230:233], v138 offset:3072
	v_lshl_add_u64 v[138:139], v[192:193], 0, s[22:23]
	s_mov_b32 m0, s36
	s_nop 0
	global_load_lds_dwordx4 v[138:139], off
	v_lshl_add_u64 v[138:139], v[214:215], 0, s[22:23]
	s_add_i32 m0, s36, 0x2000
	s_nop 0
	global_load_lds_dwordx4 v[138:139], off
	s_barrier
	s_waitcnt lgkmcnt(0)
	s_setprio 1
	s_waitcnt lgkmcnt(0)
	v_mfma_f32_16x16x32_bf16 v[78:81], v[226:229], v[122:125], v[78:81]
	v_mfma_f32_16x16x32_bf16 v[138:141], v[208:211], v[122:125], v[154:157]
	v_mfma_f32_16x16x32_bf16 v[146:149], v[230:233], v[130:133], v[78:81]
	v_mfma_f32_16x16x32_bf16 v[78:81], v[208:211], v[176:179], v[86:89]
	v_mfma_f32_16x16x32_bf16 v[154:157], v[222:225], v[130:133], v[138:141]
	v_mfma_f32_16x16x32_bf16 v[138:141], v[222:225], v[180:183], v[78:81]
	v_mfma_f32_16x16x32_bf16 v[78:81], v[226:229], v[176:179], v[90:93]
	v_mfma_f32_16x16x32_bf16 v[130:133], v[230:233], v[180:183], v[78:81]
	v_mfma_f32_16x16x32_bf16 v[78:81], v[208:211], v[184:187], v[94:97]
	v_mfma_f32_16x16x32_bf16 v[122:125], v[222:225], v[188:191], v[78:81]
	v_mfma_f32_16x16x32_bf16 v[78:81], v[226:229], v[184:187], v[114:117]
	v_mfma_f32_16x16x32_bf16 v[114:117], v[230:233], v[188:191], v[78:81]
	v_mfma_f32_16x16x32_bf16 v[78:81], v[208:211], v[200:203], v[106:109]
	v_mfma_f32_16x16x32_bf16 v[106:109], v[222:225], v[204:207], v[78:81]
	v_mfma_f32_16x16x32_bf16 v[78:81], v[226:229], v[200:203], v[98:101]
	v_mfma_f32_16x16x32_bf16 v[98:101], v[230:233], v[204:207], v[78:81]
	s_setprio 0
	s_mov_b32 m0, s73
	v_lshl_add_u64 v[192:193], v[234:235], 0, s[22:23]
	s_barrier
	s_nop 2
	ds_read_b128 v[78:81], v175 offset:49152
	ds_read_b128 v[86:89], v175 offset:50176
	ds_read_b128 v[90:93], v175 offset:51200
	ds_read_b128 v[94:97], v175 offset:52224
	ds_read_b128 v[176:179], v175 offset:53248
	ds_read_b128 v[180:183], v175 offset:54272
	ds_read_b128 v[184:187], v175 offset:55296
	ds_read_b128 v[188:191], v175 offset:56320
	global_load_lds_dwordx4 v[192:193], off
	v_lshl_add_u64 v[192:193], v[236:237], 0, s[22:23]
	s_mov_b32 m0, s75
	s_nop 0
	global_load_lds_dwordx4 v[192:193], off
	s_barrier
	s_waitcnt lgkmcnt(0)
	s_setprio 1
	s_waitcnt lgkmcnt(0)
	v_mfma_f32_16x16x32_bf16 v[82:85], v[62:65], v[78:81], v[82:85]
	v_mfma_f32_16x16x32_bf16 v[54:57], v[70:73], v[78:81], v[54:57]
	v_mfma_f32_16x16x32_bf16 v[46:49], v[62:65], v[90:93], v[46:49]
	v_mfma_f32_16x16x32_bf16 v[38:41], v[70:73], v[90:93], v[38:41]
	v_mfma_f32_16x16x32_bf16 v[30:33], v[62:65], v[176:179], v[30:33]
	v_mfma_f32_16x16x32_bf16 v[22:25], v[70:73], v[176:179], v[22:25]
	v_mfma_f32_16x16x32_bf16 v[14:17], v[62:65], v[184:187], v[14:17]
	v_mfma_f32_16x16x32_bf16 v[6:9], v[70:73], v[184:187], v[6:9]
	v_mfma_f32_16x16x32_bf16 v[82:85], v[66:69], v[86:89], v[82:85]
	v_mfma_f32_16x16x32_bf16 v[54:57], v[74:77], v[86:89], v[54:57]
	v_mfma_f32_16x16x32_bf16 v[46:49], v[66:69], v[94:97], v[46:49]
	v_mfma_f32_16x16x32_bf16 v[38:41], v[74:77], v[94:97], v[38:41]
	v_mfma_f32_16x16x32_bf16 v[30:33], v[66:69], v[180:183], v[30:33]
	v_mfma_f32_16x16x32_bf16 v[22:25], v[74:77], v[180:183], v[22:25]
	v_mfma_f32_16x16x32_bf16 v[14:17], v[66:69], v[188:191], v[14:17]
	v_mfma_f32_16x16x32_bf16 v[6:9], v[74:77], v[188:191], v[6:9]
	s_setprio 0
	s_barrier
	s_add_u32 s36, s64, 0x40080
	s_addc_u32 s37, s65, 0
	s_add_i32 s64, s66, s68
	v_lshl_add_u64 v[62:63], s[36:37], 0, v[164:165]
	s_mov_b32 m0, s64
	s_nop 0
	global_load_lds_dwordx4 v[62:63], off
	v_lshl_add_u64 v[62:63], s[36:37], 0, v[162:163]
	s_add_i32 m0, s64, 0x2000
	s_nop 0
	global_load_lds_dwordx4 v[62:63], off
	s_waitcnt vmcnt(6)
	s_barrier
	s_setprio 1
	v_mfma_f32_16x16x32_bf16 v[58:61], v[208:211], v[78:81], v[58:61]
	v_mfma_f32_16x16x32_bf16 v[50:53], v[226:229], v[78:81], v[50:53]
	v_mfma_f32_16x16x32_bf16 v[42:45], v[208:211], v[90:93], v[42:45]
	v_mfma_f32_16x16x32_bf16 v[34:37], v[226:229], v[90:93], v[34:37]
	v_mfma_f32_16x16x32_bf16 v[26:29], v[208:211], v[176:179], v[26:29]
	v_mfma_f32_16x16x32_bf16 v[18:21], v[226:229], v[176:179], v[18:21]
	v_mfma_f32_16x16x32_bf16 v[10:13], v[208:211], v[184:187], v[10:13]
	v_mfma_f32_16x16x32_bf16 v[2:5], v[226:229], v[184:187], v[2:5]
	v_mfma_f32_16x16x32_bf16 v[74:77], v[222:225], v[86:89], v[58:61]
	v_mfma_f32_16x16x32_bf16 v[50:53], v[230:233], v[86:89], v[50:53]
	v_mfma_f32_16x16x32_bf16 v[42:45], v[222:225], v[94:97], v[42:45]
	v_mfma_f32_16x16x32_bf16 v[34:37], v[230:233], v[94:97], v[34:37]
	v_mfma_f32_16x16x32_bf16 v[26:29], v[222:225], v[180:183], v[26:29]
	v_mfma_f32_16x16x32_bf16 v[18:21], v[230:233], v[180:183], v[18:21]
	v_mfma_f32_16x16x32_bf16 v[10:13], v[222:225], v[188:191], v[10:13]
	v_mfma_f32_16x16x32_bf16 v[2:5], v[230:233], v[188:191], v[2:5]
	s_setprio 0
	s_add_i32 s83, s83, 2
	s_add_u32 s81, s81, 0x100
	s_addc_u32 s82, s82, 0
	s_cmp_gt_u32 s83, 13
	s_mov_b64 s[36:37], s[62:63]
	s_barrier
	s_cbranch_scc0 .LBB0_1099
	v_lshl_add_u64 v[250:251], s[56:57], 0, v[168:169]
	s_add_i32 m0, s69, 0xc000
	s_nop 0
	global_load_lds_dwordx4 v[250:251], off
	v_lshl_add_u64 v[250:251], s[56:57], 0, v[166:167]
	s_add_i32 m0, s69, 0xe000
	s_nop 0
	global_load_lds_dwordx4 v[250:251], off
	v_lshl_or_b32 v58, s27, 8, v174
	v_mov_b32_e32 v177, v1
	v_ashrrev_i32_e32 v59, 31, v58
	v_lshlrev_b64 v[58:59], 2, v[58:59]
	v_lshl_add_u64 v[66:67], s[46:47], 0, v[58:59]
	v_lshl_add_u64 v[70:71], s[48:49], 0, v[58:59]
	flat_load_dwordx4 v[86:89], v[66:67]
	flat_load_dwordx4 v[78:81], v[70:71]
	flat_load_dwordx4 v[62:65], v[66:67] offset:16
	flat_load_dwordx4 v[58:61], v[70:71] offset:16
	flat_load_dwordx4 v[94:97], v[66:67] offset:512
	flat_load_dwordx4 v[90:93], v[70:71] offset:512
	s_nop 0
	flat_load_dwordx4 v[66:69], v[66:67] offset:528
	s_nop 0
	flat_load_dwordx4 v[70:73], v[70:71] offset:528
	s_lshl_b32 s3, s3, 8
	v_lshl_or_b32 v176, s27, 7, v174
	v_add_u32_e32 v184, s3, v177
	v_lshl_add_u32 v177, v177, 3, s33
	s_waitcnt vmcnt(0)
	ds_read_b64 v[178:179], v177
	s_movk_i32 s27, 0xb00
	s_and_b64 vcc, exec, s[60:61]
	s_waitcnt lgkmcnt(0)
	v_xor_b32_e32 v89, 0x80000000, v89
	v_xor_b32_e32 v88, 0x80000000, v88
	v_pk_fma_f32 v[160:161], v[88:89], v[178:179], v[160:161] op_sel_hi:[1,0,1]
	v_pk_fma_f32 v[158:159], v[86:87], v[178:179], v[158:159] op_sel_hi:[1,0,1] neg_lo:[1,0,0] neg_hi:[1,0,0]
	v_pk_fma_f32 v[160:161], v[178:179], v[160:161], v[80:81] op_sel:[1,0,0]
	v_pk_fma_f32 v[158:159], v[178:179], v[158:159], v[78:79] op_sel:[1,0,0]
	v_pk_fma_f32 v[154:155], v[94:95], v[178:179], v[154:155] op_sel_hi:[1,0,1] neg_lo:[1,0,0] neg_hi:[1,0,0]
	v_mul_f32_e32 v182, 0xbfb8aa3b, v160
	v_pk_fma_f32 v[180:181], v[178:179], v[154:155], v[90:91] op_sel:[1,0,0]
	v_mul_f32_e32 v154, 0xbfb8aa3b, v158
	v_mul_f32_e32 v155, 0xbfb8aa3b, v159
	v_mul_f32_e32 v183, 0xbfb8aa3b, v161
	v_exp_f32_e32 v154, v154
	v_exp_f32_e32 v155, v155
	v_exp_f32_e32 v182, v182
	v_exp_f32_e32 v183, v183
	v_add_f32_e32 v154, 1.0, v154
	v_add_f32_e32 v155, 1.0, v155
	v_add_f32_e32 v182, 1.0, v182
	v_add_f32_e32 v183, 1.0, v183
	v_rcp_f32_e32 v154, v154
	v_rcp_f32_e32 v155, v155
	v_rcp_f32_e32 v182, v182
	v_rcp_f32_e32 v183, v183
	v_xor_b32_e32 v97, 0x80000000, v97
	v_xor_b32_e32 v96, 0x80000000, v96
	v_xor_b32_e32 v65, 0x80000000, v65
	v_xor_b32_e32 v64, 0x80000000, v64
	v_pk_fma_f32 v[156:157], v[96:97], v[178:179], v[156:157] op_sel_hi:[1,0,1]
	v_pk_fma_f32 v[152:153], v[64:65], v[178:179], v[152:153] op_sel_hi:[1,0,1]
	v_pk_fma_f32 v[150:151], v[62:63], v[178:179], v[150:151] op_sel_hi:[1,0,1] neg_lo:[1,0,0] neg_hi:[1,0,0]
	v_pk_fma_f32 v[156:157], v[178:179], v[156:157], v[92:93] op_sel:[1,0,0]
	v_pk_mul_f32 v[160:161], v[160:161], v[182:183]
	v_pk_mul_f32 v[158:159], v[158:159], v[154:155]
	v_pk_fma_f32 v[152:153], v[178:179], v[152:153], v[60:61] op_sel:[1,0,0]
	v_pk_fma_f32 v[150:151], v[178:179], v[150:151], v[58:59] op_sel:[1,0,0]
	v_pk_mul_f32 v[154:155], v[156:157], v[160:161]
	v_pk_mul_f32 v[156:157], v[180:181], v[158:159]
	v_mul_f32_e32 v158, 0xbfb8aa3b, v150
	v_mul_f32_e32 v159, 0xbfb8aa3b, v151
	v_mul_f32_e32 v160, 0xbfb8aa3b, v152
	v_mul_f32_e32 v161, 0xbfb8aa3b, v153
	v_exp_f32_e32 v158, v158
	v_exp_f32_e32 v159, v159
	v_exp_f32_e32 v160, v160
	v_exp_f32_e32 v161, v161
	v_add_f32_e32 v158, 1.0, v158
	v_add_f32_e32 v159, 1.0, v159
	v_add_f32_e32 v160, 1.0, v160
	v_add_f32_e32 v161, 1.0, v161
	v_rcp_f32_e32 v158, v158
	v_rcp_f32_e32 v159, v159
	v_rcp_f32_e32 v160, v160
	v_rcp_f32_e32 v161, v161
	v_xor_b32_e32 v69, 0x80000000, v69
	v_xor_b32_e32 v68, 0x80000000, v68
	v_pk_fma_f32 v[148:149], v[68:69], v[178:179], v[148:149] op_sel_hi:[1,0,1]
	v_pk_fma_f32 v[146:147], v[66:67], v[178:179], v[146:147] op_sel_hi:[1,0,1] neg_lo:[1,0,0] neg_hi:[1,0,0]
	v_pk_fma_f32 v[148:149], v[178:179], v[148:149], v[72:73] op_sel:[1,0,0]
	v_pk_fma_f32 v[146:147], v[178:179], v[146:147], v[70:71] op_sel:[1,0,0]
	v_pk_mul_f32 v[152:153], v[152:153], v[160:161]
	v_pk_mul_f32 v[150:151], v[150:151], v[158:159]
	v_mul_lo_u32 v158, v184, s27
	v_pk_mul_f32 v[152:153], v[148:149], v[152:153]
	v_pk_mul_f32 v[148:149], v[146:147], v[150:151]
	v_add_lshl_u32 v150, v158, v176, 1
	v_cvt_pk_bf16_f32 v146, v156, v157
	v_cvt_pk_bf16_f32 v147, v154, v155
	v_cvt_pk_bf16_f32 v148, v148, v149
	v_cvt_pk_bf16_f32 v149, v152, v153
	buffer_store_dwordx4 v[146:149], v150, s[28:31], 0 offen sc1
	ds_read_b64 v[146:147], v177 offset:128
	s_waitcnt lgkmcnt(0)
	v_pk_fma_f32 v[142:143], v[86:87], v[146:147], v[142:143] op_sel_hi:[1,0,1] neg_lo:[1,0,0] neg_hi:[1,0,0]
	s_nop 0
	v_pk_fma_f32 v[142:143], v[146:147], v[142:143], v[78:79] op_sel:[1,0,0]
	v_pk_fma_f32 v[144:145], v[88:89], v[146:147], v[144:145] op_sel_hi:[1,0,1]
	v_mul_f32_e32 v148, 0xbfb8aa3b, v142
	v_mul_f32_e32 v149, 0xbfb8aa3b, v143
	v_pk_fma_f32 v[144:145], v[146:147], v[144:145], v[80:81] op_sel:[1,0,0]
	v_exp_f32_e32 v148, v148
	v_exp_f32_e32 v149, v149
	v_mul_f32_e32 v150, 0xbfb8aa3b, v144
	v_mul_f32_e32 v151, 0xbfb8aa3b, v145
	v_exp_f32_e32 v150, v150
	v_exp_f32_e32 v151, v151
	v_add_f32_e32 v148, 1.0, v148
	v_add_f32_e32 v149, 1.0, v149
	v_rcp_f32_e32 v148, v148
	v_rcp_f32_e32 v149, v149
	v_add_f32_e32 v150, 1.0, v150
	v_add_f32_e32 v151, 1.0, v151
	v_rcp_f32_e32 v150, v150
	v_rcp_f32_e32 v151, v151
	v_pk_fma_f32 v[138:139], v[94:95], v[146:147], v[138:139] op_sel_hi:[1,0,1] neg_lo:[1,0,0] neg_hi:[1,0,0]
	v_pk_fma_f32 v[134:135], v[62:63], v[146:147], v[134:135] op_sel_hi:[1,0,1] neg_lo:[1,0,0] neg_hi:[1,0,0]
	v_pk_fma_f32 v[138:139], v[146:147], v[138:139], v[90:91] op_sel:[1,0,0]
	v_pk_mul_f32 v[142:143], v[142:143], v[148:149]
	v_pk_fma_f32 v[134:135], v[146:147], v[134:135], v[58:59] op_sel:[1,0,0]
	v_pk_fma_f32 v[140:141], v[96:97], v[146:147], v[140:141] op_sel_hi:[1,0,1]
	v_pk_mul_f32 v[138:139], v[138:139], v[142:143]
	v_pk_fma_f32 v[136:137], v[64:65], v[146:147], v[136:137] op_sel_hi:[1,0,1]
	v_mul_f32_e32 v142, 0xbfb8aa3b, v134
	v_mul_f32_e32 v143, 0xbfb8aa3b, v135
	v_pk_fma_f32 v[140:141], v[146:147], v[140:141], v[92:93] op_sel:[1,0,0]
	v_pk_mul_f32 v[144:145], v[144:145], v[150:151]
	v_pk_fma_f32 v[136:137], v[146:147], v[136:137], v[60:61] op_sel:[1,0,0]
	v_exp_f32_e32 v142, v142
	v_exp_f32_e32 v143, v143
	v_pk_mul_f32 v[140:141], v[140:141], v[144:145]
	v_mul_f32_e32 v144, 0xbfb8aa3b, v136
	v_mul_f32_e32 v145, 0xbfb8aa3b, v137
	v_exp_f32_e32 v144, v144
	v_exp_f32_e32 v145, v145
	v_add_f32_e32 v142, 1.0, v142
	v_add_f32_e32 v143, 1.0, v143
	v_rcp_f32_e32 v142, v142
	v_rcp_f32_e32 v143, v143
	v_add_f32_e32 v144, 1.0, v144
	v_add_f32_e32 v145, 1.0, v145
	v_rcp_f32_e32 v144, v144
	v_rcp_f32_e32 v145, v145
	v_pk_fma_f32 v[130:131], v[66:67], v[146:147], v[130:131] op_sel_hi:[1,0,1] neg_lo:[1,0,0] neg_hi:[1,0,0]
	v_pk_mul_f32 v[134:135], v[134:135], v[142:143]
	v_pk_fma_f32 v[130:131], v[146:147], v[130:131], v[70:71] op_sel:[1,0,0]
	v_pk_fma_f32 v[132:133], v[68:69], v[146:147], v[132:133] op_sel_hi:[1,0,1]
	v_pk_mul_f32 v[134:135], v[130:131], v[134:135]
	v_add_u32_e32 v130, 0xb000, v176
	v_pk_fma_f32 v[132:133], v[146:147], v[132:133], v[72:73] op_sel:[1,0,0]
	v_pk_mul_f32 v[136:137], v[136:137], v[144:145]
	v_add_lshl_u32 v131, v158, v130, 1
	v_pk_mul_f32 v[136:137], v[132:133], v[136:137]
	v_cvt_pk_bf16_f32 v132, v138, v139
	v_cvt_pk_bf16_f32 v133, v140, v141
	v_cvt_pk_bf16_f32 v134, v134, v135
	s_nop 0
	v_cvt_pk_bf16_f32 v135, v136, v137
	buffer_store_dwordx4 v[132:135], v131, s[28:31], 0 offen sc1
	v_mov_b32_e32 v131, v171
	s_nop 0
	v_add_u32_e32 v138, s3, v131
	v_lshl_add_u32 v131, v131, 3, s33
	ds_read_b64 v[132:133], v131
	s_waitcnt lgkmcnt(0)
	v_pk_fma_f32 v[128:129], v[88:89], v[132:133], v[128:129] op_sel_hi:[1,0,1]
	v_pk_fma_f32 v[126:127], v[86:87], v[132:133], v[126:127] op_sel_hi:[1,0,1] neg_lo:[1,0,0] neg_hi:[1,0,0]
	v_pk_fma_f32 v[128:129], v[132:133], v[128:129], v[80:81] op_sel:[1,0,0]
	v_pk_fma_f32 v[126:127], v[132:133], v[126:127], v[78:79] op_sel:[1,0,0]
	v_mul_f32_e32 v136, 0xbfb8aa3b, v128
	v_mul_f32_e32 v134, 0xbfb8aa3b, v126
	v_mul_f32_e32 v135, 0xbfb8aa3b, v127
	v_mul_f32_e32 v137, 0xbfb8aa3b, v129
	v_exp_f32_e32 v134, v134
	v_exp_f32_e32 v135, v135
	v_exp_f32_e32 v136, v136
	v_exp_f32_e32 v137, v137
	v_add_f32_e32 v134, 1.0, v134
	v_add_f32_e32 v135, 1.0, v135
	v_add_f32_e32 v136, 1.0, v136
	v_add_f32_e32 v137, 1.0, v137
	v_rcp_f32_e32 v134, v134
	v_rcp_f32_e32 v135, v135
	v_rcp_f32_e32 v136, v136
	v_rcp_f32_e32 v137, v137
	v_pk_fma_f32 v[124:125], v[96:97], v[132:133], v[124:125] op_sel_hi:[1,0,1]
	v_pk_fma_f32 v[122:123], v[94:95], v[132:133], v[122:123] op_sel_hi:[1,0,1] neg_lo:[1,0,0] neg_hi:[1,0,0]
	v_pk_fma_f32 v[120:121], v[64:65], v[132:133], v[120:121] op_sel_hi:[1,0,1]
	v_pk_fma_f32 v[118:119], v[62:63], v[132:133], v[118:119] op_sel_hi:[1,0,1] neg_lo:[1,0,0] neg_hi:[1,0,0]
	v_pk_fma_f32 v[124:125], v[132:133], v[124:125], v[92:93] op_sel:[1,0,0]
	v_pk_fma_f32 v[122:123], v[132:133], v[122:123], v[90:91] op_sel:[1,0,0]
	v_pk_mul_f32 v[128:129], v[128:129], v[136:137]
	v_pk_mul_f32 v[126:127], v[126:127], v[134:135]
	v_pk_fma_f32 v[120:121], v[132:133], v[120:121], v[60:61] op_sel:[1,0,0]
	v_pk_fma_f32 v[118:119], v[132:133], v[118:119], v[58:59] op_sel:[1,0,0]
	v_pk_mul_f32 v[124:125], v[124:125], v[128:129]
	v_pk_mul_f32 v[122:123], v[122:123], v[126:127]
	v_mul_f32_e32 v126, 0xbfb8aa3b, v118
	v_mul_f32_e32 v127, 0xbfb8aa3b, v119
	v_mul_f32_e32 v128, 0xbfb8aa3b, v120
	v_mul_f32_e32 v129, 0xbfb8aa3b, v121
	v_exp_f32_e32 v126, v126
	v_exp_f32_e32 v127, v127
	v_exp_f32_e32 v128, v128
	v_exp_f32_e32 v129, v129
	v_add_f32_e32 v126, 1.0, v126
	v_add_f32_e32 v127, 1.0, v127
	v_add_f32_e32 v128, 1.0, v128
	v_add_f32_e32 v129, 1.0, v129
	v_rcp_f32_e32 v126, v126
	v_rcp_f32_e32 v127, v127
	v_rcp_f32_e32 v128, v128
	v_rcp_f32_e32 v129, v129
	v_pk_fma_f32 v[116:117], v[68:69], v[132:133], v[116:117] op_sel_hi:[1,0,1]
	v_pk_fma_f32 v[114:115], v[66:67], v[132:133], v[114:115] op_sel_hi:[1,0,1] neg_lo:[1,0,0] neg_hi:[1,0,0]
	v_pk_fma_f32 v[116:117], v[132:133], v[116:117], v[72:73] op_sel:[1,0,0]
	v_pk_fma_f32 v[114:115], v[132:133], v[114:115], v[70:71] op_sel:[1,0,0]
	v_pk_mul_f32 v[120:121], v[120:121], v[128:129]
	v_pk_mul_f32 v[118:119], v[118:119], v[126:127]
	v_mul_lo_u32 v126, v138, s27
	v_pk_mul_f32 v[120:121], v[116:117], v[120:121]
	v_pk_mul_f32 v[116:117], v[114:115], v[118:119]
	v_add_lshl_u32 v118, v126, v176, 1
	v_cvt_pk_bf16_f32 v114, v122, v123
	v_cvt_pk_bf16_f32 v115, v124, v125
	v_cvt_pk_bf16_f32 v116, v116, v117
	v_cvt_pk_bf16_f32 v117, v120, v121
	buffer_store_dwordx4 v[114:117], v118, s[28:31], 0 offen sc1
	ds_read_b64 v[114:115], v131 offset:128
	s_waitcnt lgkmcnt(0)
	v_pk_fma_f32 v[112:113], v[88:89], v[114:115], v[112:113] op_sel_hi:[1,0,1]
	v_pk_fma_f32 v[110:111], v[86:87], v[114:115], v[110:111] op_sel_hi:[1,0,1] neg_lo:[1,0,0] neg_hi:[1,0,0]
	v_pk_fma_f32 v[112:113], v[114:115], v[112:113], v[80:81] op_sel:[1,0,0]
	v_pk_fma_f32 v[110:111], v[114:115], v[110:111], v[78:79] op_sel:[1,0,0]
	v_mul_f32_e32 v118, 0xbfb8aa3b, v112
	v_mul_f32_e32 v116, 0xbfb8aa3b, v110
	v_mul_f32_e32 v117, 0xbfb8aa3b, v111
	v_mul_f32_e32 v119, 0xbfb8aa3b, v113
	v_exp_f32_e32 v116, v116
	v_exp_f32_e32 v117, v117
	v_exp_f32_e32 v118, v118
	v_exp_f32_e32 v119, v119
	v_add_f32_e32 v116, 1.0, v116
	v_add_f32_e32 v117, 1.0, v117
	v_add_f32_e32 v118, 1.0, v118
	v_add_f32_e32 v119, 1.0, v119
	v_rcp_f32_e32 v116, v116
	v_rcp_f32_e32 v117, v117
	v_rcp_f32_e32 v118, v118
	v_rcp_f32_e32 v119, v119
	v_pk_fma_f32 v[108:109], v[96:97], v[114:115], v[108:109] op_sel_hi:[1,0,1]
	v_pk_fma_f32 v[106:107], v[94:95], v[114:115], v[106:107] op_sel_hi:[1,0,1] neg_lo:[1,0,0] neg_hi:[1,0,0]
	v_pk_fma_f32 v[104:105], v[64:65], v[114:115], v[104:105] op_sel_hi:[1,0,1]
	v_pk_fma_f32 v[102:103], v[62:63], v[114:115], v[102:103] op_sel_hi:[1,0,1] neg_lo:[1,0,0] neg_hi:[1,0,0]
	v_pk_fma_f32 v[108:109], v[114:115], v[108:109], v[92:93] op_sel:[1,0,0]
	v_pk_fma_f32 v[106:107], v[114:115], v[106:107], v[90:91] op_sel:[1,0,0]
	v_pk_mul_f32 v[112:113], v[112:113], v[118:119]
	v_pk_mul_f32 v[110:111], v[110:111], v[116:117]
	v_pk_fma_f32 v[104:105], v[114:115], v[104:105], v[60:61] op_sel:[1,0,0]
	v_pk_fma_f32 v[102:103], v[114:115], v[102:103], v[58:59] op_sel:[1,0,0]
	v_pk_mul_f32 v[108:109], v[108:109], v[112:113]
	v_pk_mul_f32 v[106:107], v[106:107], v[110:111]
	v_mul_f32_e32 v110, 0xbfb8aa3b, v102
	v_mul_f32_e32 v111, 0xbfb8aa3b, v103
	v_mul_f32_e32 v112, 0xbfb8aa3b, v104
	v_mul_f32_e32 v113, 0xbfb8aa3b, v105
	v_exp_f32_e32 v110, v110
	v_exp_f32_e32 v111, v111
	v_exp_f32_e32 v112, v112
	v_exp_f32_e32 v113, v113
	v_add_f32_e32 v110, 1.0, v110
	v_add_f32_e32 v111, 1.0, v111
	v_add_f32_e32 v112, 1.0, v112
	v_add_f32_e32 v113, 1.0, v113
	v_rcp_f32_e32 v110, v110
	v_rcp_f32_e32 v111, v111
	v_rcp_f32_e32 v112, v112
	v_rcp_f32_e32 v113, v113
	v_pk_fma_f32 v[100:101], v[68:69], v[114:115], v[100:101] op_sel_hi:[1,0,1]
	v_pk_fma_f32 v[98:99], v[66:67], v[114:115], v[98:99] op_sel_hi:[1,0,1] neg_lo:[1,0,0] neg_hi:[1,0,0]
	v_pk_fma_f32 v[100:101], v[114:115], v[100:101], v[72:73] op_sel:[1,0,0]
	v_pk_fma_f32 v[98:99], v[114:115], v[98:99], v[70:71] op_sel:[1,0,0]
	v_pk_mul_f32 v[104:105], v[104:105], v[112:113]
	v_pk_mul_f32 v[102:103], v[102:103], v[110:111]
	v_pk_mul_f32 v[104:105], v[100:101], v[104:105]
	v_pk_mul_f32 v[100:101], v[98:99], v[102:103]
	v_add_lshl_u32 v102, v126, v130, 1
	v_cvt_pk_bf16_f32 v98, v106, v107
	v_cvt_pk_bf16_f32 v99, v108, v109
	v_cvt_pk_bf16_f32 v100, v100, v101
	v_cvt_pk_bf16_f32 v101, v104, v105
	buffer_store_dwordx4 v[98:101], v102, s[28:31], 0 offen sc1
	s_nop 1
	v_mov_b32_e32 v98, v172
	s_nop 0
	v_lshl_add_u32 v105, v98, 3, s33
	v_add_u32_e32 v104, s3, v98
	ds_read_b64 v[98:99], v105
	s_waitcnt lgkmcnt(0)
	v_pk_fma_f32 v[84:85], v[88:89], v[98:99], v[84:85] op_sel_hi:[1,0,1]
	v_pk_fma_f32 v[82:83], v[86:87], v[98:99], v[82:83] op_sel_hi:[1,0,1] neg_lo:[1,0,0] neg_hi:[1,0,0]
	v_pk_fma_f32 v[84:85], v[98:99], v[84:85], v[80:81] op_sel:[1,0,0]
	v_pk_fma_f32 v[82:83], v[98:99], v[82:83], v[78:79] op_sel:[1,0,0]
	v_mul_f32_e32 v102, 0xbfb8aa3b, v84
	v_mul_f32_e32 v100, 0xbfb8aa3b, v82
	v_mul_f32_e32 v101, 0xbfb8aa3b, v83
	v_mul_f32_e32 v103, 0xbfb8aa3b, v85
	v_exp_f32_e32 v100, v100
	v_exp_f32_e32 v101, v101
	v_exp_f32_e32 v102, v102
	v_exp_f32_e32 v103, v103
	v_add_f32_e32 v100, 1.0, v100
	v_add_f32_e32 v101, 1.0, v101
	v_add_f32_e32 v102, 1.0, v102
	v_add_f32_e32 v103, 1.0, v103
	v_rcp_f32_e32 v100, v100
	v_rcp_f32_e32 v101, v101
	v_rcp_f32_e32 v102, v102
	v_rcp_f32_e32 v103, v103
	v_pk_fma_f32 v[76:77], v[96:97], v[98:99], v[76:77] op_sel_hi:[1,0,1]
	v_pk_fma_f32 v[74:75], v[94:95], v[98:99], v[74:75] op_sel_hi:[1,0,1] neg_lo:[1,0,0] neg_hi:[1,0,0]
	v_pk_fma_f32 v[56:57], v[64:65], v[98:99], v[56:57] op_sel_hi:[1,0,1]
	v_pk_fma_f32 v[54:55], v[62:63], v[98:99], v[54:55] op_sel_hi:[1,0,1] neg_lo:[1,0,0] neg_hi:[1,0,0]
	v_pk_fma_f32 v[76:77], v[98:99], v[76:77], v[92:93] op_sel:[1,0,0]
	v_pk_fma_f32 v[74:75], v[98:99], v[74:75], v[90:91] op_sel:[1,0,0]
	v_pk_mul_f32 v[84:85], v[84:85], v[102:103]
	v_pk_mul_f32 v[82:83], v[82:83], v[100:101]
	v_pk_fma_f32 v[56:57], v[98:99], v[56:57], v[60:61] op_sel:[1,0,0]
	v_pk_fma_f32 v[54:55], v[98:99], v[54:55], v[58:59] op_sel:[1,0,0]
	v_pk_mul_f32 v[76:77], v[76:77], v[84:85]
	v_pk_mul_f32 v[74:75], v[74:75], v[82:83]
	v_mul_f32_e32 v82, 0xbfb8aa3b, v54
	v_mul_f32_e32 v83, 0xbfb8aa3b, v55
	v_mul_f32_e32 v84, 0xbfb8aa3b, v56
	v_mul_f32_e32 v85, 0xbfb8aa3b, v57
	v_exp_f32_e32 v82, v82
	v_exp_f32_e32 v83, v83
	v_exp_f32_e32 v84, v84
	v_exp_f32_e32 v85, v85
	v_add_f32_e32 v82, 1.0, v82
	v_add_f32_e32 v83, 1.0, v83
	v_add_f32_e32 v84, 1.0, v84
	v_add_f32_e32 v85, 1.0, v85
	v_rcp_f32_e32 v82, v82
	v_rcp_f32_e32 v83, v83
	v_rcp_f32_e32 v84, v84
	v_rcp_f32_e32 v85, v85
	v_pk_fma_f32 v[52:53], v[68:69], v[98:99], v[52:53] op_sel_hi:[1,0,1]
	v_pk_fma_f32 v[50:51], v[66:67], v[98:99], v[50:51] op_sel_hi:[1,0,1] neg_lo:[1,0,0] neg_hi:[1,0,0]
	v_pk_fma_f32 v[52:53], v[98:99], v[52:53], v[72:73] op_sel:[1,0,0]
	v_pk_fma_f32 v[50:51], v[98:99], v[50:51], v[70:71] op_sel:[1,0,0]
	v_pk_mul_f32 v[56:57], v[56:57], v[84:85]
	v_pk_mul_f32 v[54:55], v[54:55], v[82:83]
	v_mul_lo_u32 v82, v104, s27
	v_pk_mul_f32 v[56:57], v[52:53], v[56:57]
	v_pk_mul_f32 v[52:53], v[50:51], v[54:55]
	v_add_lshl_u32 v54, v82, v176, 1
	v_cvt_pk_bf16_f32 v50, v74, v75
	v_cvt_pk_bf16_f32 v51, v76, v77
	v_cvt_pk_bf16_f32 v52, v52, v53
	v_cvt_pk_bf16_f32 v53, v56, v57
	buffer_store_dwordx4 v[50:53], v54, s[28:31], 0 offen sc1
	ds_read_b64 v[50:51], v105 offset:128
	s_waitcnt lgkmcnt(0)
	v_pk_fma_f32 v[48:49], v[88:89], v[50:51], v[48:49] op_sel_hi:[1,0,1]
	v_pk_fma_f32 v[46:47], v[86:87], v[50:51], v[46:47] op_sel_hi:[1,0,1] neg_lo:[1,0,0] neg_hi:[1,0,0]
	v_pk_fma_f32 v[48:49], v[50:51], v[48:49], v[80:81] op_sel:[1,0,0]
	v_pk_fma_f32 v[46:47], v[50:51], v[46:47], v[78:79] op_sel:[1,0,0]
	v_mul_f32_e32 v54, 0xbfb8aa3b, v48
	v_mul_f32_e32 v52, 0xbfb8aa3b, v46
	v_mul_f32_e32 v53, 0xbfb8aa3b, v47
	v_mul_f32_e32 v55, 0xbfb8aa3b, v49
	v_exp_f32_e32 v52, v52
	v_exp_f32_e32 v53, v53
	v_exp_f32_e32 v54, v54
	v_exp_f32_e32 v55, v55
	v_add_f32_e32 v52, 1.0, v52
	v_add_f32_e32 v53, 1.0, v53
	v_add_f32_e32 v54, 1.0, v54
	v_add_f32_e32 v55, 1.0, v55
	v_rcp_f32_e32 v52, v52
	v_rcp_f32_e32 v53, v53
	v_rcp_f32_e32 v54, v54
	v_rcp_f32_e32 v55, v55
	v_pk_fma_f32 v[44:45], v[96:97], v[50:51], v[44:45] op_sel_hi:[1,0,1]
	v_pk_fma_f32 v[42:43], v[94:95], v[50:51], v[42:43] op_sel_hi:[1,0,1] neg_lo:[1,0,0] neg_hi:[1,0,0]
	v_pk_fma_f32 v[40:41], v[64:65], v[50:51], v[40:41] op_sel_hi:[1,0,1]
	v_pk_fma_f32 v[38:39], v[62:63], v[50:51], v[38:39] op_sel_hi:[1,0,1] neg_lo:[1,0,0] neg_hi:[1,0,0]
	v_pk_fma_f32 v[44:45], v[50:51], v[44:45], v[92:93] op_sel:[1,0,0]
	v_pk_fma_f32 v[42:43], v[50:51], v[42:43], v[90:91] op_sel:[1,0,0]
	v_pk_mul_f32 v[48:49], v[48:49], v[54:55]
	v_pk_mul_f32 v[46:47], v[46:47], v[52:53]
	v_pk_fma_f32 v[40:41], v[50:51], v[40:41], v[60:61] op_sel:[1,0,0]
	v_pk_fma_f32 v[38:39], v[50:51], v[38:39], v[58:59] op_sel:[1,0,0]
	v_pk_mul_f32 v[44:45], v[44:45], v[48:49]
	v_pk_mul_f32 v[42:43], v[42:43], v[46:47]
	v_mul_f32_e32 v46, 0xbfb8aa3b, v38
	v_mul_f32_e32 v47, 0xbfb8aa3b, v39
	v_mul_f32_e32 v48, 0xbfb8aa3b, v40
	v_mul_f32_e32 v49, 0xbfb8aa3b, v41
	v_exp_f32_e32 v46, v46
	v_exp_f32_e32 v47, v47
	v_exp_f32_e32 v48, v48
	v_exp_f32_e32 v49, v49
	v_add_f32_e32 v46, 1.0, v46
	v_add_f32_e32 v47, 1.0, v47
	v_add_f32_e32 v48, 1.0, v48
	v_add_f32_e32 v49, 1.0, v49
	v_rcp_f32_e32 v46, v46
	v_rcp_f32_e32 v47, v47
	v_rcp_f32_e32 v48, v48
	v_rcp_f32_e32 v49, v49
	v_pk_fma_f32 v[36:37], v[68:69], v[50:51], v[36:37] op_sel_hi:[1,0,1]
	v_pk_fma_f32 v[34:35], v[66:67], v[50:51], v[34:35] op_sel_hi:[1,0,1] neg_lo:[1,0,0] neg_hi:[1,0,0]
	v_pk_fma_f32 v[36:37], v[50:51], v[36:37], v[72:73] op_sel:[1,0,0]
	v_pk_fma_f32 v[34:35], v[50:51], v[34:35], v[70:71] op_sel:[1,0,0]
	v_pk_mul_f32 v[40:41], v[40:41], v[48:49]
	v_pk_mul_f32 v[38:39], v[38:39], v[46:47]
	v_pk_mul_f32 v[40:41], v[36:37], v[40:41]
	v_pk_mul_f32 v[36:37], v[34:35], v[38:39]
	v_add_lshl_u32 v38, v82, v130, 1
	v_cvt_pk_bf16_f32 v34, v42, v43
	v_cvt_pk_bf16_f32 v35, v44, v45
	v_cvt_pk_bf16_f32 v36, v36, v37
	v_cvt_pk_bf16_f32 v37, v40, v41
	buffer_store_dwordx4 v[34:37], v38, s[28:31], 0 offen sc1
	s_nop 1
	v_mov_b32_e32 v34, v173
	s_nop 0
	v_lshl_add_u32 v41, v34, 3, s33
	v_add_u32_e32 v40, s3, v34
	ds_read_b64 v[34:35], v41
	s_mov_b32 s3, s77
	s_waitcnt lgkmcnt(0)
	v_pk_fma_f32 v[32:33], v[88:89], v[34:35], v[32:33] op_sel_hi:[1,0,1]
	v_pk_fma_f32 v[30:31], v[86:87], v[34:35], v[30:31] op_sel_hi:[1,0,1] neg_lo:[1,0,0] neg_hi:[1,0,0]
	v_pk_fma_f32 v[32:33], v[34:35], v[32:33], v[80:81] op_sel:[1,0,0]
	v_pk_fma_f32 v[30:31], v[34:35], v[30:31], v[78:79] op_sel:[1,0,0]
	v_mul_f32_e32 v38, 0xbfb8aa3b, v32
	v_mul_f32_e32 v36, 0xbfb8aa3b, v30
	v_mul_f32_e32 v37, 0xbfb8aa3b, v31
	v_mul_f32_e32 v39, 0xbfb8aa3b, v33
	v_exp_f32_e32 v36, v36
	v_exp_f32_e32 v37, v37
	v_exp_f32_e32 v38, v38
	v_exp_f32_e32 v39, v39
	v_add_f32_e32 v36, 1.0, v36
	v_add_f32_e32 v37, 1.0, v37
	v_add_f32_e32 v38, 1.0, v38
	v_add_f32_e32 v39, 1.0, v39
	v_rcp_f32_e32 v36, v36
	v_rcp_f32_e32 v37, v37
	v_rcp_f32_e32 v38, v38
	v_rcp_f32_e32 v39, v39
	v_pk_fma_f32 v[28:29], v[96:97], v[34:35], v[28:29] op_sel_hi:[1,0,1]
	v_pk_fma_f32 v[26:27], v[94:95], v[34:35], v[26:27] op_sel_hi:[1,0,1] neg_lo:[1,0,0] neg_hi:[1,0,0]
	v_pk_fma_f32 v[24:25], v[64:65], v[34:35], v[24:25] op_sel_hi:[1,0,1]
	v_pk_fma_f32 v[22:23], v[62:63], v[34:35], v[22:23] op_sel_hi:[1,0,1] neg_lo:[1,0,0] neg_hi:[1,0,0]
	v_pk_fma_f32 v[28:29], v[34:35], v[28:29], v[92:93] op_sel:[1,0,0]
	v_pk_fma_f32 v[26:27], v[34:35], v[26:27], v[90:91] op_sel:[1,0,0]
	v_pk_mul_f32 v[32:33], v[32:33], v[38:39]
	v_pk_mul_f32 v[30:31], v[30:31], v[36:37]
	v_pk_fma_f32 v[24:25], v[34:35], v[24:25], v[60:61] op_sel:[1,0,0]
	v_pk_fma_f32 v[22:23], v[34:35], v[22:23], v[58:59] op_sel:[1,0,0]
	v_pk_mul_f32 v[28:29], v[28:29], v[32:33]
	v_pk_mul_f32 v[26:27], v[26:27], v[30:31]
	v_mul_f32_e32 v30, 0xbfb8aa3b, v22
	v_mul_f32_e32 v31, 0xbfb8aa3b, v23
	v_mul_f32_e32 v32, 0xbfb8aa3b, v24
	v_mul_f32_e32 v33, 0xbfb8aa3b, v25
	v_exp_f32_e32 v30, v30
	v_exp_f32_e32 v31, v31
	v_exp_f32_e32 v32, v32
	v_exp_f32_e32 v33, v33
	v_add_f32_e32 v30, 1.0, v30
	v_add_f32_e32 v31, 1.0, v31
	v_add_f32_e32 v32, 1.0, v32
	v_add_f32_e32 v33, 1.0, v33
	v_rcp_f32_e32 v30, v30
	v_rcp_f32_e32 v31, v31
	v_rcp_f32_e32 v32, v32
	v_rcp_f32_e32 v33, v33
	v_pk_fma_f32 v[20:21], v[68:69], v[34:35], v[20:21] op_sel_hi:[1,0,1]
	v_pk_fma_f32 v[18:19], v[66:67], v[34:35], v[18:19] op_sel_hi:[1,0,1] neg_lo:[1,0,0] neg_hi:[1,0,0]
	v_pk_fma_f32 v[20:21], v[34:35], v[20:21], v[72:73] op_sel:[1,0,0]
	v_pk_fma_f32 v[18:19], v[34:35], v[18:19], v[70:71] op_sel:[1,0,0]
	v_pk_mul_f32 v[24:25], v[24:25], v[32:33]
	v_pk_mul_f32 v[22:23], v[22:23], v[30:31]
	v_mul_lo_u32 v30, v40, s27
	v_pk_mul_f32 v[24:25], v[20:21], v[24:25]
	v_pk_mul_f32 v[20:21], v[18:19], v[22:23]
	v_add_lshl_u32 v22, v30, v176, 1
	v_cvt_pk_bf16_f32 v18, v26, v27
	v_cvt_pk_bf16_f32 v19, v28, v29
	v_cvt_pk_bf16_f32 v20, v20, v21
	v_cvt_pk_bf16_f32 v21, v24, v25
	buffer_store_dwordx4 v[18:21], v22, s[28:31], 0 offen sc1
	ds_read_b64 v[18:19], v41 offset:128
	s_mov_b32 s27, s58
	s_waitcnt lgkmcnt(0)
	v_pk_fma_f32 v[16:17], v[88:89], v[18:19], v[16:17] op_sel_hi:[1,0,1]
	v_pk_fma_f32 v[14:15], v[86:87], v[18:19], v[14:15] op_sel_hi:[1,0,1] neg_lo:[1,0,0] neg_hi:[1,0,0]
	v_pk_fma_f32 v[16:17], v[18:19], v[16:17], v[80:81] op_sel:[1,0,0]
	v_pk_fma_f32 v[14:15], v[18:19], v[14:15], v[78:79] op_sel:[1,0,0]
	v_mul_f32_e32 v22, 0xbfb8aa3b, v16
	v_mul_f32_e32 v20, 0xbfb8aa3b, v14
	v_mul_f32_e32 v21, 0xbfb8aa3b, v15
	v_mul_f32_e32 v23, 0xbfb8aa3b, v17
	v_exp_f32_e32 v20, v20
	v_exp_f32_e32 v21, v21
	v_exp_f32_e32 v22, v22
	v_exp_f32_e32 v23, v23
	v_add_f32_e32 v20, 1.0, v20
	v_add_f32_e32 v21, 1.0, v21
	v_add_f32_e32 v22, 1.0, v22
	v_add_f32_e32 v23, 1.0, v23
	v_rcp_f32_e32 v20, v20
	v_rcp_f32_e32 v21, v21
	v_rcp_f32_e32 v22, v22
	v_rcp_f32_e32 v23, v23
	v_pk_fma_f32 v[12:13], v[96:97], v[18:19], v[12:13] op_sel_hi:[1,0,1]
	v_pk_fma_f32 v[10:11], v[94:95], v[18:19], v[10:11] op_sel_hi:[1,0,1] neg_lo:[1,0,0] neg_hi:[1,0,0]
	v_pk_fma_f32 v[8:9], v[64:65], v[18:19], v[8:9] op_sel_hi:[1,0,1]
	v_pk_fma_f32 v[6:7], v[62:63], v[18:19], v[6:7] op_sel_hi:[1,0,1] neg_lo:[1,0,0] neg_hi:[1,0,0]
	v_pk_fma_f32 v[12:13], v[18:19], v[12:13], v[92:93] op_sel:[1,0,0]
	v_pk_fma_f32 v[10:11], v[18:19], v[10:11], v[90:91] op_sel:[1,0,0]
	v_pk_mul_f32 v[16:17], v[16:17], v[22:23]
	v_pk_mul_f32 v[14:15], v[14:15], v[20:21]
	v_pk_fma_f32 v[8:9], v[18:19], v[8:9], v[60:61] op_sel:[1,0,0]
	v_pk_fma_f32 v[6:7], v[18:19], v[6:7], v[58:59] op_sel:[1,0,0]
	v_pk_mul_f32 v[12:13], v[12:13], v[16:17]
	v_pk_mul_f32 v[10:11], v[10:11], v[14:15]
	v_mul_f32_e32 v14, 0xbfb8aa3b, v6
	v_mul_f32_e32 v15, 0xbfb8aa3b, v7
	v_mul_f32_e32 v16, 0xbfb8aa3b, v8
	v_mul_f32_e32 v17, 0xbfb8aa3b, v9
	v_exp_f32_e32 v14, v14
	v_exp_f32_e32 v15, v15
	v_exp_f32_e32 v16, v16
	v_exp_f32_e32 v17, v17
	v_add_f32_e32 v14, 1.0, v14
	v_add_f32_e32 v15, 1.0, v15
	v_add_f32_e32 v16, 1.0, v16
	v_add_f32_e32 v17, 1.0, v17
	v_rcp_f32_e32 v14, v14
	v_rcp_f32_e32 v15, v15
	v_rcp_f32_e32 v16, v16
	v_rcp_f32_e32 v17, v17
	v_pk_fma_f32 v[4:5], v[68:69], v[18:19], v[4:5] op_sel_hi:[1,0,1]
	v_pk_fma_f32 v[2:3], v[66:67], v[18:19], v[2:3] op_sel_hi:[1,0,1] neg_lo:[1,0,0] neg_hi:[1,0,0]
	v_pk_fma_f32 v[4:5], v[18:19], v[4:5], v[72:73] op_sel:[1,0,0]
	v_pk_fma_f32 v[2:3], v[18:19], v[2:3], v[70:71] op_sel:[1,0,0]
	v_pk_mul_f32 v[8:9], v[8:9], v[16:17]
	v_pk_mul_f32 v[6:7], v[6:7], v[14:15]
	v_pk_mul_f32 v[8:9], v[4:5], v[8:9]
	v_pk_mul_f32 v[4:5], v[2:3], v[6:7]
	v_add_lshl_u32 v6, v30, v130, 1
	v_cvt_pk_bf16_f32 v2, v10, v11
	v_cvt_pk_bf16_f32 v3, v12, v13
	v_cvt_pk_bf16_f32 v4, v4, v5
	v_cvt_pk_bf16_f32 v5, v8, v9
	buffer_store_dwordx4 v[2:5], v6, s[28:31], 0 offen sc1
	s_cbranch_vccz .Lhdr_epi_2
	s_waitcnt vmcnt(0)
	v_readlane_b32 s76, v255, 13
	s_cmpk_gt_u32 s38, 0xff
	v_readlane_b32 s77, v255, 14
	s_cbranch_scc1 .LBB0_1103
	s_barrier

.Lhdr_epi_2:
	s_add_i32 s76, s76, 1
	s_mov_b64 s[62:63], s[54:55]
	s_mul_i32 s54, s76, s26
	s_add_i32 s64, s54, s2
	s_cmpk_gt_i32 s64, 0x57f
	s_cselect_b64 s[60:61], -1, 0
	s_lshl_b32 s54, s64, 3
	s_and_b32 s54, s54, 56
	s_bfe_u32 s55, s64, 0x30003
	s_or_b32 s77, s54, s55
	s_ashr_i32 s58, s64, 6
	s_lshl_b32 s54, s77, 19
	s_mov_b64 s[36:37], s[56:57]
	s_add_u32 s56, s52, s54
	s_addc_u32 s57, s53, 0
	s_ashr_i32 s59, s58, 31
	s_lshl_b64 s[54:55], s[58:59], 19
	s_add_u32 s54, s4, s54
	s_addc_u32 s55, s5, s55
	s_cmpk_lt_i32 s64, 0x580
	s_cselect_b32 s59, s57, s37
	s_cselect_b32 s78, s56, s36
	s_cselect_b32 s79, s55, s63
	s_cselect_b32 s80, s54, s62
	s_add_u32 s81, s62, 0x100
	s_addc_u32 s82, s63, 0
	s_mov_b32 s83, -2
	s_add_u32 s62, s36, 0x100
	s_addc_u32 s63, s37, 0
	s_add_i32 s84, 0, 0x10000
	v_add_u32_e32 v70, s84, v170
	ds_read_b128 v[58:61], v70
	ds_read_b128 v[62:65], v70 offset:1024
	ds_read_b128 v[66:69], v70 offset:2048
	ds_read_b128 v[70:73], v70 offset:3072
	s_cmp_eq_u32 s83, 12
	s_cselect_b32 s67, s59, s63
	s_cselect_b32 s66, s78, s62
	s_cselect_b32 s65, s79, s82
	s_cselect_b32 s64, s80, s81
	v_lshl_add_u64 v[192:193], s[36:37], 0, v[168:169]
	s_add_i32 m0, s69, 0xc000
	ds_read_b128 v[78:81], v175
	ds_read_b128 v[86:89], v175 offset:1024
	ds_read_b128 v[90:93], v175 offset:2048
	ds_read_b128 v[94:97], v175 offset:3072
	ds_read_b128 v[176:179], v175 offset:4096
	ds_read_b128 v[180:183], v175 offset:5120
	ds_read_b128 v[184:187], v175 offset:6144
	ds_read_b128 v[188:191], v175 offset:7168
	v_lshl_add_u64 v[192:193], s[36:37], 0, v[166:167]
	s_add_i32 m0, s69, 0xe000
	s_nop 0
	s_waitcnt lgkmcnt(8)
	s_barrier
	s_waitcnt lgkmcnt(0)
	s_setprio 1
	s_waitcnt lgkmcnt(0)
	v_mfma_f32_16x16x32_bf16 v[158:161], v[58:61], v[78:81], 0
	v_mfma_f32_16x16x32_bf16 v[150:153], v[66:69], v[78:81], 0
	v_mfma_f32_16x16x32_bf16 v[142:145], v[58:61], v[90:93], 0
	v_mfma_f32_16x16x32_bf16 v[134:137], v[66:69], v[90:93], 0
	v_mfma_f32_16x16x32_bf16 v[126:129], v[58:61], v[176:179], 0
	v_mfma_f32_16x16x32_bf16 v[118:121], v[66:69], v[176:179], 0
	v_mfma_f32_16x16x32_bf16 v[110:113], v[58:61], v[184:187], 0
	v_mfma_f32_16x16x32_bf16 v[102:105], v[66:69], v[184:187], 0
	v_mfma_f32_16x16x32_bf16 v[158:161], v[62:65], v[86:89], v[158:161]
	v_mfma_f32_16x16x32_bf16 v[150:153], v[70:73], v[86:89], v[150:153]
	v_mfma_f32_16x16x32_bf16 v[142:145], v[62:65], v[94:97], v[142:145]
	v_mfma_f32_16x16x32_bf16 v[134:137], v[70:73], v[94:97], v[134:137]
	v_mfma_f32_16x16x32_bf16 v[126:129], v[62:65], v[180:183], v[126:129]
	v_mfma_f32_16x16x32_bf16 v[118:121], v[70:73], v[180:183], v[118:121]
	v_mfma_f32_16x16x32_bf16 v[110:113], v[62:65], v[188:191], v[110:113]
	v_mfma_f32_16x16x32_bf16 v[102:105], v[70:73], v[188:191], v[102:105]
	s_setprio 0
	s_barrier
	s_add_i32 s85, 0, 0x14000
	v_add_u32_e32 v192, s85, v170
	s_add_i32 s36, s84, s68
	ds_read_b128 v[200:203], v192
	ds_read_b128 v[204:207], v192 offset:1024
	ds_read_b128 v[208:211], v192 offset:2048
	ds_read_b128 v[222:225], v192 offset:3072
	v_lshl_add_u64 v[192:193], s[64:65], 0, v[164:165]
	s_mov_b32 m0, s36
	v_lshl_add_u64 v[214:215], s[64:65], 0, v[162:163]
	global_load_lds_dwordx4 v[192:193], off
	s_add_i32 m0, s36, 0x2000
	s_nop 0
	global_load_lds_dwordx4 v[214:215], off
	s_barrier
	s_waitcnt lgkmcnt(0)
	s_setprio 1
	s_waitcnt lgkmcnt(0)
	v_mfma_f32_16x16x32_bf16 v[154:157], v[200:203], v[78:81], 0
	v_mfma_f32_16x16x32_bf16 v[78:81], v[208:211], v[78:81], 0
	v_mfma_f32_16x16x32_bf16 v[154:157], v[204:207], v[86:89], v[154:157]
	v_mfma_f32_16x16x32_bf16 v[78:81], v[222:225], v[86:89], v[78:81]
	v_mfma_f32_16x16x32_bf16 v[86:89], v[200:203], v[90:93], 0
	v_mfma_f32_16x16x32_bf16 v[90:93], v[208:211], v[90:93], 0
	v_mfma_f32_16x16x32_bf16 v[114:117], v[208:211], v[176:179], 0
	v_mfma_f32_16x16x32_bf16 v[106:109], v[200:203], v[184:187], 0
	v_mfma_f32_16x16x32_bf16 v[98:101], v[208:211], v[184:187], 0
	v_mfma_f32_16x16x32_bf16 v[86:89], v[204:207], v[94:97], v[86:89]
	v_mfma_f32_16x16x32_bf16 v[90:93], v[222:225], v[94:97], v[90:93]
	v_mfma_f32_16x16x32_bf16 v[94:97], v[200:203], v[176:179], 0
	v_mfma_f32_16x16x32_bf16 v[114:117], v[222:225], v[180:183], v[114:117]
	v_mfma_f32_16x16x32_bf16 v[106:109], v[204:207], v[188:191], v[106:109]
	v_mfma_f32_16x16x32_bf16 v[98:101], v[222:225], v[188:191], v[98:101]
	v_mfma_f32_16x16x32_bf16 v[94:97], v[204:207], v[180:183], v[94:97]
	s_setprio 0
	s_mov_b32 m0, s69
	v_lshl_add_u64 v[234:235], s[66:67], 0, v[164:165]
	s_barrier
	ds_read_b128 v[122:125], v175 offset:16384
	ds_read_b128 v[130:133], v175 offset:17408
	ds_read_b128 v[138:141], v175 offset:18432
	ds_read_b128 v[146:149], v175 offset:19456
	ds_read_b128 v[176:179], v175 offset:20480
	ds_read_b128 v[180:183], v175 offset:21504
	ds_read_b128 v[184:187], v175 offset:22528
	ds_read_b128 v[188:191], v175 offset:23552
	global_load_lds_dwordx4 v[234:235], off
	v_lshl_add_u64 v[236:237], s[66:67], 0, v[162:163]
	s_mov_b32 m0, s70
	s_nop 0
	global_load_lds_dwordx4 v[236:237], off
	s_barrier
	s_waitcnt lgkmcnt(0)
	s_setprio 1
	s_waitcnt lgkmcnt(0)
	v_mfma_f32_16x16x32_bf16 v[82:85], v[58:61], v[122:125], 0
	v_mfma_f32_16x16x32_bf16 v[54:57], v[66:69], v[122:125], 0
	v_mfma_f32_16x16x32_bf16 v[46:49], v[58:61], v[138:141], 0
	v_mfma_f32_16x16x32_bf16 v[38:41], v[66:69], v[138:141], 0
	v_mfma_f32_16x16x32_bf16 v[30:33], v[58:61], v[176:179], 0
	v_mfma_f32_16x16x32_bf16 v[22:25], v[66:69], v[176:179], 0
	v_mfma_f32_16x16x32_bf16 v[14:17], v[58:61], v[184:187], 0
	v_mfma_f32_16x16x32_bf16 v[6:9], v[66:69], v[184:187], 0
	v_mfma_f32_16x16x32_bf16 v[82:85], v[62:65], v[130:133], v[82:85]
	v_mfma_f32_16x16x32_bf16 v[54:57], v[70:73], v[130:133], v[54:57]
	v_mfma_f32_16x16x32_bf16 v[46:49], v[62:65], v[146:149], v[46:49]
	v_mfma_f32_16x16x32_bf16 v[38:41], v[70:73], v[146:149], v[38:41]
	v_mfma_f32_16x16x32_bf16 v[30:33], v[62:65], v[180:183], v[30:33]
	v_mfma_f32_16x16x32_bf16 v[22:25], v[70:73], v[180:183], v[22:25]
	v_mfma_f32_16x16x32_bf16 v[14:17], v[62:65], v[188:191], v[14:17]
	v_mfma_f32_16x16x32_bf16 v[6:9], v[70:73], v[188:191], v[6:9]
	s_setprio 0
	s_barrier
	s_add_u32 s36, s64, 0x40000
	s_addc_u32 s37, s65, 0
	s_add_i32 s84, s85, s68
	v_lshl_add_u64 v[58:59], s[36:37], 0, v[164:165]
	s_mov_b32 m0, s84
	s_nop 0
	global_load_lds_dwordx4 v[58:59], off
	v_lshl_add_u64 v[58:59], s[36:37], 0, v[162:163]
	s_add_i32 m0, s84, 0x2000
	s_nop 0
	global_load_lds_dwordx4 v[58:59], off
	s_barrier
	s_setprio 1
	v_mfma_f32_16x16x32_bf16 v[50:53], v[208:211], v[122:125], 0
	v_mfma_f32_16x16x32_bf16 v[42:45], v[200:203], v[138:141], 0
	v_mfma_f32_16x16x32_bf16 v[34:37], v[208:211], v[138:141], 0
	v_mfma_f32_16x16x32_bf16 v[26:29], v[200:203], v[176:179], 0
	v_mfma_f32_16x16x32_bf16 v[18:21], v[208:211], v[176:179], 0
	v_mfma_f32_16x16x32_bf16 v[10:13], v[200:203], v[184:187], 0
	v_mfma_f32_16x16x32_bf16 v[2:5], v[208:211], v[184:187], 0
	v_mfma_f32_16x16x32_bf16 v[58:61], v[200:203], v[122:125], 0
	v_mfma_f32_16x16x32_bf16 v[50:53], v[222:225], v[130:133], v[50:53]
	v_mfma_f32_16x16x32_bf16 v[42:45], v[204:207], v[146:149], v[42:45]
	v_mfma_f32_16x16x32_bf16 v[34:37], v[222:225], v[146:149], v[34:37]
	v_mfma_f32_16x16x32_bf16 v[26:29], v[204:207], v[180:183], v[26:29]
	v_mfma_f32_16x16x32_bf16 v[18:21], v[222:225], v[180:183], v[18:21]
	v_mfma_f32_16x16x32_bf16 v[10:13], v[204:207], v[188:191], v[10:13]
	v_mfma_f32_16x16x32_bf16 v[2:5], v[222:225], v[188:191], v[2:5]
	v_mfma_f32_16x16x32_bf16 v[58:61], v[204:207], v[130:133], v[58:61]
	s_setprio 0
	s_add_i32 s84, 0, 0x18000
	v_add_u32_e32 v74, s84, v170
	s_barrier
	ds_read_b128 v[62:65], v74
	ds_read_b128 v[66:69], v74 offset:1024
	ds_read_b128 v[70:73], v74 offset:2048
	ds_read_b128 v[74:77], v74 offset:3072
	s_add_u32 s36, s66, 0x40000
	s_addc_u32 s37, s67, 0
	s_mov_b32 m0, s71
	v_lshl_add_u64 v[138:139], s[36:37], 0, v[164:165]
	ds_read_b128 v[122:125], v175 offset:32768
	ds_read_b128 v[130:133], v175 offset:33792
	ds_read_b128 v[176:179], v175 offset:34816
	ds_read_b128 v[180:183], v175 offset:35840
	ds_read_b128 v[184:187], v175 offset:36864
	ds_read_b128 v[188:191], v175 offset:37888
	ds_read_b128 v[200:203], v175 offset:38912
	ds_read_b128 v[204:207], v175 offset:39936
	global_load_lds_dwordx4 v[138:139], off
	v_lshl_add_u64 v[138:139], s[36:37], 0, v[162:163]
	s_mov_b32 m0, s72
	s_nop 0
	global_load_lds_dwordx4 v[138:139], off
	s_waitcnt lgkmcnt(8)
	s_barrier
	s_waitcnt lgkmcnt(0)
	s_setprio 1
	s_waitcnt lgkmcnt(0)
	v_mfma_f32_16x16x32_bf16 v[138:141], v[62:65], v[122:125], v[158:161]
	v_mfma_f32_16x16x32_bf16 v[158:161], v[66:69], v[130:133], v[138:141]
	v_mfma_f32_16x16x32_bf16 v[138:141], v[70:73], v[122:125], v[150:153]
	v_mfma_f32_16x16x32_bf16 v[150:153], v[74:77], v[130:133], v[138:141]
	v_mfma_f32_16x16x32_bf16 v[138:141], v[62:65], v[176:179], v[142:145]
	v_mfma_f32_16x16x32_bf16 v[134:137], v[70:73], v[176:179], v[134:137]
	v_mfma_f32_16x16x32_bf16 v[126:129], v[62:65], v[184:187], v[126:129]
	v_mfma_f32_16x16x32_bf16 v[118:121], v[70:73], v[184:187], v[118:121]
	v_mfma_f32_16x16x32_bf16 v[110:113], v[62:65], v[200:203], v[110:113]
	v_mfma_f32_16x16x32_bf16 v[102:105], v[70:73], v[200:203], v[102:105]
	v_mfma_f32_16x16x32_bf16 v[142:145], v[66:69], v[180:183], v[138:141]
	v_mfma_f32_16x16x32_bf16 v[134:137], v[74:77], v[180:183], v[134:137]
	v_mfma_f32_16x16x32_bf16 v[126:129], v[66:69], v[188:191], v[126:129]
	v_mfma_f32_16x16x32_bf16 v[118:121], v[74:77], v[188:191], v[118:121]
	v_mfma_f32_16x16x32_bf16 v[110:113], v[66:69], v[204:207], v[110:113]
	v_mfma_f32_16x16x32_bf16 v[102:105], v[74:77], v[204:207], v[102:105]
	s_setprio 0
	s_barrier
	s_add_i32 s66, 0, 0x1c000
	v_add_u32_e32 v138, s66, v170
	s_add_i32 s36, s84, s68
	ds_read_b128 v[208:211], v138
	ds_read_b128 v[222:225], v138 offset:1024
	ds_read_b128 v[226:229], v138 offset:2048
	ds_read_b128 v[230:233], v138 offset:3072
	v_lshl_add_u64 v[138:139], v[192:193], 0, s[22:23]
	s_mov_b32 m0, s36
	s_nop 0
	global_load_lds_dwordx4 v[138:139], off
	v_lshl_add_u64 v[138:139], v[214:215], 0, s[22:23]
	s_add_i32 m0, s36, 0x2000
	s_nop 0
	global_load_lds_dwordx4 v[138:139], off
	s_barrier
	s_waitcnt lgkmcnt(0)
	s_setprio 1
	s_waitcnt lgkmcnt(0)
	v_mfma_f32_16x16x32_bf16 v[78:81], v[226:229], v[122:125], v[78:81]
	v_mfma_f32_16x16x32_bf16 v[138:141], v[208:211], v[122:125], v[154:157]
	v_mfma_f32_16x16x32_bf16 v[146:149], v[230:233], v[130:133], v[78:81]
	v_mfma_f32_16x16x32_bf16 v[78:81], v[208:211], v[176:179], v[86:89]
	v_mfma_f32_16x16x32_bf16 v[154:157], v[222:225], v[130:133], v[138:141]
	v_mfma_f32_16x16x32_bf16 v[138:141], v[222:225], v[180:183], v[78:81]
	v_mfma_f32_16x16x32_bf16 v[78:81], v[226:229], v[176:179], v[90:93]
	v_mfma_f32_16x16x32_bf16 v[130:133], v[230:233], v[180:183], v[78:81]
	v_mfma_f32_16x16x32_bf16 v[78:81], v[208:211], v[184:187], v[94:97]
	v_mfma_f32_16x16x32_bf16 v[122:125], v[222:225], v[188:191], v[78:81]
	v_mfma_f32_16x16x32_bf16 v[78:81], v[226:229], v[184:187], v[114:117]
	v_mfma_f32_16x16x32_bf16 v[114:117], v[230:233], v[188:191], v[78:81]
	v_mfma_f32_16x16x32_bf16 v[78:81], v[208:211], v[200:203], v[106:109]
	v_mfma_f32_16x16x32_bf16 v[106:109], v[222:225], v[204:207], v[78:81]
	v_mfma_f32_16x16x32_bf16 v[78:81], v[226:229], v[200:203], v[98:101]
	v_mfma_f32_16x16x32_bf16 v[98:101], v[230:233], v[204:207], v[78:81]
	s_setprio 0
	s_mov_b32 m0, s73
	v_lshl_add_u64 v[192:193], v[234:235], 0, s[22:23]
	s_barrier
	s_nop 2
	ds_read_b128 v[78:81], v175 offset:49152
	ds_read_b128 v[86:89], v175 offset:50176
	ds_read_b128 v[90:93], v175 offset:51200
	ds_read_b128 v[94:97], v175 offset:52224
	ds_read_b128 v[176:179], v175 offset:53248
	ds_read_b128 v[180:183], v175 offset:54272
	ds_read_b128 v[184:187], v175 offset:55296
	ds_read_b128 v[188:191], v175 offset:56320
	global_load_lds_dwordx4 v[192:193], off
	v_lshl_add_u64 v[192:193], v[236:237], 0, s[22:23]
	s_mov_b32 m0, s75
	s_nop 0
	global_load_lds_dwordx4 v[192:193], off
	s_barrier
	s_waitcnt lgkmcnt(0)
	s_setprio 1
	s_waitcnt lgkmcnt(0)
	v_mfma_f32_16x16x32_bf16 v[82:85], v[62:65], v[78:81], v[82:85]
	v_mfma_f32_16x16x32_bf16 v[54:57], v[70:73], v[78:81], v[54:57]
	v_mfma_f32_16x16x32_bf16 v[46:49], v[62:65], v[90:93], v[46:49]
	v_mfma_f32_16x16x32_bf16 v[38:41], v[70:73], v[90:93], v[38:41]
	v_mfma_f32_16x16x32_bf16 v[30:33], v[62:65], v[176:179], v[30:33]
	v_mfma_f32_16x16x32_bf16 v[22:25], v[70:73], v[176:179], v[22:25]
	v_mfma_f32_16x16x32_bf16 v[14:17], v[62:65], v[184:187], v[14:17]
	v_mfma_f32_16x16x32_bf16 v[6:9], v[70:73], v[184:187], v[6:9]
	v_mfma_f32_16x16x32_bf16 v[82:85], v[66:69], v[86:89], v[82:85]
	v_mfma_f32_16x16x32_bf16 v[54:57], v[74:77], v[86:89], v[54:57]
	v_mfma_f32_16x16x32_bf16 v[46:49], v[66:69], v[94:97], v[46:49]
	v_mfma_f32_16x16x32_bf16 v[38:41], v[74:77], v[94:97], v[38:41]
	v_mfma_f32_16x16x32_bf16 v[30:33], v[66:69], v[180:183], v[30:33]
	v_mfma_f32_16x16x32_bf16 v[22:25], v[74:77], v[180:183], v[22:25]
	v_mfma_f32_16x16x32_bf16 v[14:17], v[66:69], v[188:191], v[14:17]
	v_mfma_f32_16x16x32_bf16 v[6:9], v[74:77], v[188:191], v[6:9]
	s_setprio 0
	s_barrier
	s_add_u32 s36, s64, 0x40080
	s_addc_u32 s37, s65, 0
	s_add_i32 s64, s66, s68
	v_lshl_add_u64 v[62:63], s[36:37], 0, v[164:165]
	s_mov_b32 m0, s64
	s_nop 0
	global_load_lds_dwordx4 v[62:63], off
	v_lshl_add_u64 v[62:63], s[36:37], 0, v[162:163]
	s_add_i32 m0, s64, 0x2000
	s_nop 0
	global_load_lds_dwordx4 v[62:63], off
	s_waitcnt vmcnt(6)
	s_barrier
	s_setprio 1
	v_mfma_f32_16x16x32_bf16 v[58:61], v[208:211], v[78:81], v[58:61]
	v_mfma_f32_16x16x32_bf16 v[50:53], v[226:229], v[78:81], v[50:53]
	v_mfma_f32_16x16x32_bf16 v[42:45], v[208:211], v[90:93], v[42:45]
	v_mfma_f32_16x16x32_bf16 v[34:37], v[226:229], v[90:93], v[34:37]
	v_mfma_f32_16x16x32_bf16 v[26:29], v[208:211], v[176:179], v[26:29]
	v_mfma_f32_16x16x32_bf16 v[18:21], v[226:229], v[176:179], v[18:21]
	v_mfma_f32_16x16x32_bf16 v[10:13], v[208:211], v[184:187], v[10:13]
	v_mfma_f32_16x16x32_bf16 v[2:5], v[226:229], v[184:187], v[2:5]
	v_mfma_f32_16x16x32_bf16 v[74:77], v[222:225], v[86:89], v[58:61]
	v_mfma_f32_16x16x32_bf16 v[50:53], v[230:233], v[86:89], v[50:53]
	v_mfma_f32_16x16x32_bf16 v[42:45], v[222:225], v[94:97], v[42:45]
	v_mfma_f32_16x16x32_bf16 v[34:37], v[230:233], v[94:97], v[34:37]
	v_mfma_f32_16x16x32_bf16 v[26:29], v[222:225], v[180:183], v[26:29]
	v_mfma_f32_16x16x32_bf16 v[18:21], v[230:233], v[180:183], v[18:21]
	v_mfma_f32_16x16x32_bf16 v[10:13], v[222:225], v[188:191], v[10:13]
	v_mfma_f32_16x16x32_bf16 v[2:5], v[230:233], v[188:191], v[2:5]
	s_setprio 0
	s_add_i32 s83, s83, 2
	s_add_u32 s81, s81, 0x100
	s_addc_u32 s82, s82, 0
	s_cmp_gt_u32 s83, 13
	s_mov_b64 s[36:37], s[62:63]
	s_barrier
	s_branch .LBB0_1099
